# GEMM256 loops: LDS-DMA 3-stage ring with source-side XOR swizzle; lat_scan batched prefetch; setup conversion loop loads batched; DA K/V load addressing via saddr
# speedup vs baseline: 1.0741x; 1.0741x over previous
.LBB0_91:
	s_lshr_b32 s8, s10, 3
	s_and_b32 s8, s8, 0xffffff8
	s_and_b32 s9, s10, 7
	s_or_b32 s8, s8, s9
	s_and_b32 s9, s10, 56
	v_readlane_b32 s0, v252, 42
	s_or_b32 s11, s9, s0
	v_mov_b32_e32 v6, v171
	s_lshl_b32 s9, s11, 19
	v_lshlrev_b32_e32 v2, 3, v6
	s_add_u32 s12, s98, s9
	v_ashrrev_i32_e32 v3, 31, v2
	s_addc_u32 s13, s99, 0
	v_lshlrev_b64 v[4:5], 1, v[2:3]
	s_mov_b32 s9, s15
	v_lshl_add_u64 v[154:155], s[12:13], 0, v[4:5]
	s_lshl_b64 s[12:13], s[8:9], 18
	v_readlane_b32 s0, v252, 36
	v_readlane_b32 s1, v252, 37
	s_add_u32 s12, s0, s12
	s_addc_u32 s13, s1, s13
	v_lshrrev_b32_e32 v3, 2, v6
	v_and_b32_e32 v0, 24, v2
	v_lshl_add_u64 v[156:157], s[12:13], 0, v[4:5]
	v_mad_u64_u32 v[158:159], s[12:13], v3, 40, v[0:1]
	s_movk_i32 s0, 0x50
	v_and_b32_e32 v2, 0x30, v6
	v_xor_b32_e32 v154, v154, v2
	v_xor_b32_e32 v156, v156, v2
	v_and_b32_e32 v130, 31, v6
	v_lshlrev_b32_e32 v130, 6, v130
	v_lshrrev_b32_e32 v131, 2, v6
	v_and_b32_e32 v131, 3, v131
	v_bfe_u32 v133, v6, 5, 1
	v_xor_b32_e32 v131, v131, v133
	v_lshl_or_b32 v130, v131, 4, v130
	v_lshrrev_b32_e32 v131, 7, v6
	v_lshl_or_b32 v132, v131, 13, v130
	v_bfe_u32 v131, v6, 6, 1
	v_lshl_or_b32 v133, v131, 12, v130
	v_or_b32_e32 v133, 0x4000, v133
	v_xor_b32_e32 v134, 32, v132
	v_xor_b32_e32 v135, 32, v133
	v_lshrrev_b32_e32 v131, 6, v6
	s_nop 1
	v_readfirstlane_b32 s72, v131
	s_nop 3
	s_lshl_b32 s72, s72, 10
	s_waitcnt lgkmcnt(0)
	s_barrier
	s_mov_b32 s14, 0
	s_lshl_b64 s[12:13], s[14:15], 14
	v_lshl_add_u64 v[244:245], v[154:155], 0, s[12:13]
	s_add_u32 s12, s12, 0x1000
	s_addc_u32 s13, s13, 0
	v_lshl_add_u64 v[246:247], v[154:155], 0, s[12:13]
	s_add_u32 s12, s12, 0x1000
	s_addc_u32 s13, s13, 0
	v_lshl_add_u64 v[248:249], v[154:155], 0, s[12:13]
	s_add_u32 s12, s12, 0x1000
	s_addc_u32 s13, s13, 0
	v_lshl_add_u64 v[140:141], v[154:155], 0, s[12:13]
	s_lshl_b64 s[12:13], s[14:15], 13
	v_lshl_add_u64 v[142:143], v[156:157], 0, s[12:13]
	s_add_u32 s12, s12, 0x1000
	s_addc_u32 s13, s13, 0
	v_lshl_add_u64 v[144:145], v[156:157], 0, s[12:13]
	s_add_u32 m0, s72, 0x0
	s_nop 0
	global_load_lds_dwordx4 v[244:245], off
	s_add_u32 m0, m0, 0x1000
	s_nop 0
	global_load_lds_dwordx4 v[246:247], off
	s_add_u32 m0, m0, 0x1000
	s_nop 0
	global_load_lds_dwordx4 v[248:249], off
	s_add_u32 m0, m0, 0x1000
	s_nop 0
	global_load_lds_dwordx4 v[140:141], off
	s_add_u32 m0, m0, 0x1000
	s_nop 0
	global_load_lds_dwordx4 v[142:143], off
	s_add_u32 m0, m0, 0x1000
	s_nop 0
	global_load_lds_dwordx4 v[144:145], off
	s_mov_b32 s14, 1
	s_lshl_b64 s[12:13], s[14:15], 14
	v_lshl_add_u64 v[244:245], v[154:155], 0, s[12:13]
	s_add_u32 s12, s12, 0x1000
	s_addc_u32 s13, s13, 0
	v_lshl_add_u64 v[246:247], v[154:155], 0, s[12:13]
	s_add_u32 s12, s12, 0x1000
	s_addc_u32 s13, s13, 0
	v_lshl_add_u64 v[248:249], v[154:155], 0, s[12:13]
	s_add_u32 s12, s12, 0x1000
	s_addc_u32 s13, s13, 0
	v_lshl_add_u64 v[140:141], v[154:155], 0, s[12:13]
	s_lshl_b64 s[12:13], s[14:15], 13
	v_lshl_add_u64 v[142:143], v[156:157], 0, s[12:13]
	s_add_u32 s12, s12, 0x1000
	s_addc_u32 s13, s13, 0
	v_lshl_add_u64 v[144:145], v[156:157], 0, s[12:13]
	s_add_u32 m0, s72, 0x6000
	s_nop 0
	global_load_lds_dwordx4 v[244:245], off
	s_add_u32 m0, m0, 0x1000
	s_nop 0
	global_load_lds_dwordx4 v[246:247], off
	s_add_u32 m0, m0, 0x1000
	s_nop 0
	global_load_lds_dwordx4 v[248:249], off
	s_add_u32 m0, m0, 0x1000
	s_nop 0
	global_load_lds_dwordx4 v[140:141], off
	s_add_u32 m0, m0, 0x1000
	s_nop 0
	global_load_lds_dwordx4 v[142:143], off
	s_add_u32 m0, m0, 0x1000
	s_nop 0
	global_load_lds_dwordx4 v[144:145], off
	s_mov_b32 s14, 2
	s_lshl_b64 s[12:13], s[14:15], 14
	v_lshl_add_u64 v[244:245], v[154:155], 0, s[12:13]
	s_add_u32 s12, s12, 0x1000
	s_addc_u32 s13, s13, 0
	v_lshl_add_u64 v[246:247], v[154:155], 0, s[12:13]
	s_add_u32 s12, s12, 0x1000
	s_addc_u32 s13, s13, 0
	v_lshl_add_u64 v[248:249], v[154:155], 0, s[12:13]
	s_add_u32 s12, s12, 0x1000
	s_addc_u32 s13, s13, 0
	v_lshl_add_u64 v[140:141], v[154:155], 0, s[12:13]
	s_lshl_b64 s[12:13], s[14:15], 13
	v_lshl_add_u64 v[142:143], v[156:157], 0, s[12:13]
	s_add_u32 s12, s12, 0x1000
	s_addc_u32 s13, s13, 0
	v_lshl_add_u64 v[144:145], v[156:157], 0, s[12:13]
	s_add_u32 m0, s72, 0xc000
	s_nop 0
	global_load_lds_dwordx4 v[244:245], off
	s_add_u32 m0, m0, 0x1000
	s_nop 0
	global_load_lds_dwordx4 v[246:247], off
	s_add_u32 m0, m0, 0x1000
	s_nop 0
	global_load_lds_dwordx4 v[248:249], off
	s_add_u32 m0, m0, 0x1000
	s_nop 0
	global_load_lds_dwordx4 v[140:141], off
	s_add_u32 m0, m0, 0x1000
	s_nop 0
	global_load_lds_dwordx4 v[142:143], off
	s_add_u32 m0, m0, 0x1000
	s_nop 0
	global_load_lds_dwordx4 v[144:145], off
	v_and_b32_e32 v2, 0xfffff9f, v6
	v_mul_lo_u32 v160, v2, s0
	v_or_b32_e32 v2, 0x60, v6
	v_lshrrev_b32_e32 v0, 1, v6
	v_and_b32_e32 v3, 0x5f, v6
	v_mul_lo_u32 v161, v2, s0
	v_mov_b32_e32 v2, 0
	s_mov_b32 s9, 0
	v_and_b32_e32 v0, 16, v0
	v_mul_u32_u24_e32 v159, 0x50, v3
	v_mov_b32_e32 v3, v2
	v_mov_b32_e32 v4, v2
	v_mov_b32_e32 v5, v2
	v_mov_b32_e32 v6, v2
	v_mov_b32_e32 v7, v2
	v_mov_b32_e32 v8, v2
	v_mov_b32_e32 v9, v2
	v_mov_b32_e32 v10, v2
	v_mov_b32_e32 v11, v2
	v_mov_b32_e32 v12, v2
	v_mov_b32_e32 v13, v2
	v_mov_b32_e32 v14, v2
	v_mov_b32_e32 v15, v2
	v_mov_b32_e32 v16, v2
	v_mov_b32_e32 v17, v2
	v_mov_b32_e32 v18, v2
	v_mov_b32_e32 v19, v2
	v_mov_b32_e32 v20, v2
	v_mov_b32_e32 v21, v2
	v_mov_b32_e32 v22, v2
	v_mov_b32_e32 v23, v2
	v_mov_b32_e32 v24, v2
	v_mov_b32_e32 v25, v2
	v_mov_b32_e32 v26, v2
	v_mov_b32_e32 v27, v2
	v_mov_b32_e32 v28, v2
	v_mov_b32_e32 v29, v2
	v_mov_b32_e32 v30, v2
	v_mov_b32_e32 v31, v2
	v_mov_b32_e32 v32, v2
	v_mov_b32_e32 v33, v2
	v_mov_b32_e32 v34, v2
	v_mov_b32_e32 v35, v2
	v_mov_b32_e32 v36, v2
	v_mov_b32_e32 v37, v2
	v_mov_b32_e32 v38, v2
	v_mov_b32_e32 v39, v2
	v_mov_b32_e32 v40, v2
	v_mov_b32_e32 v41, v2
	v_mov_b32_e32 v42, v2
	v_mov_b32_e32 v43, v2
	v_mov_b32_e32 v44, v2
	v_mov_b32_e32 v45, v2
	v_mov_b32_e32 v46, v2
	v_mov_b32_e32 v47, v2
	v_mov_b32_e32 v48, v2
	v_mov_b32_e32 v49, v2
	v_mov_b32_e32 v50, v2
	v_mov_b32_e32 v51, v2
	v_mov_b32_e32 v52, v2
	v_mov_b32_e32 v53, v2
	v_mov_b32_e32 v54, v2
	v_mov_b32_e32 v55, v2
	v_mov_b32_e32 v56, v2
	v_mov_b32_e32 v57, v2
	v_mov_b32_e32 v58, v2
	v_mov_b32_e32 v59, v2
	v_mov_b32_e32 v60, v2
	v_mov_b32_e32 v61, v2
	v_mov_b32_e32 v62, v2
	v_mov_b32_e32 v63, v2
	v_mov_b32_e32 v64, v2
	v_mov_b32_e32 v65, v2
	v_mov_b32_e32 v66, v2
	v_mov_b32_e32 v67, v2
	v_mov_b32_e32 v68, v2
	v_mov_b32_e32 v69, v2
	v_mov_b32_e32 v70, v2
	v_mov_b32_e32 v71, v2
	v_mov_b32_e32 v72, v2
	v_mov_b32_e32 v73, v2
	v_mov_b32_e32 v74, v2
	v_mov_b32_e32 v75, v2
	v_mov_b32_e32 v76, v2
	v_mov_b32_e32 v77, v2
	v_mov_b32_e32 v78, v2
	v_mov_b32_e32 v79, v2
	v_mov_b32_e32 v80, v2
	v_mov_b32_e32 v81, v2
	s_waitcnt vmcnt(17)
	v_mov_b32_e32 v82, v2
	v_mov_b32_e32 v83, v2
	v_mov_b32_e32 v84, v2
	v_mov_b32_e32 v85, v2
	s_waitcnt vmcnt(16)
	v_mov_b32_e32 v86, v2
	v_mov_b32_e32 v87, v2
	v_mov_b32_e32 v88, v2
	v_mov_b32_e32 v89, v2
	s_waitcnt vmcnt(15)
	v_mov_b32_e32 v90, v2
	v_mov_b32_e32 v91, v2
	v_mov_b32_e32 v92, v2
	v_mov_b32_e32 v93, v2
	s_waitcnt vmcnt(14)
	v_mov_b32_e32 v94, v2
	v_mov_b32_e32 v95, v2
	v_mov_b32_e32 v96, v2
	v_mov_b32_e32 v97, v2
	v_mov_b32_e32 v98, v2
	v_mov_b32_e32 v99, v2
	v_mov_b32_e32 v100, v2
	v_mov_b32_e32 v101, v2
	v_mov_b32_e32 v102, v2
	v_mov_b32_e32 v103, v2
	v_mov_b32_e32 v104, v2
	v_mov_b32_e32 v105, v2
	v_mov_b32_e32 v106, v2
	v_mov_b32_e32 v107, v2
	v_mov_b32_e32 v108, v2
	v_mov_b32_e32 v109, v2
	v_mov_b32_e32 v110, v2
	v_mov_b32_e32 v111, v2
	v_mov_b32_e32 v112, v2
	v_mov_b32_e32 v113, v2
	v_mov_b32_e32 v114, v2
	v_mov_b32_e32 v115, v2
	v_mov_b32_e32 v116, v2
	v_mov_b32_e32 v117, v2
	v_mov_b32_e32 v118, v2
	v_mov_b32_e32 v119, v2
	v_mov_b32_e32 v120, v2
	v_mov_b32_e32 v121, v2
	v_mov_b32_e32 v122, v2
	v_mov_b32_e32 v123, v2
	v_mov_b32_e32 v124, v2
	v_mov_b32_e32 v125, v2
	v_mov_b32_e32 v126, v2
	v_mov_b32_e32 v127, v2
	v_mov_b32_e32 v128, v2
	v_mov_b32_e32 v129, v2
	s_mov_b32 s9, 0
	s_mov_b32 s34, 0
	v_mov_b32_e32 v138, v132
	v_mov_b32_e32 v139, v133
	s_waitcnt vmcnt(12)
	s_barrier
	ds_read_b128 v[162:165], v138 offset:0
	ds_read_b128 v[228:231], v139 offset:0
	ds_read_b128 v[236:239], v139 offset:2048
	ds_read_b128 v[204:207], v138 offset:2048
	ds_read_b128 v[212:215], v138 offset:4096
	ds_read_b128 v[220:223], v138 offset:6144
.Lg92_loop:
	v_add_u32_e32 v136, s34, v134
	v_add_u32_e32 v137, s34, v135
	ds_read_b128 v[166:169], v136 offset:0
	ds_read_b128 v[232:235], v137 offset:0
	ds_read_b128 v[240:243], v137 offset:2048
	ds_read_b128 v[208:211], v136 offset:2048
	ds_read_b128 v[216:219], v136 offset:4096
	ds_read_b128 v[224:227], v136 offset:6144
	s_add_i32 s9, s9, 1
	s_add_u32 s73, s34, 0x6000
	s_cmp_lt_u32 s73, 0x12000
	s_cselect_b32 s73, s73, 0
	v_add_u32_e32 v138, s73, v132
	v_add_u32_e32 v139, s73, v133
	s_waitcnt lgkmcnt(6)
	v_mfma_f32_32x32x16_bf16 v[114:129], v[162:165], v[228:231], v[114:129]
	s_add_i32 s14, s9, 2
	s_lshl_b64 s[12:13], s[14:15], 14
	v_lshl_add_u64 v[244:245], v[154:155], 0, s[12:13]
	v_mfma_f32_32x32x16_bf16 v[98:113], v[162:165], v[236:239], v[98:113]
	s_add_u32 s12, s12, 0x1000
	s_addc_u32 s13, s13, 0
	v_lshl_add_u64 v[246:247], v[154:155], 0, s[12:13]
	v_mfma_f32_32x32x16_bf16 v[82:97], v[204:207], v[228:231], v[82:97]
	s_add_u32 s12, s12, 0x1000
	s_addc_u32 s13, s13, 0
	v_lshl_add_u64 v[248:249], v[154:155], 0, s[12:13]
	v_mfma_f32_32x32x16_bf16 v[66:81], v[204:207], v[236:239], v[66:81]
	s_add_u32 s12, s12, 0x1000
	s_addc_u32 s13, s13, 0
	v_lshl_add_u64 v[140:141], v[154:155], 0, s[12:13]
	v_mfma_f32_32x32x16_bf16 v[50:65], v[212:215], v[228:231], v[50:65]
	s_lshl_b64 s[12:13], s[14:15], 13
	v_lshl_add_u64 v[142:143], v[156:157], 0, s[12:13]
	v_mfma_f32_32x32x16_bf16 v[34:49], v[212:215], v[236:239], v[34:49]
	s_add_u32 s12, s12, 0x1000
	s_addc_u32 s13, s13, 0
	v_lshl_add_u64 v[144:145], v[156:157], 0, s[12:13]
	v_mfma_f32_32x32x16_bf16 v[18:33], v[220:223], v[228:231], v[18:33]
	v_mfma_f32_32x32x16_bf16 v[2:17], v[220:223], v[236:239], v[2:17]
	s_waitcnt vmcnt(6) lgkmcnt(0)
	s_barrier
	s_add_u32 m0, s34, s72
	v_mfma_f32_32x32x16_bf16 v[114:129], v[166:169], v[232:235], v[114:129]
	global_load_lds_dwordx4 v[244:245], off
	ds_read_b128 v[162:165], v138 offset:0
	ds_read_b128 v[228:231], v139 offset:0
	s_add_u32 m0, m0, 0x1000
	v_mfma_f32_32x32x16_bf16 v[98:113], v[166:169], v[240:243], v[98:113]
	global_load_lds_dwordx4 v[246:247], off
	ds_read_b128 v[236:239], v139 offset:2048
	ds_read_b128 v[204:207], v138 offset:2048
	s_add_u32 m0, m0, 0x1000
	v_mfma_f32_32x32x16_bf16 v[82:97], v[208:211], v[232:235], v[82:97]
	global_load_lds_dwordx4 v[248:249], off
	ds_read_b128 v[212:215], v138 offset:4096
	ds_read_b128 v[220:223], v138 offset:6144
	s_add_u32 m0, m0, 0x1000
	v_mfma_f32_32x32x16_bf16 v[66:81], v[208:211], v[240:243], v[66:81]
	global_load_lds_dwordx4 v[140:141], off
	s_add_u32 m0, m0, 0x1000
	v_mfma_f32_32x32x16_bf16 v[50:65], v[216:219], v[232:235], v[50:65]
	global_load_lds_dwordx4 v[142:143], off
	s_add_u32 m0, m0, 0x1000
	v_mfma_f32_32x32x16_bf16 v[34:49], v[216:219], v[240:243], v[34:49]
	global_load_lds_dwordx4 v[144:145], off
	v_mfma_f32_32x32x16_bf16 v[18:33], v[224:227], v[232:235], v[18:33]
	v_mfma_f32_32x32x16_bf16 v[2:17], v[224:227], v[240:243], v[2:17]
	s_mov_b32 s34, s73
	s_cmp_lg_u32 s9, 29
	s_cbranch_scc1 .Lg92_loop
	v_add_u32_e32 v136, s34, v134
	v_add_u32_e32 v137, s34, v135
	ds_read_b128 v[166:169], v136 offset:0
	ds_read_b128 v[232:235], v137 offset:0
	ds_read_b128 v[240:243], v137 offset:2048
	ds_read_b128 v[208:211], v136 offset:2048
	ds_read_b128 v[216:219], v136 offset:4096
	ds_read_b128 v[224:227], v136 offset:6144
	s_add_i32 s9, s9, 1
	s_add_u32 s73, s34, 0x6000
	s_cmp_lt_u32 s73, 0x12000
	s_cselect_b32 s73, s73, 0
	v_add_u32_e32 v138, s73, v132
	v_add_u32_e32 v139, s73, v133
	s_waitcnt lgkmcnt(6)
	v_mfma_f32_32x32x16_bf16 v[114:129], v[162:165], v[228:231], v[114:129]
	v_mfma_f32_32x32x16_bf16 v[98:113], v[162:165], v[236:239], v[98:113]
	v_mfma_f32_32x32x16_bf16 v[82:97], v[204:207], v[228:231], v[82:97]
	v_mfma_f32_32x32x16_bf16 v[66:81], v[204:207], v[236:239], v[66:81]
	v_mfma_f32_32x32x16_bf16 v[50:65], v[212:215], v[228:231], v[50:65]
	v_mfma_f32_32x32x16_bf16 v[34:49], v[212:215], v[236:239], v[34:49]
	v_mfma_f32_32x32x16_bf16 v[18:33], v[220:223], v[228:231], v[18:33]
	v_mfma_f32_32x32x16_bf16 v[2:17], v[220:223], v[236:239], v[2:17]
	s_waitcnt vmcnt(6) lgkmcnt(0)
	s_barrier
	v_mfma_f32_32x32x16_bf16 v[114:129], v[166:169], v[232:235], v[114:129]
	ds_read_b128 v[162:165], v138 offset:0
	ds_read_b128 v[228:231], v139 offset:0
	v_mfma_f32_32x32x16_bf16 v[98:113], v[166:169], v[240:243], v[98:113]
	ds_read_b128 v[236:239], v139 offset:2048
	ds_read_b128 v[204:207], v138 offset:2048
	v_mfma_f32_32x32x16_bf16 v[82:97], v[208:211], v[232:235], v[82:97]
	ds_read_b128 v[212:215], v138 offset:4096
	ds_read_b128 v[220:223], v138 offset:6144
	v_mfma_f32_32x32x16_bf16 v[66:81], v[208:211], v[240:243], v[66:81]
	v_mfma_f32_32x32x16_bf16 v[50:65], v[216:219], v[232:235], v[50:65]
	v_mfma_f32_32x32x16_bf16 v[34:49], v[216:219], v[240:243], v[34:49]
	v_mfma_f32_32x32x16_bf16 v[18:33], v[224:227], v[232:235], v[18:33]
	v_mfma_f32_32x32x16_bf16 v[2:17], v[224:227], v[240:243], v[2:17]
	s_mov_b32 s34, s73
	v_add_u32_e32 v136, s34, v134
	v_add_u32_e32 v137, s34, v135
	ds_read_b128 v[166:169], v136 offset:0
	ds_read_b128 v[232:235], v137 offset:0
	ds_read_b128 v[240:243], v137 offset:2048
	ds_read_b128 v[208:211], v136 offset:2048
	ds_read_b128 v[216:219], v136 offset:4096
	ds_read_b128 v[224:227], v136 offset:6144
	s_add_i32 s9, s9, 1
	s_add_u32 s73, s34, 0x6000
	s_cmp_lt_u32 s73, 0x12000
	s_cselect_b32 s73, s73, 0
	v_add_u32_e32 v138, s73, v132
	v_add_u32_e32 v139, s73, v133
	s_waitcnt lgkmcnt(6)
	v_mfma_f32_32x32x16_bf16 v[114:129], v[162:165], v[228:231], v[114:129]
	v_mfma_f32_32x32x16_bf16 v[98:113], v[162:165], v[236:239], v[98:113]
	v_mfma_f32_32x32x16_bf16 v[82:97], v[204:207], v[228:231], v[82:97]
	v_mfma_f32_32x32x16_bf16 v[66:81], v[204:207], v[236:239], v[66:81]
	v_mfma_f32_32x32x16_bf16 v[50:65], v[212:215], v[228:231], v[50:65]
	v_mfma_f32_32x32x16_bf16 v[34:49], v[212:215], v[236:239], v[34:49]
	v_mfma_f32_32x32x16_bf16 v[18:33], v[220:223], v[228:231], v[18:33]
	v_mfma_f32_32x32x16_bf16 v[2:17], v[220:223], v[236:239], v[2:17]
	s_waitcnt vmcnt(0) lgkmcnt(0)
	s_barrier
	v_mfma_f32_32x32x16_bf16 v[114:129], v[166:169], v[232:235], v[114:129]
	ds_read_b128 v[162:165], v138 offset:0
	ds_read_b128 v[228:231], v139 offset:0
	v_mfma_f32_32x32x16_bf16 v[98:113], v[166:169], v[240:243], v[98:113]
	ds_read_b128 v[236:239], v139 offset:2048
	ds_read_b128 v[204:207], v138 offset:2048
	v_mfma_f32_32x32x16_bf16 v[82:97], v[208:211], v[232:235], v[82:97]
	ds_read_b128 v[212:215], v138 offset:4096
	ds_read_b128 v[220:223], v138 offset:6144
	v_mfma_f32_32x32x16_bf16 v[66:81], v[208:211], v[240:243], v[66:81]
	v_mfma_f32_32x32x16_bf16 v[50:65], v[216:219], v[232:235], v[50:65]
	v_mfma_f32_32x32x16_bf16 v[34:49], v[216:219], v[240:243], v[34:49]
	v_mfma_f32_32x32x16_bf16 v[18:33], v[224:227], v[232:235], v[18:33]
	v_mfma_f32_32x32x16_bf16 v[2:17], v[224:227], v[240:243], v[2:17]
	s_mov_b32 s34, s73
	v_add_u32_e32 v136, s34, v134
	v_add_u32_e32 v137, s34, v135
	ds_read_b128 v[166:169], v136 offset:0
	ds_read_b128 v[232:235], v137 offset:0
	ds_read_b128 v[240:243], v137 offset:2048
	ds_read_b128 v[208:211], v136 offset:2048
	ds_read_b128 v[216:219], v136 offset:4096
	ds_read_b128 v[224:227], v136 offset:6144
	s_add_i32 s9, s9, 1
	s_waitcnt lgkmcnt(6)
	v_mfma_f32_32x32x16_bf16 v[114:129], v[162:165], v[228:231], v[114:129]
	v_mfma_f32_32x32x16_bf16 v[98:113], v[162:165], v[236:239], v[98:113]
	v_mfma_f32_32x32x16_bf16 v[82:97], v[204:207], v[228:231], v[82:97]
	v_mfma_f32_32x32x16_bf16 v[66:81], v[204:207], v[236:239], v[66:81]
	v_mfma_f32_32x32x16_bf16 v[50:65], v[212:215], v[228:231], v[50:65]
	v_mfma_f32_32x32x16_bf16 v[34:49], v[212:215], v[236:239], v[34:49]
	v_mfma_f32_32x32x16_bf16 v[18:33], v[220:223], v[228:231], v[18:33]
	v_mfma_f32_32x32x16_bf16 v[2:17], v[220:223], v[236:239], v[2:17]
	s_waitcnt lgkmcnt(0)
	v_mfma_f32_32x32x16_bf16 v[114:129], v[166:169], v[232:235], v[114:129]
	v_mfma_f32_32x32x16_bf16 v[98:113], v[166:169], v[240:243], v[98:113]
	v_mfma_f32_32x32x16_bf16 v[82:97], v[208:211], v[232:235], v[82:97]
	v_mfma_f32_32x32x16_bf16 v[66:81], v[208:211], v[240:243], v[66:81]
	v_mfma_f32_32x32x16_bf16 v[50:65], v[216:219], v[232:235], v[50:65]
	v_mfma_f32_32x32x16_bf16 v[34:49], v[216:219], v[240:243], v[34:49]
	v_mfma_f32_32x32x16_bf16 v[18:33], v[224:227], v[232:235], v[18:33]
	v_mfma_f32_32x32x16_bf16 v[2:17], v[224:227], v[240:243], v[2:17]
	s_mov_b32 s14, 31
	s_lshl_b64 s[12:13], s[14:15], 13
	s_movk_i32 s34, 0x7800
	s_movk_i32 s72, 0x6000
	s_mov_b32 s73, 0xc000
	v_mov_b32_e32 v0, v171
	s_barrier
	s_waitcnt vmcnt(4)
	v_lshrrev_b32_e32 v130, 1, v0
	v_and_b32_e32 v130, 0xfffffc0, v130
	v_lshrrev_b32_e32 v131, 3, v0
	v_and_or_b32 v130, v131, 4, v130
	v_and_b32_e32 v0, 0x5f, v0
	v_mul_lo_u32 v130, v130, s53
	v_lshl_add_u32 v0, v0, 2, v130
	s_barrier
	ds_write2_b32 v0, v114, v98 offset1:32
	ds_write2_b32 v0, v115, v99 offset0:132 offset1:164
	v_add_u32_e32 v98, 0x400, v0
	ds_write2_b32 v98, v116, v100 offset0:8 offset1:40
	ds_write2_b32 v98, v117, v101 offset0:140 offset1:172
	v_add_u32_e32 v98, 0x1000, v0
	ds_write2_b32 v98, v118, v102 offset0:32 offset1:64
	ds_write2_b32 v98, v119, v103 offset0:164 offset1:196
	v_add_u32_e32 v98, 0x1400, v0
	ds_write2_b32 v98, v120, v104 offset0:40 offset1:72
	ds_write2_b32 v98, v121, v105 offset0:172 offset1:204
	v_add_u32_e32 v98, 0x2000, v0
	ds_write2_b32 v98, v122, v106 offset0:64 offset1:96
	ds_write2_b32 v98, v123, v107 offset0:196 offset1:228
	v_add_u32_e32 v98, 0x2400, v0
	ds_write2_b32 v98, v124, v108 offset0:72 offset1:104
	ds_write2_b32 v98, v125, v109 offset0:204 offset1:236
	v_add_u32_e32 v98, 0x3000, v0
	ds_write2_b32 v98, v126, v110 offset0:96 offset1:128
	v_add_u32_e32 v98, 0x3200, v0
	ds_write2_b32 v98, v127, v111 offset0:100 offset1:132
	v_add_u32_e32 v98, 0x3400, v0
	ds_write2_b32 v98, v128, v112 offset0:104 offset1:136
	v_add_u32_e32 v98, 0x3600, v0
	ds_write2_b32 v98, v129, v113 offset0:108 offset1:140
	v_add_u32_e32 v98, 0x4000, v0
	ds_write2_b32 v98, v82, v66 offset0:128 offset1:160
	v_add_u32_e32 v66, 0x4400, v0
	ds_write2_b32 v66, v83, v67 offset0:4 offset1:36
	ds_write2_b32 v66, v84, v68 offset0:136 offset1:168
	v_add_u32_e32 v66, 0x4800, v0
	ds_write2_b32 v66, v85, v69 offset0:12 offset1:44
	v_add_u32_e32 v66, 0x5000, v0
	ds_write2_b32 v66, v86, v70 offset0:160 offset1:192
	v_add_u32_e32 v66, 0x5400, v0
	ds_write2_b32 v66, v87, v71 offset0:36 offset1:68
	ds_write2_b32 v66, v88, v72 offset0:168 offset1:200
	v_add_u32_e32 v66, 0x5800, v0
	ds_write2_b32 v66, v89, v73 offset0:44 offset1:76
	v_add_u32_e32 v66, 0x6000, v0
	ds_write2_b32 v66, v90, v74 offset0:192 offset1:224
	v_add_u32_e32 v66, 0x6400, v0
	ds_write2_b32 v66, v91, v75 offset0:68 offset1:100
	ds_write2_b32 v66, v92, v76 offset0:200 offset1:232
	v_add_u32_e32 v66, 0x6800, v0
	ds_write2_b32 v66, v93, v77 offset0:76 offset1:108
	v_add_u32_e32 v66, 0x7200, v0
	ds_write2_b32 v66, v94, v78 offset0:96 offset1:128
	v_add_u32_e32 v66, 0x7400, v0
	ds_write2_b32 v66, v95, v79 offset0:100 offset1:132
	v_add_u32_e32 v66, 0x7600, v0
	v_add_u32_e32 v0, 0x7800, v0
	v_mov_b32_e32 v74, v171
	ds_write2_b32 v66, v96, v80 offset0:104 offset1:136
	ds_write2_b32 v0, v97, v81 offset0:108 offset1:140
	s_waitcnt lgkmcnt(0)
	s_barrier
	s_lshl_b32 s8, s8, 7
	v_lshlrev_b32_e32 v75, 3, v74
	v_and_b32_e32 v0, 0x78, v75
	v_or_b32_e32 v0, s8, v0
	v_lshl_add_u64 v[70:71], v[0:1], 2, s[6:7]
	global_load_dwordx4 v[66:69], v[70:71], off
	s_nop 0
	global_load_dwordx4 v[70:73], v[70:71], off offset:16
	v_ashrrev_i32_e32 v76, 4, v74
	v_lshrrev_b32_e32 v77, 5, v0
	v_and_b32_e32 v0, 24, v75
	v_mul_lo_u32 v75, v76, s53
	v_and_b32_e32 v74, 15, v74
	v_readlane_b32 s0, v252, 46
	s_lshl_b32 s9, s11, 8
	v_lshl_add_u32 v78, v74, 5, v75
	v_lshlrev_b32_e32 v79, 1, v76
	s_mov_b32 s11, 0
	v_lshlrev_b32_e32 v74, 1, v0
	v_readlane_b32 s1, v252, 47
	s_waitcnt vmcnt(0)

.LBB0_279:
	v_mul_u32_u24_e32 v66, s36, v150
	v_mul_u32_u24_e32 v67, s36, v154
	v_mul_u32_u24_e32 v68, s36, v158
	v_mul_u32_u24_e32 v69, s36, v162
	v_add_lshl_u32 v66, v66, v152, 1
	v_add_lshl_u32 v67, v67, v156, 1
	v_add_lshl_u32 v68, v68, v160, 1
	v_add_lshl_u32 v69, v69, v164, 1
	global_load_dwordx4 v[118:121], v66, s[10:11]
	global_load_dwordx4 v[114:117], v67, s[10:11]
	global_load_dwordx4 v[126:129], v68, s[10:11]
	global_load_dwordx4 v[122:125], v69, s[10:11]
	v_mul_u32_u24_e32 v66, s12, v166
	v_mul_u32_u24_e32 v67, s12, v170
	v_mul_u32_u24_e32 v68, s12, v172
	v_mul_u32_u24_e32 v69, s12, v174
	v_lshl_add_u32 v66, v66, 1, v0
	v_lshl_add_u32 v67, v67, 1, v0
	v_lshl_add_u32 v68, v68, 1, v0
	v_lshl_add_u32 v69, v69, 1, v0
	global_load_dwordx4 v[134:137], v66, s[8:9]
	global_load_dwordx4 v[130:133], v67, s[8:9]
	global_load_dwordx4 v[142:145], v68, s[8:9]
	global_load_dwordx4 v[138:141], v69, s[8:9]
	v_add_u32_e32 v0, s79, v213
	v_lshlrev_b32_e32 v78, 1, v205
	v_lshlrev_b32_e32 v79, 1, v148
	v_add3_u32 v0, v0, v78, v79
	ds_read_b128 v[218:221], v0
	ds_read_b128 v[222:225], v0 offset:32
	ds_read_b128 v[226:229], v0 offset:8704
	ds_read_b128 v[230:233], v0 offset:8736
	ds_read_b128 v[234:237], v0 offset:64
	ds_read_b128 v[238:241], v0 offset:96
	ds_read_b128 v[242:245], v0 offset:8768
	ds_read_b128 v[246:249], v0 offset:8800
	v_xor_b32_e32 v66, 0x80000000, v216
	v_mov_b32_e32 v67, v66
	v_mov_b32_e32 v68, v66
	v_mov_b32_e32 v69, v66
	v_mov_b32_e32 v70, v66
	v_mov_b32_e32 v71, v66
	v_mov_b32_e32 v72, v66
	v_mov_b32_e32 v73, v66
	v_mov_b32_e32 v74, v66
	v_mov_b32_e32 v75, v66
	v_mov_b32_e32 v76, v66
	v_mov_b32_e32 v77, v66
	v_mov_b32_e32 v78, v66
	v_mov_b32_e32 v79, v66
	v_mov_b32_e32 v80, v66
	v_mov_b32_e32 v81, v66
	s_waitcnt lgkmcnt(7)
	s_nop 0
	v_mfma_f32_32x32x16_bf16 v[82:97], v[218:221], v[98:101], v[66:81]
	s_mov_b32 s0, 0x41600000
	s_waitcnt lgkmcnt(6)
	v_mfma_f32_32x32x16_bf16 v[82:97], v[222:225], v[102:105], v[82:97]
	s_waitcnt lgkmcnt(5)
	v_mfma_f32_32x32x16_bf16 v[66:81], v[226:229], v[98:101], v[66:81]
	s_waitcnt lgkmcnt(3)
	v_mfma_f32_32x32x16_bf16 v[82:97], v[234:237], v[106:109], v[82:97]
	v_mfma_f32_32x32x16_bf16 v[66:81], v[230:233], v[102:105], v[66:81]
	s_waitcnt lgkmcnt(2)
	v_mfma_f32_32x32x16_bf16 v[82:97], v[238:241], v[110:113], v[82:97]
	s_waitcnt lgkmcnt(1)
	v_mfma_f32_32x32x16_bf16 v[66:81], v[242:245], v[106:109], v[66:81]
	s_nop 9
	v_max_f32_e32 v0, v83, v83
	v_max_f32_e32 v217, v82, v82
	v_max_f32_e32 v0, v217, v0
	v_max3_f32 v0, v0, v84, v85
	v_max3_f32 v0, v0, v86, v87
	v_max3_f32 v0, v0, v88, v89
	v_max3_f32 v0, v0, v90, v91
	s_waitcnt lgkmcnt(0)
	v_mfma_f32_32x32x16_bf16 v[66:81], v[246:249], v[110:113], v[66:81]
	v_max3_f32 v0, v0, v92, v93
	v_max3_f32 v0, v0, v94, v95
	v_max3_f32 v0, v0, v96, v97
	s_nop 8
	v_max3_f32 v0, v0, v66, v67
	v_max3_f32 v0, v0, v68, v69
	v_max3_f32 v0, v0, v70, v71
	v_max3_f32 v0, v0, v72, v73
	v_max3_f32 v0, v0, v74, v75
	v_max3_f32 v0, v0, v76, v77
	v_max3_f32 v0, v0, v78, v79
	v_max3_f32 v0, v0, v80, v81
	v_cmp_lt_f32_e32 vcc, s0, v0
	s_cbranch_vccz .LBB0_270
	v_cmp_lt_i32_e32 vcc, v186, v185
	s_nop 1
	v_cndmask_b32_e32 v217, v183, v186, vcc
	v_lshlrev_b32_e32 v217, 2, v217
	ds_bpermute_b32 v217, v217, v0
	s_waitcnt lgkmcnt(0)
	v_max3_f32 v0, v0, v217, 0
	v_exp_f32_e64 v218, -v0
	v_add_f32_e32 v216, v216, v0
	v_pk_add_f32 v[82:83], v[82:83], v[0:1] op_sel_hi:[1,0] neg_lo:[0,1] neg_hi:[0,1]
	v_pk_add_f32 v[66:67], v[66:67], v[0:1] op_sel_hi:[1,0] neg_lo:[0,1] neg_hi:[0,1]
	v_pk_add_f32 v[84:85], v[84:85], v[0:1] op_sel_hi:[1,0] neg_lo:[0,1] neg_hi:[0,1]
	v_pk_add_f32 v[68:69], v[68:69], v[0:1] op_sel_hi:[1,0] neg_lo:[0,1] neg_hi:[0,1]
	v_pk_add_f32 v[86:87], v[86:87], v[0:1] op_sel_hi:[1,0] neg_lo:[0,1] neg_hi:[0,1]
	v_pk_add_f32 v[70:71], v[70:71], v[0:1] op_sel_hi:[1,0] neg_lo:[0,1] neg_hi:[0,1]
	v_pk_add_f32 v[88:89], v[88:89], v[0:1] op_sel_hi:[1,0] neg_lo:[0,1] neg_hi:[0,1]
	v_pk_add_f32 v[72:73], v[72:73], v[0:1] op_sel_hi:[1,0] neg_lo:[0,1] neg_hi:[0,1]
	v_pk_add_f32 v[90:91], v[90:91], v[0:1] op_sel_hi:[1,0] neg_lo:[0,1] neg_hi:[0,1]
	v_pk_add_f32 v[74:75], v[74:75], v[0:1] op_sel_hi:[1,0] neg_lo:[0,1] neg_hi:[0,1]
	v_pk_add_f32 v[92:93], v[92:93], v[0:1] op_sel_hi:[1,0] neg_lo:[0,1] neg_hi:[0,1]
	v_pk_add_f32 v[76:77], v[76:77], v[0:1] op_sel_hi:[1,0] neg_lo:[0,1] neg_hi:[0,1]
	v_pk_add_f32 v[94:95], v[94:95], v[0:1] op_sel_hi:[1,0] neg_lo:[0,1] neg_hi:[0,1]
	v_pk_add_f32 v[78:79], v[78:79], v[0:1] op_sel_hi:[1,0] neg_lo:[0,1] neg_hi:[0,1]
	v_pk_add_f32 v[96:97], v[96:97], v[0:1] op_sel_hi:[1,0] neg_lo:[0,1] neg_hi:[0,1]
	v_pk_add_f32 v[80:81], v[80:81], v[0:1] op_sel_hi:[1,0] neg_lo:[0,1] neg_hi:[0,1]
	v_pk_mul_f32 v[64:65], v[64:65], v[218:219] op_sel_hi:[1,0]
	v_pk_mul_f32 v[62:63], v[62:63], v[218:219] op_sel_hi:[1,0]
	v_pk_mul_f32 v[60:61], v[60:61], v[218:219] op_sel_hi:[1,0]
	v_pk_mul_f32 v[58:59], v[58:59], v[218:219] op_sel_hi:[1,0]
	v_pk_mul_f32 v[56:57], v[56:57], v[218:219] op_sel_hi:[1,0]
	v_pk_mul_f32 v[54:55], v[54:55], v[218:219] op_sel_hi:[1,0]
	v_pk_mul_f32 v[52:53], v[52:53], v[218:219] op_sel_hi:[1,0]
	v_pk_mul_f32 v[50:51], v[50:51], v[218:219] op_sel_hi:[1,0]
	v_pk_mul_f32 v[48:49], v[48:49], v[218:219] op_sel_hi:[1,0]
	v_pk_mul_f32 v[46:47], v[46:47], v[218:219] op_sel_hi:[1,0]
	v_pk_mul_f32 v[44:45], v[44:45], v[218:219] op_sel_hi:[1,0]
	v_pk_mul_f32 v[42:43], v[42:43], v[218:219] op_sel_hi:[1,0]
	v_pk_mul_f32 v[40:41], v[40:41], v[218:219] op_sel_hi:[1,0]
	v_pk_mul_f32 v[38:39], v[38:39], v[218:219] op_sel_hi:[1,0]
	v_pk_mul_f32 v[36:37], v[36:37], v[218:219] op_sel_hi:[1,0]
	v_pk_mul_f32 v[34:35], v[34:35], v[218:219] op_sel_hi:[1,0]
	v_pk_mul_f32 v[32:33], v[32:33], v[218:219] op_sel_hi:[1,0]
	v_pk_mul_f32 v[30:31], v[30:31], v[218:219] op_sel_hi:[1,0]
	v_pk_mul_f32 v[28:29], v[28:29], v[218:219] op_sel_hi:[1,0]
	v_pk_mul_f32 v[26:27], v[26:27], v[218:219] op_sel_hi:[1,0]
	v_pk_mul_f32 v[24:25], v[24:25], v[218:219] op_sel_hi:[1,0]
	v_pk_mul_f32 v[22:23], v[22:23], v[218:219] op_sel_hi:[1,0]
	v_pk_mul_f32 v[20:21], v[20:21], v[218:219] op_sel_hi:[1,0]
	v_pk_mul_f32 v[18:19], v[18:19], v[218:219] op_sel_hi:[1,0]
	v_pk_mul_f32 v[16:17], v[16:17], v[218:219] op_sel_hi:[1,0]
	v_pk_mul_f32 v[14:15], v[14:15], v[218:219] op_sel_hi:[1,0]
	v_pk_mul_f32 v[12:13], v[12:13], v[218:219] op_sel_hi:[1,0]
	v_pk_mul_f32 v[10:11], v[10:11], v[218:219] op_sel_hi:[1,0]
	v_pk_mul_f32 v[8:9], v[8:9], v[218:219] op_sel_hi:[1,0]
	v_pk_mul_f32 v[6:7], v[6:7], v[218:219] op_sel_hi:[1,0]
	v_pk_mul_f32 v[4:5], v[4:5], v[218:219] op_sel_hi:[1,0]
	v_pk_mul_f32 v[2:3], v[2:3], v[218:219] op_sel_hi:[1,0]
	v_mul_f32_e32 v215, v215, v218
	s_branch .LBB0_270

.LBB0_356:
	s_lshr_b32 s6, s12, 3
	s_and_b32 s8, s12, 56
	v_readlane_b32 s0, v252, 42
	s_and_b32 s6, s6, 0xffffff8
	s_and_b32 s7, s12, 7
	s_or_b32 s9, s8, s0
	v_mov_b32_e32 v6, v171
	s_or_b32 s6, s6, s7
	s_lshl_b32 s7, s9, 19
	v_lshlrev_b32_e32 v2, 3, v6
	s_add_u32 s10, s98, s7
	v_ashrrev_i32_e32 v3, 31, v2
	s_addc_u32 s11, s99, 0
	v_lshlrev_b64 v[4:5], 1, v[2:3]
	s_mov_b32 s7, s15
	v_lshl_add_u64 v[154:155], s[10:11], 0, v[4:5]
	s_lshl_b64 s[10:11], s[6:7], 18
	v_readlane_b32 s0, v252, 38
	v_readlane_b32 s1, v252, 39
	s_add_u32 s10, s0, s10
	s_addc_u32 s11, s1, s11
	v_lshrrev_b32_e32 v3, 2, v6
	v_and_b32_e32 v0, 24, v2
	v_lshl_add_u64 v[156:157], s[10:11], 0, v[4:5]
	v_mad_u64_u32 v[158:159], s[10:11], v3, 40, v[0:1]
	s_movk_i32 s0, 0x50
	v_and_b32_e32 v2, 0x30, v6
	v_xor_b32_e32 v154, v154, v2
	v_xor_b32_e32 v156, v156, v2
	v_and_b32_e32 v130, 31, v6
	v_lshlrev_b32_e32 v130, 6, v130
	v_lshrrev_b32_e32 v131, 2, v6
	v_and_b32_e32 v131, 3, v131
	v_bfe_u32 v133, v6, 5, 1
	v_xor_b32_e32 v131, v131, v133
	v_lshl_or_b32 v130, v131, 4, v130
	v_lshrrev_b32_e32 v131, 7, v6
	v_lshl_or_b32 v132, v131, 13, v130
	v_bfe_u32 v131, v6, 6, 1
	v_lshl_or_b32 v133, v131, 12, v130
	v_or_b32_e32 v133, 0x4000, v133
	v_xor_b32_e32 v134, 32, v132
	v_xor_b32_e32 v135, 32, v133
	v_lshrrev_b32_e32 v131, 6, v6
	s_nop 1
	v_readfirstlane_b32 s72, v131
	s_nop 3
	s_lshl_b32 s72, s72, 10
	s_waitcnt lgkmcnt(0)
	s_barrier
	s_mov_b32 s14, 0
	s_lshl_b64 s[10:11], s[14:15], 14
	v_lshl_add_u64 v[244:245], v[154:155], 0, s[10:11]
	s_add_u32 s10, s10, 0x1000
	s_addc_u32 s11, s11, 0
	v_lshl_add_u64 v[246:247], v[154:155], 0, s[10:11]
	s_add_u32 s10, s10, 0x1000
	s_addc_u32 s11, s11, 0
	v_lshl_add_u64 v[248:249], v[154:155], 0, s[10:11]
	s_add_u32 s10, s10, 0x1000
	s_addc_u32 s11, s11, 0
	v_lshl_add_u64 v[140:141], v[154:155], 0, s[10:11]
	s_lshl_b64 s[10:11], s[14:15], 13
	v_lshl_add_u64 v[142:143], v[156:157], 0, s[10:11]
	s_add_u32 s10, s10, 0x1000
	s_addc_u32 s11, s11, 0
	v_lshl_add_u64 v[144:145], v[156:157], 0, s[10:11]
	s_add_u32 m0, s72, 0x0
	s_nop 0
	global_load_lds_dwordx4 v[244:245], off
	s_add_u32 m0, m0, 0x1000
	s_nop 0
	global_load_lds_dwordx4 v[246:247], off
	s_add_u32 m0, m0, 0x1000
	s_nop 0
	global_load_lds_dwordx4 v[248:249], off
	s_add_u32 m0, m0, 0x1000
	s_nop 0
	global_load_lds_dwordx4 v[140:141], off
	s_add_u32 m0, m0, 0x1000
	s_nop 0
	global_load_lds_dwordx4 v[142:143], off
	s_add_u32 m0, m0, 0x1000
	s_nop 0
	global_load_lds_dwordx4 v[144:145], off
	s_mov_b32 s14, 1
	s_lshl_b64 s[10:11], s[14:15], 14
	v_lshl_add_u64 v[244:245], v[154:155], 0, s[10:11]
	s_add_u32 s10, s10, 0x1000
	s_addc_u32 s11, s11, 0
	v_lshl_add_u64 v[246:247], v[154:155], 0, s[10:11]
	s_add_u32 s10, s10, 0x1000
	s_addc_u32 s11, s11, 0
	v_lshl_add_u64 v[248:249], v[154:155], 0, s[10:11]
	s_add_u32 s10, s10, 0x1000
	s_addc_u32 s11, s11, 0
	v_lshl_add_u64 v[140:141], v[154:155], 0, s[10:11]
	s_lshl_b64 s[10:11], s[14:15], 13
	v_lshl_add_u64 v[142:143], v[156:157], 0, s[10:11]
	s_add_u32 s10, s10, 0x1000
	s_addc_u32 s11, s11, 0
	v_lshl_add_u64 v[144:145], v[156:157], 0, s[10:11]
	s_add_u32 m0, s72, 0x6000
	s_nop 0
	global_load_lds_dwordx4 v[244:245], off
	s_add_u32 m0, m0, 0x1000
	s_nop 0
	global_load_lds_dwordx4 v[246:247], off
	s_add_u32 m0, m0, 0x1000
	s_nop 0
	global_load_lds_dwordx4 v[248:249], off
	s_add_u32 m0, m0, 0x1000
	s_nop 0
	global_load_lds_dwordx4 v[140:141], off
	s_add_u32 m0, m0, 0x1000
	s_nop 0
	global_load_lds_dwordx4 v[142:143], off
	s_add_u32 m0, m0, 0x1000
	s_nop 0
	global_load_lds_dwordx4 v[144:145], off
	s_mov_b32 s14, 2
	s_lshl_b64 s[10:11], s[14:15], 14
	v_lshl_add_u64 v[244:245], v[154:155], 0, s[10:11]
	s_add_u32 s10, s10, 0x1000
	s_addc_u32 s11, s11, 0
	v_lshl_add_u64 v[246:247], v[154:155], 0, s[10:11]
	s_add_u32 s10, s10, 0x1000
	s_addc_u32 s11, s11, 0
	v_lshl_add_u64 v[248:249], v[154:155], 0, s[10:11]
	s_add_u32 s10, s10, 0x1000
	s_addc_u32 s11, s11, 0
	v_lshl_add_u64 v[140:141], v[154:155], 0, s[10:11]
	s_lshl_b64 s[10:11], s[14:15], 13
	v_lshl_add_u64 v[142:143], v[156:157], 0, s[10:11]
	s_add_u32 s10, s10, 0x1000
	s_addc_u32 s11, s11, 0
	v_lshl_add_u64 v[144:145], v[156:157], 0, s[10:11]
	s_add_u32 m0, s72, 0xc000
	s_nop 0
	global_load_lds_dwordx4 v[244:245], off
	s_add_u32 m0, m0, 0x1000
	s_nop 0
	global_load_lds_dwordx4 v[246:247], off
	s_add_u32 m0, m0, 0x1000
	s_nop 0
	global_load_lds_dwordx4 v[248:249], off
	s_add_u32 m0, m0, 0x1000
	s_nop 0
	global_load_lds_dwordx4 v[140:141], off
	s_add_u32 m0, m0, 0x1000
	s_nop 0
	global_load_lds_dwordx4 v[142:143], off
	s_add_u32 m0, m0, 0x1000
	s_nop 0
	global_load_lds_dwordx4 v[144:145], off
	v_and_b32_e32 v2, 0xfffff9f, v6
	v_mul_lo_u32 v160, v2, s0
	v_or_b32_e32 v2, 0x60, v6
	v_lshrrev_b32_e32 v0, 1, v6
	v_and_b32_e32 v3, 0x5f, v6
	v_mul_lo_u32 v161, v2, s0
	v_mov_b32_e32 v2, 0
	s_mov_b32 s7, 0
	v_and_b32_e32 v0, 16, v0
	v_mul_u32_u24_e32 v159, 0x50, v3
	v_mov_b32_e32 v3, v2
	v_mov_b32_e32 v4, v2
	v_mov_b32_e32 v5, v2
	v_mov_b32_e32 v6, v2
	v_mov_b32_e32 v7, v2
	v_mov_b32_e32 v8, v2
	v_mov_b32_e32 v9, v2
	v_mov_b32_e32 v10, v2
	v_mov_b32_e32 v11, v2
	v_mov_b32_e32 v12, v2
	v_mov_b32_e32 v13, v2
	v_mov_b32_e32 v14, v2
	v_mov_b32_e32 v15, v2
	v_mov_b32_e32 v16, v2
	v_mov_b32_e32 v17, v2
	v_mov_b32_e32 v18, v2
	v_mov_b32_e32 v19, v2
	v_mov_b32_e32 v20, v2
	v_mov_b32_e32 v21, v2
	v_mov_b32_e32 v22, v2
	v_mov_b32_e32 v23, v2
	v_mov_b32_e32 v24, v2
	v_mov_b32_e32 v25, v2
	v_mov_b32_e32 v26, v2
	v_mov_b32_e32 v27, v2
	v_mov_b32_e32 v28, v2
	v_mov_b32_e32 v29, v2
	v_mov_b32_e32 v30, v2
	v_mov_b32_e32 v31, v2
	v_mov_b32_e32 v32, v2
	v_mov_b32_e32 v33, v2
	v_mov_b32_e32 v34, v2
	v_mov_b32_e32 v35, v2
	v_mov_b32_e32 v36, v2
	v_mov_b32_e32 v37, v2
	v_mov_b32_e32 v38, v2
	v_mov_b32_e32 v39, v2
	v_mov_b32_e32 v40, v2
	v_mov_b32_e32 v41, v2
	v_mov_b32_e32 v42, v2
	v_mov_b32_e32 v43, v2
	v_mov_b32_e32 v44, v2
	v_mov_b32_e32 v45, v2
	v_mov_b32_e32 v46, v2
	v_mov_b32_e32 v47, v2
	v_mov_b32_e32 v48, v2
	v_mov_b32_e32 v49, v2
	v_mov_b32_e32 v50, v2
	v_mov_b32_e32 v51, v2
	v_mov_b32_e32 v52, v2
	v_mov_b32_e32 v53, v2
	v_mov_b32_e32 v54, v2
	v_mov_b32_e32 v55, v2
	v_mov_b32_e32 v56, v2
	v_mov_b32_e32 v57, v2
	v_mov_b32_e32 v58, v2
	v_mov_b32_e32 v59, v2
	v_mov_b32_e32 v60, v2
	v_mov_b32_e32 v61, v2
	v_mov_b32_e32 v62, v2
	v_mov_b32_e32 v63, v2
	v_mov_b32_e32 v64, v2
	v_mov_b32_e32 v65, v2
	v_mov_b32_e32 v66, v2
	v_mov_b32_e32 v67, v2
	v_mov_b32_e32 v68, v2
	v_mov_b32_e32 v69, v2
	v_mov_b32_e32 v70, v2
	v_mov_b32_e32 v71, v2
	v_mov_b32_e32 v72, v2
	v_mov_b32_e32 v73, v2
	v_mov_b32_e32 v74, v2
	v_mov_b32_e32 v75, v2
	v_mov_b32_e32 v76, v2
	v_mov_b32_e32 v77, v2
	v_mov_b32_e32 v78, v2
	v_mov_b32_e32 v79, v2
	v_mov_b32_e32 v80, v2
	v_mov_b32_e32 v81, v2
	s_waitcnt vmcnt(17)
	v_mov_b32_e32 v82, v2
	v_mov_b32_e32 v83, v2
	v_mov_b32_e32 v84, v2
	v_mov_b32_e32 v85, v2
	s_waitcnt vmcnt(16)
	v_mov_b32_e32 v86, v2
	v_mov_b32_e32 v87, v2
	v_mov_b32_e32 v88, v2
	v_mov_b32_e32 v89, v2
	s_waitcnt vmcnt(15)
	v_mov_b32_e32 v90, v2
	v_mov_b32_e32 v91, v2
	v_mov_b32_e32 v92, v2
	v_mov_b32_e32 v93, v2
	s_waitcnt vmcnt(14)
	v_mov_b32_e32 v94, v2
	v_mov_b32_e32 v95, v2
	v_mov_b32_e32 v96, v2
	v_mov_b32_e32 v97, v2
	v_mov_b32_e32 v98, v2
	v_mov_b32_e32 v99, v2
	v_mov_b32_e32 v100, v2
	v_mov_b32_e32 v101, v2
	v_mov_b32_e32 v102, v2
	v_mov_b32_e32 v103, v2
	v_mov_b32_e32 v104, v2
	v_mov_b32_e32 v105, v2
	v_mov_b32_e32 v106, v2
	v_mov_b32_e32 v107, v2
	v_mov_b32_e32 v108, v2
	v_mov_b32_e32 v109, v2
	v_mov_b32_e32 v110, v2
	v_mov_b32_e32 v111, v2
	v_mov_b32_e32 v112, v2
	v_mov_b32_e32 v113, v2
	v_mov_b32_e32 v114, v2
	v_mov_b32_e32 v115, v2
	v_mov_b32_e32 v116, v2
	v_mov_b32_e32 v117, v2
	v_mov_b32_e32 v118, v2
	v_mov_b32_e32 v119, v2
	v_mov_b32_e32 v120, v2
	v_mov_b32_e32 v121, v2
	v_mov_b32_e32 v122, v2
	v_mov_b32_e32 v123, v2
	v_mov_b32_e32 v124, v2
	v_mov_b32_e32 v125, v2
	v_mov_b32_e32 v126, v2
	v_mov_b32_e32 v127, v2
	v_mov_b32_e32 v128, v2
	v_mov_b32_e32 v129, v2
	s_mov_b32 s7, 0
	s_mov_b32 s13, 0
	v_mov_b32_e32 v138, v132
	v_mov_b32_e32 v139, v133
	s_waitcnt vmcnt(12)
	s_barrier
	ds_read_b128 v[162:165], v138 offset:0
	ds_read_b128 v[228:231], v139 offset:0
	ds_read_b128 v[236:239], v139 offset:2048
	ds_read_b128 v[204:207], v138 offset:2048
	ds_read_b128 v[212:215], v138 offset:4096
	ds_read_b128 v[220:223], v138 offset:6144
.Lg357_loop:
	v_add_u32_e32 v136, s13, v134
	v_add_u32_e32 v137, s13, v135
	ds_read_b128 v[166:169], v136 offset:0
	ds_read_b128 v[232:235], v137 offset:0
	ds_read_b128 v[240:243], v137 offset:2048
	ds_read_b128 v[208:211], v136 offset:2048
	ds_read_b128 v[216:219], v136 offset:4096
	ds_read_b128 v[224:227], v136 offset:6144
	s_add_i32 s7, s7, 1
	s_add_u32 s73, s13, 0x6000
	s_cmp_lt_u32 s73, 0x12000
	s_cselect_b32 s73, s73, 0
	v_add_u32_e32 v138, s73, v132
	v_add_u32_e32 v139, s73, v133
	s_waitcnt lgkmcnt(6)
	v_mfma_f32_32x32x16_bf16 v[114:129], v[162:165], v[228:231], v[114:129]
	s_add_i32 s14, s7, 2
	s_lshl_b64 s[10:11], s[14:15], 14
	v_lshl_add_u64 v[244:245], v[154:155], 0, s[10:11]
	v_mfma_f32_32x32x16_bf16 v[98:113], v[162:165], v[236:239], v[98:113]
	s_add_u32 s10, s10, 0x1000
	s_addc_u32 s11, s11, 0
	v_lshl_add_u64 v[246:247], v[154:155], 0, s[10:11]
	v_mfma_f32_32x32x16_bf16 v[82:97], v[204:207], v[228:231], v[82:97]
	s_add_u32 s10, s10, 0x1000
	s_addc_u32 s11, s11, 0
	v_lshl_add_u64 v[248:249], v[154:155], 0, s[10:11]
	v_mfma_f32_32x32x16_bf16 v[66:81], v[204:207], v[236:239], v[66:81]
	s_add_u32 s10, s10, 0x1000
	s_addc_u32 s11, s11, 0
	v_lshl_add_u64 v[140:141], v[154:155], 0, s[10:11]
	v_mfma_f32_32x32x16_bf16 v[50:65], v[212:215], v[228:231], v[50:65]
	s_lshl_b64 s[10:11], s[14:15], 13
	v_lshl_add_u64 v[142:143], v[156:157], 0, s[10:11]
	v_mfma_f32_32x32x16_bf16 v[34:49], v[212:215], v[236:239], v[34:49]
	s_add_u32 s10, s10, 0x1000
	s_addc_u32 s11, s11, 0
	v_lshl_add_u64 v[144:145], v[156:157], 0, s[10:11]
	v_mfma_f32_32x32x16_bf16 v[18:33], v[220:223], v[228:231], v[18:33]
	v_mfma_f32_32x32x16_bf16 v[2:17], v[220:223], v[236:239], v[2:17]
	s_waitcnt vmcnt(6) lgkmcnt(0)
	s_barrier
	s_add_u32 m0, s13, s72
	v_mfma_f32_32x32x16_bf16 v[114:129], v[166:169], v[232:235], v[114:129]
	global_load_lds_dwordx4 v[244:245], off
	ds_read_b128 v[162:165], v138 offset:0
	ds_read_b128 v[228:231], v139 offset:0
	s_add_u32 m0, m0, 0x1000
	v_mfma_f32_32x32x16_bf16 v[98:113], v[166:169], v[240:243], v[98:113]
	global_load_lds_dwordx4 v[246:247], off
	ds_read_b128 v[236:239], v139 offset:2048
	ds_read_b128 v[204:207], v138 offset:2048
	s_add_u32 m0, m0, 0x1000
	v_mfma_f32_32x32x16_bf16 v[82:97], v[208:211], v[232:235], v[82:97]
	global_load_lds_dwordx4 v[248:249], off
	ds_read_b128 v[212:215], v138 offset:4096
	ds_read_b128 v[220:223], v138 offset:6144
	s_add_u32 m0, m0, 0x1000
	v_mfma_f32_32x32x16_bf16 v[66:81], v[208:211], v[240:243], v[66:81]
	global_load_lds_dwordx4 v[140:141], off
	s_add_u32 m0, m0, 0x1000
	v_mfma_f32_32x32x16_bf16 v[50:65], v[216:219], v[232:235], v[50:65]
	global_load_lds_dwordx4 v[142:143], off
	s_add_u32 m0, m0, 0x1000
	v_mfma_f32_32x32x16_bf16 v[34:49], v[216:219], v[240:243], v[34:49]
	global_load_lds_dwordx4 v[144:145], off
	v_mfma_f32_32x32x16_bf16 v[18:33], v[224:227], v[232:235], v[18:33]
	v_mfma_f32_32x32x16_bf16 v[2:17], v[224:227], v[240:243], v[2:17]
	s_mov_b32 s13, s73
	s_cmp_lg_u32 s7, 29
	s_cbranch_scc1 .Lg357_loop
	v_add_u32_e32 v136, s13, v134
	v_add_u32_e32 v137, s13, v135
	ds_read_b128 v[166:169], v136 offset:0
	ds_read_b128 v[232:235], v137 offset:0
	ds_read_b128 v[240:243], v137 offset:2048
	ds_read_b128 v[208:211], v136 offset:2048
	ds_read_b128 v[216:219], v136 offset:4096
	ds_read_b128 v[224:227], v136 offset:6144
	s_add_i32 s7, s7, 1
	s_add_u32 s73, s13, 0x6000
	s_cmp_lt_u32 s73, 0x12000
	s_cselect_b32 s73, s73, 0
	v_add_u32_e32 v138, s73, v132
	v_add_u32_e32 v139, s73, v133
	s_waitcnt lgkmcnt(6)
	v_mfma_f32_32x32x16_bf16 v[114:129], v[162:165], v[228:231], v[114:129]
	v_mfma_f32_32x32x16_bf16 v[98:113], v[162:165], v[236:239], v[98:113]
	v_mfma_f32_32x32x16_bf16 v[82:97], v[204:207], v[228:231], v[82:97]
	v_mfma_f32_32x32x16_bf16 v[66:81], v[204:207], v[236:239], v[66:81]
	v_mfma_f32_32x32x16_bf16 v[50:65], v[212:215], v[228:231], v[50:65]
	v_mfma_f32_32x32x16_bf16 v[34:49], v[212:215], v[236:239], v[34:49]
	v_mfma_f32_32x32x16_bf16 v[18:33], v[220:223], v[228:231], v[18:33]
	v_mfma_f32_32x32x16_bf16 v[2:17], v[220:223], v[236:239], v[2:17]
	s_waitcnt vmcnt(6) lgkmcnt(0)
	s_barrier
	v_mfma_f32_32x32x16_bf16 v[114:129], v[166:169], v[232:235], v[114:129]
	ds_read_b128 v[162:165], v138 offset:0
	ds_read_b128 v[228:231], v139 offset:0
	v_mfma_f32_32x32x16_bf16 v[98:113], v[166:169], v[240:243], v[98:113]
	ds_read_b128 v[236:239], v139 offset:2048
	ds_read_b128 v[204:207], v138 offset:2048
	v_mfma_f32_32x32x16_bf16 v[82:97], v[208:211], v[232:235], v[82:97]
	ds_read_b128 v[212:215], v138 offset:4096
	ds_read_b128 v[220:223], v138 offset:6144
	v_mfma_f32_32x32x16_bf16 v[66:81], v[208:211], v[240:243], v[66:81]
	v_mfma_f32_32x32x16_bf16 v[50:65], v[216:219], v[232:235], v[50:65]
	v_mfma_f32_32x32x16_bf16 v[34:49], v[216:219], v[240:243], v[34:49]
	v_mfma_f32_32x32x16_bf16 v[18:33], v[224:227], v[232:235], v[18:33]
	v_mfma_f32_32x32x16_bf16 v[2:17], v[224:227], v[240:243], v[2:17]
	s_mov_b32 s13, s73
	v_add_u32_e32 v136, s13, v134
	v_add_u32_e32 v137, s13, v135
	ds_read_b128 v[166:169], v136 offset:0
	ds_read_b128 v[232:235], v137 offset:0
	ds_read_b128 v[240:243], v137 offset:2048
	ds_read_b128 v[208:211], v136 offset:2048
	ds_read_b128 v[216:219], v136 offset:4096
	ds_read_b128 v[224:227], v136 offset:6144
	s_add_i32 s7, s7, 1
	s_add_u32 s73, s13, 0x6000
	s_cmp_lt_u32 s73, 0x12000
	s_cselect_b32 s73, s73, 0
	v_add_u32_e32 v138, s73, v132
	v_add_u32_e32 v139, s73, v133
	s_waitcnt lgkmcnt(6)
	v_mfma_f32_32x32x16_bf16 v[114:129], v[162:165], v[228:231], v[114:129]
	v_mfma_f32_32x32x16_bf16 v[98:113], v[162:165], v[236:239], v[98:113]
	v_mfma_f32_32x32x16_bf16 v[82:97], v[204:207], v[228:231], v[82:97]
	v_mfma_f32_32x32x16_bf16 v[66:81], v[204:207], v[236:239], v[66:81]
	v_mfma_f32_32x32x16_bf16 v[50:65], v[212:215], v[228:231], v[50:65]
	v_mfma_f32_32x32x16_bf16 v[34:49], v[212:215], v[236:239], v[34:49]
	v_mfma_f32_32x32x16_bf16 v[18:33], v[220:223], v[228:231], v[18:33]
	v_mfma_f32_32x32x16_bf16 v[2:17], v[220:223], v[236:239], v[2:17]
	s_waitcnt vmcnt(0) lgkmcnt(0)
	s_barrier
	v_mfma_f32_32x32x16_bf16 v[114:129], v[166:169], v[232:235], v[114:129]
	ds_read_b128 v[162:165], v138 offset:0
	ds_read_b128 v[228:231], v139 offset:0
	v_mfma_f32_32x32x16_bf16 v[98:113], v[166:169], v[240:243], v[98:113]
	ds_read_b128 v[236:239], v139 offset:2048
	ds_read_b128 v[204:207], v138 offset:2048
	v_mfma_f32_32x32x16_bf16 v[82:97], v[208:211], v[232:235], v[82:97]
	ds_read_b128 v[212:215], v138 offset:4096
	ds_read_b128 v[220:223], v138 offset:6144
	v_mfma_f32_32x32x16_bf16 v[66:81], v[208:211], v[240:243], v[66:81]
	v_mfma_f32_32x32x16_bf16 v[50:65], v[216:219], v[232:235], v[50:65]
	v_mfma_f32_32x32x16_bf16 v[34:49], v[216:219], v[240:243], v[34:49]
	v_mfma_f32_32x32x16_bf16 v[18:33], v[224:227], v[232:235], v[18:33]
	v_mfma_f32_32x32x16_bf16 v[2:17], v[224:227], v[240:243], v[2:17]
	s_mov_b32 s13, s73
	v_add_u32_e32 v136, s13, v134
	v_add_u32_e32 v137, s13, v135
	ds_read_b128 v[166:169], v136 offset:0
	ds_read_b128 v[232:235], v137 offset:0
	ds_read_b128 v[240:243], v137 offset:2048
	ds_read_b128 v[208:211], v136 offset:2048
	ds_read_b128 v[216:219], v136 offset:4096
	ds_read_b128 v[224:227], v136 offset:6144
	s_add_i32 s7, s7, 1
	s_waitcnt lgkmcnt(6)
	v_mfma_f32_32x32x16_bf16 v[114:129], v[162:165], v[228:231], v[114:129]
	v_mfma_f32_32x32x16_bf16 v[98:113], v[162:165], v[236:239], v[98:113]
	v_mfma_f32_32x32x16_bf16 v[82:97], v[204:207], v[228:231], v[82:97]
	v_mfma_f32_32x32x16_bf16 v[66:81], v[204:207], v[236:239], v[66:81]
	v_mfma_f32_32x32x16_bf16 v[50:65], v[212:215], v[228:231], v[50:65]
	v_mfma_f32_32x32x16_bf16 v[34:49], v[212:215], v[236:239], v[34:49]
	v_mfma_f32_32x32x16_bf16 v[18:33], v[220:223], v[228:231], v[18:33]
	v_mfma_f32_32x32x16_bf16 v[2:17], v[220:223], v[236:239], v[2:17]
	s_waitcnt lgkmcnt(0)
	v_mfma_f32_32x32x16_bf16 v[114:129], v[166:169], v[232:235], v[114:129]
	v_mfma_f32_32x32x16_bf16 v[98:113], v[166:169], v[240:243], v[98:113]
	v_mfma_f32_32x32x16_bf16 v[82:97], v[208:211], v[232:235], v[82:97]
	v_mfma_f32_32x32x16_bf16 v[66:81], v[208:211], v[240:243], v[66:81]
	v_mfma_f32_32x32x16_bf16 v[50:65], v[216:219], v[232:235], v[50:65]
	v_mfma_f32_32x32x16_bf16 v[34:49], v[216:219], v[240:243], v[34:49]
	v_mfma_f32_32x32x16_bf16 v[18:33], v[224:227], v[232:235], v[18:33]
	v_mfma_f32_32x32x16_bf16 v[2:17], v[224:227], v[240:243], v[2:17]
	s_mov_b32 s14, 31
	s_lshl_b64 s[10:11], s[14:15], 13
	s_movk_i32 s13, 0x7800
	s_movk_i32 s72, 0x6000
	s_mov_b32 s73, 0xc000
	v_mov_b32_e32 v0, v171
	s_barrier
	s_waitcnt vmcnt(4)
	v_lshrrev_b32_e32 v130, 1, v0
	v_and_b32_e32 v130, 0xfffffc0, v130
	v_lshrrev_b32_e32 v131, 3, v0
	v_and_or_b32 v130, v131, 4, v130
	v_and_b32_e32 v0, 0x5f, v0
	v_mul_lo_u32 v130, v130, s53
	v_lshl_add_u32 v0, v0, 2, v130
	s_barrier
	ds_write2_b32 v0, v114, v98 offset1:32
	ds_write2_b32 v0, v115, v99 offset0:132 offset1:164
	v_add_u32_e32 v98, 0x400, v0
	ds_write2_b32 v98, v116, v100 offset0:8 offset1:40
	ds_write2_b32 v98, v117, v101 offset0:140 offset1:172
	v_add_u32_e32 v98, 0x1000, v0
	ds_write2_b32 v98, v118, v102 offset0:32 offset1:64
	ds_write2_b32 v98, v119, v103 offset0:164 offset1:196
	v_add_u32_e32 v98, 0x1400, v0
	ds_write2_b32 v98, v120, v104 offset0:40 offset1:72
	ds_write2_b32 v98, v121, v105 offset0:172 offset1:204
	v_add_u32_e32 v98, 0x2000, v0
	ds_write2_b32 v98, v122, v106 offset0:64 offset1:96
	ds_write2_b32 v98, v123, v107 offset0:196 offset1:228
	v_add_u32_e32 v98, 0x2400, v0
	ds_write2_b32 v98, v124, v108 offset0:72 offset1:104
	ds_write2_b32 v98, v125, v109 offset0:204 offset1:236
	v_add_u32_e32 v98, 0x3000, v0
	ds_write2_b32 v98, v126, v110 offset0:96 offset1:128
	v_add_u32_e32 v98, 0x3200, v0
	ds_write2_b32 v98, v127, v111 offset0:100 offset1:132
	v_add_u32_e32 v98, 0x3400, v0
	ds_write2_b32 v98, v128, v112 offset0:104 offset1:136
	v_add_u32_e32 v98, 0x3600, v0
	ds_write2_b32 v98, v129, v113 offset0:108 offset1:140
	v_add_u32_e32 v98, 0x4000, v0
	ds_write2_b32 v98, v82, v66 offset0:128 offset1:160
	v_add_u32_e32 v66, 0x4400, v0
	ds_write2_b32 v66, v83, v67 offset0:4 offset1:36
	ds_write2_b32 v66, v84, v68 offset0:136 offset1:168
	v_add_u32_e32 v66, 0x4800, v0
	ds_write2_b32 v66, v85, v69 offset0:12 offset1:44
	v_add_u32_e32 v66, 0x5000, v0
	s_lshl_b32 s13, s9, 8
	ds_write2_b32 v66, v86, v70 offset0:160 offset1:192
	v_add_u32_e32 v66, 0x5400, v0
	s_lshl_b32 s34, s6, 7
	ds_write2_b32 v66, v87, v71 offset0:36 offset1:68
	ds_write2_b32 v66, v88, v72 offset0:168 offset1:200
	v_add_u32_e32 v66, 0x5800, v0
	s_add_i32 s6, s13, 0xffffe000
	ds_write2_b32 v66, v89, v73 offset0:44 offset1:76
	v_add_u32_e32 v66, 0x6000, v0
	s_lshr_b32 s6, s6, 12
	ds_write2_b32 v66, v90, v74 offset0:192 offset1:224
	v_add_u32_e32 v66, 0x6400, v0
	s_mulk_i32 s6, 0x1800
	ds_write2_b32 v66, v91, v75 offset0:68 offset1:100
	ds_write2_b32 v66, v92, v76 offset0:200 offset1:232
	v_add_u32_e32 v66, 0x6800, v0
	s_addk_i32 s6, 0x1800
	ds_write2_b32 v66, v93, v77 offset0:76 offset1:108
	v_add_u32_e32 v66, 0x7200, v0
	s_cmp_gt_u32 s8, 31
	ds_write2_b32 v66, v94, v78 offset0:96 offset1:128
	v_add_u32_e32 v66, 0x7400, v0
	s_cselect_b32 s14, s6, 0
	ds_write2_b32 v66, v95, v79 offset0:100 offset1:132
	v_add_u32_e32 v66, 0x7600, v0
	v_add_u32_e32 v0, 0x7800, v0
	v_mov_b32_e32 v76, v171
	s_lshl_b64 s[6:7], s[14:15], 2
	ds_write2_b32 v66, v96, v80 offset0:104 offset1:136
	ds_write2_b32 v0, v97, v81 offset0:108 offset1:140
	s_waitcnt lgkmcnt(0)
	s_barrier
	s_add_u32 s6, s61, s6
	v_lshlrev_b32_e32 v0, 3, v76
	v_and_b32_e32 v0, 0x78, v0
	s_addc_u32 s7, s79, s7
	v_or_b32_e32 v0, s34, v0
	s_add_u32 s8, s6, 0x1d642000
	s_addc_u32 s9, s7, 0
	v_lshlrev_b64 v[74:75], 2, v[0:1]
	v_lshl_add_u64 v[70:71], s[8:9], 0, v[74:75]
	global_load_dwordx4 v[66:69], v[70:71], off offset:16
	s_nop 0
	global_load_dwordx4 v[70:73], v[70:71], off
	v_ashrrev_i32_e32 v90, 4, v76
	v_lshl_add_u64 v[82:83], s[56:57], 0, v[74:75]
	v_mul_lo_u32 v74, v90, s53
	v_and_b32_e32 v75, 15, v76
	s_mov_b32 s14, 0
	v_lshl_add_u32 v91, v75, 5, v74
	v_lshlrev_b32_e32 v92, 1, v90
	s_branch .LBB0_360

.Lscan_main:
	v_lshlrev_b32_e32 v16, 3, v183
	s_add_u32 s12, s92, s4
	s_addc_u32 s13, s93, s5
	v_add_u32_e32 v16, v178, v16
	global_load_dword v17, v16, s[12:13] offset:2560
	v_lshl_add_u64 v[10:11], s[92:93], 0, v[4:5]
	s_mov_b32 s10, 0x8000
	s_mov_b32 s11, 0
	v_add_co_u32_e32 v18, vcc, s77, v10
	s_nop 1
	v_addc_co_u32_e32 v19, vcc, 0, v11, vcc
	v_mov_b32_e32 v148, v18
	v_mov_b32_e32 v149, v19
	global_load_dwordx4 v[20:23], v[18:19], off offset:2560
	v_lshl_add_u64 v[18:19], v[18:19], 0, s[10:11]
	global_load_dwordx4 v[24:27], v[18:19], off offset:2560
	v_lshl_add_u64 v[18:19], v[18:19], 0, s[10:11]
	global_load_dwordx4 v[28:31], v[18:19], off offset:2560
	v_lshl_add_u64 v[18:19], v[18:19], 0, s[10:11]
	global_load_dwordx4 v[32:35], v[18:19], off offset:2560
	v_lshl_add_u64 v[18:19], v[18:19], 0, s[10:11]
	global_load_dwordx4 v[36:39], v[18:19], off offset:2560
	v_lshl_add_u64 v[18:19], v[18:19], 0, s[10:11]
	global_load_dwordx4 v[40:43], v[18:19], off offset:2560
	v_lshl_add_u64 v[18:19], v[18:19], 0, s[10:11]
	global_load_dwordx4 v[44:47], v[18:19], off offset:2560
	v_lshl_add_u64 v[18:19], v[18:19], 0, s[10:11]
	global_load_dwordx4 v[48:51], v[18:19], off offset:2560
	v_lshl_add_u64 v[18:19], v[18:19], 0, s[10:11]
	global_load_dwordx4 v[52:55], v[18:19], off offset:2560
	v_lshl_add_u64 v[18:19], v[18:19], 0, s[10:11]
	global_load_dwordx4 v[56:59], v[18:19], off offset:2560
	v_lshl_add_u64 v[18:19], v[18:19], 0, s[10:11]
	global_load_dwordx4 v[60:63], v[18:19], off offset:2560
	v_lshl_add_u64 v[18:19], v[18:19], 0, s[10:11]
	global_load_dwordx4 v[64:67], v[18:19], off offset:2560
	v_lshl_add_u64 v[18:19], v[18:19], 0, s[10:11]
	global_load_dwordx4 v[68:71], v[18:19], off offset:2560
	v_lshl_add_u64 v[18:19], v[18:19], 0, s[10:11]
	global_load_dwordx4 v[72:75], v[18:19], off offset:2560
	v_lshl_add_u64 v[18:19], v[18:19], 0, s[10:11]
	global_load_dwordx4 v[76:79], v[18:19], off offset:2560
	v_lshl_add_u64 v[18:19], v[18:19], 0, s[10:11]
	global_load_dwordx4 v[80:83], v[18:19], off offset:2560
	v_lshl_add_u64 v[18:19], v[18:19], 0, s[10:11]
	global_load_dwordx4 v[84:87], v[18:19], off offset:2560
	v_lshl_add_u64 v[18:19], v[18:19], 0, s[10:11]
	global_load_dwordx4 v[88:91], v[18:19], off offset:2560
	v_lshl_add_u64 v[18:19], v[18:19], 0, s[10:11]
	global_load_dwordx4 v[92:95], v[18:19], off offset:2560
	v_lshl_add_u64 v[18:19], v[18:19], 0, s[10:11]
	global_load_dwordx4 v[96:99], v[18:19], off offset:2560
	v_lshl_add_u64 v[18:19], v[18:19], 0, s[10:11]
	global_load_dwordx4 v[100:103], v[18:19], off offset:2560
	v_lshl_add_u64 v[18:19], v[18:19], 0, s[10:11]
	global_load_dwordx4 v[104:107], v[18:19], off offset:2560
	v_lshl_add_u64 v[18:19], v[18:19], 0, s[10:11]
	global_load_dwordx4 v[108:111], v[18:19], off offset:2560
	v_lshl_add_u64 v[18:19], v[18:19], 0, s[10:11]
	global_load_dwordx4 v[112:115], v[18:19], off offset:2560
	v_lshl_add_u64 v[18:19], v[18:19], 0, s[10:11]
	global_load_dwordx4 v[116:119], v[18:19], off offset:2560
	v_lshl_add_u64 v[18:19], v[18:19], 0, s[10:11]
	global_load_dwordx4 v[120:123], v[18:19], off offset:2560
	v_lshl_add_u64 v[18:19], v[18:19], 0, s[10:11]
	global_load_dwordx4 v[124:127], v[18:19], off offset:2560
	v_lshl_add_u64 v[18:19], v[18:19], 0, s[10:11]
	global_load_dwordx4 v[128:131], v[18:19], off offset:2560
	v_lshl_add_u64 v[18:19], v[18:19], 0, s[10:11]
	global_load_dwordx4 v[132:135], v[18:19], off offset:2560
	v_lshl_add_u64 v[18:19], v[18:19], 0, s[10:11]
	global_load_dwordx4 v[136:139], v[18:19], off offset:2560
	v_lshl_add_u64 v[18:19], v[18:19], 0, s[10:11]
	global_load_dwordx4 v[140:143], v[18:19], off offset:2560
	v_lshl_add_u64 v[18:19], v[18:19], 0, s[10:11]
	global_load_dwordx4 v[144:147], v[18:19], off offset:2560
	v_lshl_add_u64 v[18:19], v[18:19], 0, s[10:11]
	s_waitcnt vmcnt(16)
	v_readlane_b32 s0, v17, 0
	v_readlane_b32 s12, v17, 1
	v_readlane_b32 s13, v17, 2
	v_readlane_b32 s35, v17, 3
	v_cvt_pk_bf16_f32 v150, v6, v7
	v_cvt_pk_bf16_f32 v151, v8, v9
	v_cvt_pk_bf16_f32 v152, v12, v13
	v_cvt_pk_bf16_f32 v153, v14, v15
	v_lshlrev_b32_e32 v154, 16, v20
	v_and_b32_e32 v155, 0xffff0000, v20
	v_lshlrev_b32_e32 v156, 16, v21
	v_and_b32_e32 v157, 0xffff0000, v21
	v_lshlrev_b32_e32 v158, 16, v22
	v_and_b32_e32 v159, 0xffff0000, v22
	v_lshlrev_b32_e32 v160, 16, v23
	v_and_b32_e32 v161, 0xffff0000, v23
	global_store_dwordx4 v[148:149], v[150:153], off offset:2560
	v_lshl_add_u64 v[148:149], v[148:149], 0, s[10:11]
	v_fma_f32 v6, v6, s0, v154
	v_fma_f32 v7, v7, s0, v155
	v_fma_f32 v8, v8, s0, v156
	v_fma_f32 v9, v9, s0, v157
	v_fma_f32 v12, v12, s0, v158
	v_fma_f32 v13, v13, s0, v159
	v_fma_f32 v14, v14, s0, v160
	v_fma_f32 v15, v15, s0, v161
	v_cvt_pk_bf16_f32 v150, v6, v7
	v_cvt_pk_bf16_f32 v151, v8, v9
	v_cvt_pk_bf16_f32 v152, v12, v13
	v_cvt_pk_bf16_f32 v153, v14, v15
	v_lshlrev_b32_e32 v154, 16, v24
	v_and_b32_e32 v155, 0xffff0000, v24
	v_lshlrev_b32_e32 v156, 16, v25
	v_and_b32_e32 v157, 0xffff0000, v25
	v_lshlrev_b32_e32 v158, 16, v26
	v_and_b32_e32 v159, 0xffff0000, v26
	v_lshlrev_b32_e32 v160, 16, v27
	v_and_b32_e32 v161, 0xffff0000, v27
	global_store_dwordx4 v[148:149], v[150:153], off offset:2560
	v_lshl_add_u64 v[148:149], v[148:149], 0, s[10:11]
	v_fma_f32 v6, v6, s12, v154
	v_fma_f32 v7, v7, s12, v155
	v_fma_f32 v8, v8, s12, v156
	v_fma_f32 v9, v9, s12, v157
	v_fma_f32 v12, v12, s12, v158
	v_fma_f32 v13, v13, s12, v159
	v_fma_f32 v14, v14, s12, v160
	v_fma_f32 v15, v15, s12, v161
	v_cvt_pk_bf16_f32 v150, v6, v7
	v_cvt_pk_bf16_f32 v151, v8, v9
	v_cvt_pk_bf16_f32 v152, v12, v13
	v_cvt_pk_bf16_f32 v153, v14, v15
	v_lshlrev_b32_e32 v154, 16, v28
	v_and_b32_e32 v155, 0xffff0000, v28
	v_lshlrev_b32_e32 v156, 16, v29
	v_and_b32_e32 v157, 0xffff0000, v29
	v_lshlrev_b32_e32 v158, 16, v30
	v_and_b32_e32 v159, 0xffff0000, v30
	v_lshlrev_b32_e32 v160, 16, v31
	v_and_b32_e32 v161, 0xffff0000, v31
	global_store_dwordx4 v[148:149], v[150:153], off offset:2560
	v_lshl_add_u64 v[148:149], v[148:149], 0, s[10:11]
	v_fma_f32 v6, v6, s13, v154
	v_fma_f32 v7, v7, s13, v155
	v_fma_f32 v8, v8, s13, v156
	v_fma_f32 v9, v9, s13, v157
	v_fma_f32 v12, v12, s13, v158
	v_fma_f32 v13, v13, s13, v159
	v_fma_f32 v14, v14, s13, v160
	v_fma_f32 v15, v15, s13, v161
	v_cvt_pk_bf16_f32 v150, v6, v7
	v_cvt_pk_bf16_f32 v151, v8, v9
	v_cvt_pk_bf16_f32 v152, v12, v13
	v_cvt_pk_bf16_f32 v153, v14, v15
	v_lshlrev_b32_e32 v154, 16, v32
	v_and_b32_e32 v155, 0xffff0000, v32
	v_lshlrev_b32_e32 v156, 16, v33
	v_and_b32_e32 v157, 0xffff0000, v33
	v_lshlrev_b32_e32 v158, 16, v34
	v_and_b32_e32 v159, 0xffff0000, v34
	v_lshlrev_b32_e32 v160, 16, v35
	v_and_b32_e32 v161, 0xffff0000, v35
	global_store_dwordx4 v[148:149], v[150:153], off offset:2560
	v_lshl_add_u64 v[148:149], v[148:149], 0, s[10:11]
	v_fma_f32 v6, v6, s35, v154
	v_fma_f32 v7, v7, s35, v155
	v_fma_f32 v8, v8, s35, v156
	v_fma_f32 v9, v9, s35, v157
	v_fma_f32 v12, v12, s35, v158
	v_fma_f32 v13, v13, s35, v159
	v_fma_f32 v14, v14, s35, v160
	v_fma_f32 v15, v15, s35, v161
	v_readlane_b32 s0, v17, 4
	v_readlane_b32 s12, v17, 5
	v_readlane_b32 s13, v17, 6
	v_readlane_b32 s35, v17, 7
	v_cvt_pk_bf16_f32 v150, v6, v7
	v_cvt_pk_bf16_f32 v151, v8, v9
	v_cvt_pk_bf16_f32 v152, v12, v13
	v_cvt_pk_bf16_f32 v153, v14, v15
	v_lshlrev_b32_e32 v154, 16, v36
	v_and_b32_e32 v155, 0xffff0000, v36
	v_lshlrev_b32_e32 v156, 16, v37
	v_and_b32_e32 v157, 0xffff0000, v37
	v_lshlrev_b32_e32 v158, 16, v38
	v_and_b32_e32 v159, 0xffff0000, v38
	v_lshlrev_b32_e32 v160, 16, v39
	v_and_b32_e32 v161, 0xffff0000, v39
	global_store_dwordx4 v[148:149], v[150:153], off offset:2560
	v_lshl_add_u64 v[148:149], v[148:149], 0, s[10:11]
	v_fma_f32 v6, v6, s0, v154
	v_fma_f32 v7, v7, s0, v155
	v_fma_f32 v8, v8, s0, v156
	v_fma_f32 v9, v9, s0, v157
	v_fma_f32 v12, v12, s0, v158
	v_fma_f32 v13, v13, s0, v159
	v_fma_f32 v14, v14, s0, v160
	v_fma_f32 v15, v15, s0, v161
	v_cvt_pk_bf16_f32 v150, v6, v7
	v_cvt_pk_bf16_f32 v151, v8, v9
	v_cvt_pk_bf16_f32 v152, v12, v13
	v_cvt_pk_bf16_f32 v153, v14, v15
	v_lshlrev_b32_e32 v154, 16, v40
	v_and_b32_e32 v155, 0xffff0000, v40
	v_lshlrev_b32_e32 v156, 16, v41
	v_and_b32_e32 v157, 0xffff0000, v41
	v_lshlrev_b32_e32 v158, 16, v42
	v_and_b32_e32 v159, 0xffff0000, v42
	v_lshlrev_b32_e32 v160, 16, v43
	v_and_b32_e32 v161, 0xffff0000, v43
	global_store_dwordx4 v[148:149], v[150:153], off offset:2560
	v_lshl_add_u64 v[148:149], v[148:149], 0, s[10:11]
	v_fma_f32 v6, v6, s12, v154
	v_fma_f32 v7, v7, s12, v155
	v_fma_f32 v8, v8, s12, v156
	v_fma_f32 v9, v9, s12, v157
	v_fma_f32 v12, v12, s12, v158
	v_fma_f32 v13, v13, s12, v159
	v_fma_f32 v14, v14, s12, v160
	v_fma_f32 v15, v15, s12, v161
	v_cvt_pk_bf16_f32 v150, v6, v7
	v_cvt_pk_bf16_f32 v151, v8, v9
	v_cvt_pk_bf16_f32 v152, v12, v13
	v_cvt_pk_bf16_f32 v153, v14, v15
	v_lshlrev_b32_e32 v154, 16, v44
	v_and_b32_e32 v155, 0xffff0000, v44
	v_lshlrev_b32_e32 v156, 16, v45
	v_and_b32_e32 v157, 0xffff0000, v45
	v_lshlrev_b32_e32 v158, 16, v46
	v_and_b32_e32 v159, 0xffff0000, v46
	v_lshlrev_b32_e32 v160, 16, v47
	v_and_b32_e32 v161, 0xffff0000, v47
	global_store_dwordx4 v[148:149], v[150:153], off offset:2560
	v_lshl_add_u64 v[148:149], v[148:149], 0, s[10:11]
	v_fma_f32 v6, v6, s13, v154
	v_fma_f32 v7, v7, s13, v155
	v_fma_f32 v8, v8, s13, v156
	v_fma_f32 v9, v9, s13, v157
	v_fma_f32 v12, v12, s13, v158
	v_fma_f32 v13, v13, s13, v159
	v_fma_f32 v14, v14, s13, v160
	v_fma_f32 v15, v15, s13, v161
	v_cvt_pk_bf16_f32 v150, v6, v7
	v_cvt_pk_bf16_f32 v151, v8, v9
	v_cvt_pk_bf16_f32 v152, v12, v13
	v_cvt_pk_bf16_f32 v153, v14, v15
	v_lshlrev_b32_e32 v154, 16, v48
	v_and_b32_e32 v155, 0xffff0000, v48
	v_lshlrev_b32_e32 v156, 16, v49
	v_and_b32_e32 v157, 0xffff0000, v49
	v_lshlrev_b32_e32 v158, 16, v50
	v_and_b32_e32 v159, 0xffff0000, v50
	v_lshlrev_b32_e32 v160, 16, v51
	v_and_b32_e32 v161, 0xffff0000, v51
	global_store_dwordx4 v[148:149], v[150:153], off offset:2560
	v_lshl_add_u64 v[148:149], v[148:149], 0, s[10:11]
	v_fma_f32 v6, v6, s35, v154
	v_fma_f32 v7, v7, s35, v155
	v_fma_f32 v8, v8, s35, v156
	v_fma_f32 v9, v9, s35, v157
	v_fma_f32 v12, v12, s35, v158
	v_fma_f32 v13, v13, s35, v159
	v_fma_f32 v14, v14, s35, v160
	v_fma_f32 v15, v15, s35, v161
	v_readlane_b32 s0, v17, 8
	v_readlane_b32 s12, v17, 9
	v_readlane_b32 s13, v17, 10
	v_readlane_b32 s35, v17, 11
	v_cvt_pk_bf16_f32 v150, v6, v7
	v_cvt_pk_bf16_f32 v151, v8, v9
	v_cvt_pk_bf16_f32 v152, v12, v13
	v_cvt_pk_bf16_f32 v153, v14, v15
	v_lshlrev_b32_e32 v154, 16, v52
	v_and_b32_e32 v155, 0xffff0000, v52
	v_lshlrev_b32_e32 v156, 16, v53
	v_and_b32_e32 v157, 0xffff0000, v53
	v_lshlrev_b32_e32 v158, 16, v54
	v_and_b32_e32 v159, 0xffff0000, v54
	v_lshlrev_b32_e32 v160, 16, v55
	v_and_b32_e32 v161, 0xffff0000, v55
	global_store_dwordx4 v[148:149], v[150:153], off offset:2560
	v_lshl_add_u64 v[148:149], v[148:149], 0, s[10:11]
	v_fma_f32 v6, v6, s0, v154
	v_fma_f32 v7, v7, s0, v155
	v_fma_f32 v8, v8, s0, v156
	v_fma_f32 v9, v9, s0, v157
	v_fma_f32 v12, v12, s0, v158
	v_fma_f32 v13, v13, s0, v159
	v_fma_f32 v14, v14, s0, v160
	v_fma_f32 v15, v15, s0, v161
	v_cvt_pk_bf16_f32 v150, v6, v7
	v_cvt_pk_bf16_f32 v151, v8, v9
	v_cvt_pk_bf16_f32 v152, v12, v13
	v_cvt_pk_bf16_f32 v153, v14, v15
	v_lshlrev_b32_e32 v154, 16, v56
	v_and_b32_e32 v155, 0xffff0000, v56
	v_lshlrev_b32_e32 v156, 16, v57
	v_and_b32_e32 v157, 0xffff0000, v57
	v_lshlrev_b32_e32 v158, 16, v58
	v_and_b32_e32 v159, 0xffff0000, v58
	v_lshlrev_b32_e32 v160, 16, v59
	v_and_b32_e32 v161, 0xffff0000, v59
	global_store_dwordx4 v[148:149], v[150:153], off offset:2560
	v_lshl_add_u64 v[148:149], v[148:149], 0, s[10:11]
	v_fma_f32 v6, v6, s12, v154
	v_fma_f32 v7, v7, s12, v155
	v_fma_f32 v8, v8, s12, v156
	v_fma_f32 v9, v9, s12, v157
	v_fma_f32 v12, v12, s12, v158
	v_fma_f32 v13, v13, s12, v159
	v_fma_f32 v14, v14, s12, v160
	v_fma_f32 v15, v15, s12, v161
	v_cvt_pk_bf16_f32 v150, v6, v7
	v_cvt_pk_bf16_f32 v151, v8, v9
	v_cvt_pk_bf16_f32 v152, v12, v13
	v_cvt_pk_bf16_f32 v153, v14, v15
	v_lshlrev_b32_e32 v154, 16, v60
	v_and_b32_e32 v155, 0xffff0000, v60
	v_lshlrev_b32_e32 v156, 16, v61
	v_and_b32_e32 v157, 0xffff0000, v61
	v_lshlrev_b32_e32 v158, 16, v62
	v_and_b32_e32 v159, 0xffff0000, v62
	v_lshlrev_b32_e32 v160, 16, v63
	v_and_b32_e32 v161, 0xffff0000, v63
	global_store_dwordx4 v[148:149], v[150:153], off offset:2560
	v_lshl_add_u64 v[148:149], v[148:149], 0, s[10:11]
	v_fma_f32 v6, v6, s13, v154
	v_fma_f32 v7, v7, s13, v155
	v_fma_f32 v8, v8, s13, v156
	v_fma_f32 v9, v9, s13, v157
	v_fma_f32 v12, v12, s13, v158
	v_fma_f32 v13, v13, s13, v159
	v_fma_f32 v14, v14, s13, v160
	v_fma_f32 v15, v15, s13, v161
	v_cvt_pk_bf16_f32 v150, v6, v7
	v_cvt_pk_bf16_f32 v151, v8, v9
	v_cvt_pk_bf16_f32 v152, v12, v13
	v_cvt_pk_bf16_f32 v153, v14, v15
	v_lshlrev_b32_e32 v154, 16, v64
	v_and_b32_e32 v155, 0xffff0000, v64
	v_lshlrev_b32_e32 v156, 16, v65
	v_and_b32_e32 v157, 0xffff0000, v65
	v_lshlrev_b32_e32 v158, 16, v66
	v_and_b32_e32 v159, 0xffff0000, v66
	v_lshlrev_b32_e32 v160, 16, v67
	v_and_b32_e32 v161, 0xffff0000, v67
	global_store_dwordx4 v[148:149], v[150:153], off offset:2560
	v_lshl_add_u64 v[148:149], v[148:149], 0, s[10:11]
	v_fma_f32 v6, v6, s35, v154
	v_fma_f32 v7, v7, s35, v155
	v_fma_f32 v8, v8, s35, v156
	v_fma_f32 v9, v9, s35, v157
	v_fma_f32 v12, v12, s35, v158
	v_fma_f32 v13, v13, s35, v159
	v_fma_f32 v14, v14, s35, v160
	v_fma_f32 v15, v15, s35, v161
	v_readlane_b32 s0, v17, 12
	v_readlane_b32 s12, v17, 13
	v_readlane_b32 s13, v17, 14
	v_readlane_b32 s35, v17, 15
	v_cvt_pk_bf16_f32 v150, v6, v7
	v_cvt_pk_bf16_f32 v151, v8, v9
	v_cvt_pk_bf16_f32 v152, v12, v13
	v_cvt_pk_bf16_f32 v153, v14, v15
	v_lshlrev_b32_e32 v154, 16, v68
	v_and_b32_e32 v155, 0xffff0000, v68
	v_lshlrev_b32_e32 v156, 16, v69
	v_and_b32_e32 v157, 0xffff0000, v69
	v_lshlrev_b32_e32 v158, 16, v70
	v_and_b32_e32 v159, 0xffff0000, v70
	v_lshlrev_b32_e32 v160, 16, v71
	v_and_b32_e32 v161, 0xffff0000, v71
	global_store_dwordx4 v[148:149], v[150:153], off offset:2560
	v_lshl_add_u64 v[148:149], v[148:149], 0, s[10:11]
	v_fma_f32 v6, v6, s0, v154
	v_fma_f32 v7, v7, s0, v155
	v_fma_f32 v8, v8, s0, v156
	v_fma_f32 v9, v9, s0, v157
	v_fma_f32 v12, v12, s0, v158
	v_fma_f32 v13, v13, s0, v159
	v_fma_f32 v14, v14, s0, v160
	v_fma_f32 v15, v15, s0, v161
	v_cvt_pk_bf16_f32 v150, v6, v7
	v_cvt_pk_bf16_f32 v151, v8, v9
	v_cvt_pk_bf16_f32 v152, v12, v13
	v_cvt_pk_bf16_f32 v153, v14, v15
	v_lshlrev_b32_e32 v154, 16, v72
	v_and_b32_e32 v155, 0xffff0000, v72
	v_lshlrev_b32_e32 v156, 16, v73
	v_and_b32_e32 v157, 0xffff0000, v73
	v_lshlrev_b32_e32 v158, 16, v74
	v_and_b32_e32 v159, 0xffff0000, v74
	v_lshlrev_b32_e32 v160, 16, v75
	v_and_b32_e32 v161, 0xffff0000, v75
	global_store_dwordx4 v[148:149], v[150:153], off offset:2560
	v_lshl_add_u64 v[148:149], v[148:149], 0, s[10:11]
	v_fma_f32 v6, v6, s12, v154
	v_fma_f32 v7, v7, s12, v155
	v_fma_f32 v8, v8, s12, v156
	v_fma_f32 v9, v9, s12, v157
	v_fma_f32 v12, v12, s12, v158
	v_fma_f32 v13, v13, s12, v159
	v_fma_f32 v14, v14, s12, v160
	v_fma_f32 v15, v15, s12, v161
	v_cvt_pk_bf16_f32 v150, v6, v7
	v_cvt_pk_bf16_f32 v151, v8, v9
	v_cvt_pk_bf16_f32 v152, v12, v13
	v_cvt_pk_bf16_f32 v153, v14, v15
	v_lshlrev_b32_e32 v154, 16, v76
	v_and_b32_e32 v155, 0xffff0000, v76
	v_lshlrev_b32_e32 v156, 16, v77
	v_and_b32_e32 v157, 0xffff0000, v77
	v_lshlrev_b32_e32 v158, 16, v78
	v_and_b32_e32 v159, 0xffff0000, v78
	v_lshlrev_b32_e32 v160, 16, v79
	v_and_b32_e32 v161, 0xffff0000, v79
	global_store_dwordx4 v[148:149], v[150:153], off offset:2560
	v_lshl_add_u64 v[148:149], v[148:149], 0, s[10:11]
	v_fma_f32 v6, v6, s13, v154
	v_fma_f32 v7, v7, s13, v155
	v_fma_f32 v8, v8, s13, v156
	v_fma_f32 v9, v9, s13, v157
	v_fma_f32 v12, v12, s13, v158
	v_fma_f32 v13, v13, s13, v159
	v_fma_f32 v14, v14, s13, v160
	v_fma_f32 v15, v15, s13, v161
	v_cvt_pk_bf16_f32 v150, v6, v7
	v_cvt_pk_bf16_f32 v151, v8, v9
	v_cvt_pk_bf16_f32 v152, v12, v13
	v_cvt_pk_bf16_f32 v153, v14, v15
	v_lshlrev_b32_e32 v154, 16, v80
	v_and_b32_e32 v155, 0xffff0000, v80
	v_lshlrev_b32_e32 v156, 16, v81
	v_and_b32_e32 v157, 0xffff0000, v81
	v_lshlrev_b32_e32 v158, 16, v82
	v_and_b32_e32 v159, 0xffff0000, v82
	v_lshlrev_b32_e32 v160, 16, v83
	v_and_b32_e32 v161, 0xffff0000, v83
	global_store_dwordx4 v[148:149], v[150:153], off offset:2560
	v_lshl_add_u64 v[148:149], v[148:149], 0, s[10:11]
	v_fma_f32 v6, v6, s35, v154
	v_fma_f32 v7, v7, s35, v155
	v_fma_f32 v8, v8, s35, v156
	v_fma_f32 v9, v9, s35, v157
	v_fma_f32 v12, v12, s35, v158
	v_fma_f32 v13, v13, s35, v159
	v_fma_f32 v14, v14, s35, v160
	v_fma_f32 v15, v15, s35, v161
	s_waitcnt vmcnt(24)
	global_load_dwordx4 v[20:23], v[18:19], off offset:2560
	v_lshl_add_u64 v[18:19], v[18:19], 0, s[10:11]
	global_load_dwordx4 v[24:27], v[18:19], off offset:2560
	v_lshl_add_u64 v[18:19], v[18:19], 0, s[10:11]
	global_load_dwordx4 v[28:31], v[18:19], off offset:2560
	v_lshl_add_u64 v[18:19], v[18:19], 0, s[10:11]
	global_load_dwordx4 v[32:35], v[18:19], off offset:2560
	v_lshl_add_u64 v[18:19], v[18:19], 0, s[10:11]
	global_load_dwordx4 v[36:39], v[18:19], off offset:2560
	v_lshl_add_u64 v[18:19], v[18:19], 0, s[10:11]
	global_load_dwordx4 v[40:43], v[18:19], off offset:2560
	v_lshl_add_u64 v[18:19], v[18:19], 0, s[10:11]
	global_load_dwordx4 v[44:47], v[18:19], off offset:2560
	v_lshl_add_u64 v[18:19], v[18:19], 0, s[10:11]
	global_load_dwordx4 v[48:51], v[18:19], off offset:2560
	v_lshl_add_u64 v[18:19], v[18:19], 0, s[10:11]
	global_load_dwordx4 v[52:55], v[18:19], off offset:2560
	v_lshl_add_u64 v[18:19], v[18:19], 0, s[10:11]
	global_load_dwordx4 v[56:59], v[18:19], off offset:2560
	v_lshl_add_u64 v[18:19], v[18:19], 0, s[10:11]
	global_load_dwordx4 v[60:63], v[18:19], off offset:2560
	v_lshl_add_u64 v[18:19], v[18:19], 0, s[10:11]
	global_load_dwordx4 v[64:67], v[18:19], off offset:2560
	v_lshl_add_u64 v[18:19], v[18:19], 0, s[10:11]
	global_load_dwordx4 v[68:71], v[18:19], off offset:2560
	v_lshl_add_u64 v[18:19], v[18:19], 0, s[10:11]
	global_load_dwordx4 v[72:75], v[18:19], off offset:2560
	v_lshl_add_u64 v[18:19], v[18:19], 0, s[10:11]
	global_load_dwordx4 v[76:79], v[18:19], off offset:2560
	v_lshl_add_u64 v[18:19], v[18:19], 0, s[10:11]
	global_load_dwordx4 v[80:83], v[18:19], off offset:2560
	v_lshl_add_u64 v[18:19], v[18:19], 0, s[10:11]
	s_waitcnt vmcnt(32)
	v_readlane_b32 s0, v17, 16
	v_readlane_b32 s12, v17, 17
	v_readlane_b32 s13, v17, 18
	v_readlane_b32 s35, v17, 19
	v_cvt_pk_bf16_f32 v150, v6, v7
	v_cvt_pk_bf16_f32 v151, v8, v9
	v_cvt_pk_bf16_f32 v152, v12, v13
	v_cvt_pk_bf16_f32 v153, v14, v15
	v_lshlrev_b32_e32 v154, 16, v84
	v_and_b32_e32 v155, 0xffff0000, v84
	v_lshlrev_b32_e32 v156, 16, v85
	v_and_b32_e32 v157, 0xffff0000, v85
	v_lshlrev_b32_e32 v158, 16, v86
	v_and_b32_e32 v159, 0xffff0000, v86
	v_lshlrev_b32_e32 v160, 16, v87
	v_and_b32_e32 v161, 0xffff0000, v87
	global_store_dwordx4 v[148:149], v[150:153], off offset:2560
	v_lshl_add_u64 v[148:149], v[148:149], 0, s[10:11]
	v_fma_f32 v6, v6, s0, v154
	v_fma_f32 v7, v7, s0, v155
	v_fma_f32 v8, v8, s0, v156
	v_fma_f32 v9, v9, s0, v157
	v_fma_f32 v12, v12, s0, v158
	v_fma_f32 v13, v13, s0, v159
	v_fma_f32 v14, v14, s0, v160
	v_fma_f32 v15, v15, s0, v161
	v_cvt_pk_bf16_f32 v150, v6, v7
	v_cvt_pk_bf16_f32 v151, v8, v9
	v_cvt_pk_bf16_f32 v152, v12, v13
	v_cvt_pk_bf16_f32 v153, v14, v15
	v_lshlrev_b32_e32 v154, 16, v88
	v_and_b32_e32 v155, 0xffff0000, v88
	v_lshlrev_b32_e32 v156, 16, v89
	v_and_b32_e32 v157, 0xffff0000, v89
	v_lshlrev_b32_e32 v158, 16, v90
	v_and_b32_e32 v159, 0xffff0000, v90
	v_lshlrev_b32_e32 v160, 16, v91
	v_and_b32_e32 v161, 0xffff0000, v91
	global_store_dwordx4 v[148:149], v[150:153], off offset:2560
	v_lshl_add_u64 v[148:149], v[148:149], 0, s[10:11]
	v_fma_f32 v6, v6, s12, v154
	v_fma_f32 v7, v7, s12, v155
	v_fma_f32 v8, v8, s12, v156
	v_fma_f32 v9, v9, s12, v157
	v_fma_f32 v12, v12, s12, v158
	v_fma_f32 v13, v13, s12, v159
	v_fma_f32 v14, v14, s12, v160
	v_fma_f32 v15, v15, s12, v161
	v_cvt_pk_bf16_f32 v150, v6, v7
	v_cvt_pk_bf16_f32 v151, v8, v9
	v_cvt_pk_bf16_f32 v152, v12, v13
	v_cvt_pk_bf16_f32 v153, v14, v15
	v_lshlrev_b32_e32 v154, 16, v92
	v_and_b32_e32 v155, 0xffff0000, v92
	v_lshlrev_b32_e32 v156, 16, v93
	v_and_b32_e32 v157, 0xffff0000, v93
	v_lshlrev_b32_e32 v158, 16, v94
	v_and_b32_e32 v159, 0xffff0000, v94
	v_lshlrev_b32_e32 v160, 16, v95
	v_and_b32_e32 v161, 0xffff0000, v95
	global_store_dwordx4 v[148:149], v[150:153], off offset:2560
	v_lshl_add_u64 v[148:149], v[148:149], 0, s[10:11]
	v_fma_f32 v6, v6, s13, v154
	v_fma_f32 v7, v7, s13, v155
	v_fma_f32 v8, v8, s13, v156
	v_fma_f32 v9, v9, s13, v157
	v_fma_f32 v12, v12, s13, v158
	v_fma_f32 v13, v13, s13, v159
	v_fma_f32 v14, v14, s13, v160
	v_fma_f32 v15, v15, s13, v161
	v_cvt_pk_bf16_f32 v150, v6, v7
	v_cvt_pk_bf16_f32 v151, v8, v9
	v_cvt_pk_bf16_f32 v152, v12, v13
	v_cvt_pk_bf16_f32 v153, v14, v15
	v_lshlrev_b32_e32 v154, 16, v96
	v_and_b32_e32 v155, 0xffff0000, v96
	v_lshlrev_b32_e32 v156, 16, v97
	v_and_b32_e32 v157, 0xffff0000, v97
	v_lshlrev_b32_e32 v158, 16, v98
	v_and_b32_e32 v159, 0xffff0000, v98
	v_lshlrev_b32_e32 v160, 16, v99
	v_and_b32_e32 v161, 0xffff0000, v99
	global_store_dwordx4 v[148:149], v[150:153], off offset:2560
	v_lshl_add_u64 v[148:149], v[148:149], 0, s[10:11]
	v_fma_f32 v6, v6, s35, v154
	v_fma_f32 v7, v7, s35, v155
	v_fma_f32 v8, v8, s35, v156
	v_fma_f32 v9, v9, s35, v157
	v_fma_f32 v12, v12, s35, v158
	v_fma_f32 v13, v13, s35, v159
	v_fma_f32 v14, v14, s35, v160
	v_fma_f32 v15, v15, s35, v161
	v_readlane_b32 s0, v17, 20
	v_readlane_b32 s12, v17, 21
	v_readlane_b32 s13, v17, 22
	v_readlane_b32 s35, v17, 23
	v_cvt_pk_bf16_f32 v150, v6, v7
	v_cvt_pk_bf16_f32 v151, v8, v9
	v_cvt_pk_bf16_f32 v152, v12, v13
	v_cvt_pk_bf16_f32 v153, v14, v15
	v_lshlrev_b32_e32 v154, 16, v100
	v_and_b32_e32 v155, 0xffff0000, v100
	v_lshlrev_b32_e32 v156, 16, v101
	v_and_b32_e32 v157, 0xffff0000, v101
	v_lshlrev_b32_e32 v158, 16, v102
	v_and_b32_e32 v159, 0xffff0000, v102
	v_lshlrev_b32_e32 v160, 16, v103
	v_and_b32_e32 v161, 0xffff0000, v103
	global_store_dwordx4 v[148:149], v[150:153], off offset:2560
	v_lshl_add_u64 v[148:149], v[148:149], 0, s[10:11]
	v_fma_f32 v6, v6, s0, v154
	v_fma_f32 v7, v7, s0, v155
	v_fma_f32 v8, v8, s0, v156
	v_fma_f32 v9, v9, s0, v157
	v_fma_f32 v12, v12, s0, v158
	v_fma_f32 v13, v13, s0, v159
	v_fma_f32 v14, v14, s0, v160
	v_fma_f32 v15, v15, s0, v161
	v_cvt_pk_bf16_f32 v150, v6, v7
	v_cvt_pk_bf16_f32 v151, v8, v9
	v_cvt_pk_bf16_f32 v152, v12, v13
	v_cvt_pk_bf16_f32 v153, v14, v15
	v_lshlrev_b32_e32 v154, 16, v104
	v_and_b32_e32 v155, 0xffff0000, v104
	v_lshlrev_b32_e32 v156, 16, v105
	v_and_b32_e32 v157, 0xffff0000, v105
	v_lshlrev_b32_e32 v158, 16, v106
	v_and_b32_e32 v159, 0xffff0000, v106
	v_lshlrev_b32_e32 v160, 16, v107
	v_and_b32_e32 v161, 0xffff0000, v107
	global_store_dwordx4 v[148:149], v[150:153], off offset:2560
	v_lshl_add_u64 v[148:149], v[148:149], 0, s[10:11]
	v_fma_f32 v6, v6, s12, v154
	v_fma_f32 v7, v7, s12, v155
	v_fma_f32 v8, v8, s12, v156
	v_fma_f32 v9, v9, s12, v157
	v_fma_f32 v12, v12, s12, v158
	v_fma_f32 v13, v13, s12, v159
	v_fma_f32 v14, v14, s12, v160
	v_fma_f32 v15, v15, s12, v161
	v_cvt_pk_bf16_f32 v150, v6, v7
	v_cvt_pk_bf16_f32 v151, v8, v9
	v_cvt_pk_bf16_f32 v152, v12, v13
	v_cvt_pk_bf16_f32 v153, v14, v15
	v_lshlrev_b32_e32 v154, 16, v108
	v_and_b32_e32 v155, 0xffff0000, v108
	v_lshlrev_b32_e32 v156, 16, v109
	v_and_b32_e32 v157, 0xffff0000, v109
	v_lshlrev_b32_e32 v158, 16, v110
	v_and_b32_e32 v159, 0xffff0000, v110
	v_lshlrev_b32_e32 v160, 16, v111
	v_and_b32_e32 v161, 0xffff0000, v111
	global_store_dwordx4 v[148:149], v[150:153], off offset:2560
	v_lshl_add_u64 v[148:149], v[148:149], 0, s[10:11]
	v_fma_f32 v6, v6, s13, v154
	v_fma_f32 v7, v7, s13, v155
	v_fma_f32 v8, v8, s13, v156
	v_fma_f32 v9, v9, s13, v157
	v_fma_f32 v12, v12, s13, v158
	v_fma_f32 v13, v13, s13, v159
	v_fma_f32 v14, v14, s13, v160
	v_fma_f32 v15, v15, s13, v161
	v_cvt_pk_bf16_f32 v150, v6, v7
	v_cvt_pk_bf16_f32 v151, v8, v9
	v_cvt_pk_bf16_f32 v152, v12, v13
	v_cvt_pk_bf16_f32 v153, v14, v15
	v_lshlrev_b32_e32 v154, 16, v112
	v_and_b32_e32 v155, 0xffff0000, v112
	v_lshlrev_b32_e32 v156, 16, v113
	v_and_b32_e32 v157, 0xffff0000, v113
	v_lshlrev_b32_e32 v158, 16, v114
	v_and_b32_e32 v159, 0xffff0000, v114
	v_lshlrev_b32_e32 v160, 16, v115
	v_and_b32_e32 v161, 0xffff0000, v115
	global_store_dwordx4 v[148:149], v[150:153], off offset:2560
	v_lshl_add_u64 v[148:149], v[148:149], 0, s[10:11]
	v_fma_f32 v6, v6, s35, v154
	v_fma_f32 v7, v7, s35, v155
	v_fma_f32 v8, v8, s35, v156
	v_fma_f32 v9, v9, s35, v157
	v_fma_f32 v12, v12, s35, v158
	v_fma_f32 v13, v13, s35, v159
	v_fma_f32 v14, v14, s35, v160
	v_fma_f32 v15, v15, s35, v161
	v_readlane_b32 s0, v17, 24
	v_readlane_b32 s12, v17, 25
	v_readlane_b32 s13, v17, 26
	v_readlane_b32 s35, v17, 27
	v_cvt_pk_bf16_f32 v150, v6, v7
	v_cvt_pk_bf16_f32 v151, v8, v9
	v_cvt_pk_bf16_f32 v152, v12, v13
	v_cvt_pk_bf16_f32 v153, v14, v15
	v_lshlrev_b32_e32 v154, 16, v116
	v_and_b32_e32 v155, 0xffff0000, v116
	v_lshlrev_b32_e32 v156, 16, v117
	v_and_b32_e32 v157, 0xffff0000, v117
	v_lshlrev_b32_e32 v158, 16, v118
	v_and_b32_e32 v159, 0xffff0000, v118
	v_lshlrev_b32_e32 v160, 16, v119
	v_and_b32_e32 v161, 0xffff0000, v119
	global_store_dwordx4 v[148:149], v[150:153], off offset:2560
	v_lshl_add_u64 v[148:149], v[148:149], 0, s[10:11]
	v_fma_f32 v6, v6, s0, v154
	v_fma_f32 v7, v7, s0, v155
	v_fma_f32 v8, v8, s0, v156
	v_fma_f32 v9, v9, s0, v157
	v_fma_f32 v12, v12, s0, v158
	v_fma_f32 v13, v13, s0, v159
	v_fma_f32 v14, v14, s0, v160
	v_fma_f32 v15, v15, s0, v161
	v_cvt_pk_bf16_f32 v150, v6, v7
	v_cvt_pk_bf16_f32 v151, v8, v9
	v_cvt_pk_bf16_f32 v152, v12, v13
	v_cvt_pk_bf16_f32 v153, v14, v15
	v_lshlrev_b32_e32 v154, 16, v120
	v_and_b32_e32 v155, 0xffff0000, v120
	v_lshlrev_b32_e32 v156, 16, v121
	v_and_b32_e32 v157, 0xffff0000, v121
	v_lshlrev_b32_e32 v158, 16, v122
	v_and_b32_e32 v159, 0xffff0000, v122
	v_lshlrev_b32_e32 v160, 16, v123
	v_and_b32_e32 v161, 0xffff0000, v123
	global_store_dwordx4 v[148:149], v[150:153], off offset:2560
	v_lshl_add_u64 v[148:149], v[148:149], 0, s[10:11]
	v_fma_f32 v6, v6, s12, v154
	v_fma_f32 v7, v7, s12, v155
	v_fma_f32 v8, v8, s12, v156
	v_fma_f32 v9, v9, s12, v157
	v_fma_f32 v12, v12, s12, v158
	v_fma_f32 v13, v13, s12, v159
	v_fma_f32 v14, v14, s12, v160
	v_fma_f32 v15, v15, s12, v161
	v_cvt_pk_bf16_f32 v150, v6, v7
	v_cvt_pk_bf16_f32 v151, v8, v9
	v_cvt_pk_bf16_f32 v152, v12, v13
	v_cvt_pk_bf16_f32 v153, v14, v15
	v_lshlrev_b32_e32 v154, 16, v124
	v_and_b32_e32 v155, 0xffff0000, v124
	v_lshlrev_b32_e32 v156, 16, v125
	v_and_b32_e32 v157, 0xffff0000, v125
	v_lshlrev_b32_e32 v158, 16, v126
	v_and_b32_e32 v159, 0xffff0000, v126
	v_lshlrev_b32_e32 v160, 16, v127
	v_and_b32_e32 v161, 0xffff0000, v127
	global_store_dwordx4 v[148:149], v[150:153], off offset:2560
	v_lshl_add_u64 v[148:149], v[148:149], 0, s[10:11]
	v_fma_f32 v6, v6, s13, v154
	v_fma_f32 v7, v7, s13, v155
	v_fma_f32 v8, v8, s13, v156
	v_fma_f32 v9, v9, s13, v157
	v_fma_f32 v12, v12, s13, v158
	v_fma_f32 v13, v13, s13, v159
	v_fma_f32 v14, v14, s13, v160
	v_fma_f32 v15, v15, s13, v161
	v_cvt_pk_bf16_f32 v150, v6, v7
	v_cvt_pk_bf16_f32 v151, v8, v9
	v_cvt_pk_bf16_f32 v152, v12, v13
	v_cvt_pk_bf16_f32 v153, v14, v15
	v_lshlrev_b32_e32 v154, 16, v128
	v_and_b32_e32 v155, 0xffff0000, v128
	v_lshlrev_b32_e32 v156, 16, v129
	v_and_b32_e32 v157, 0xffff0000, v129
	v_lshlrev_b32_e32 v158, 16, v130
	v_and_b32_e32 v159, 0xffff0000, v130
	v_lshlrev_b32_e32 v160, 16, v131
	v_and_b32_e32 v161, 0xffff0000, v131
	global_store_dwordx4 v[148:149], v[150:153], off offset:2560
	v_lshl_add_u64 v[148:149], v[148:149], 0, s[10:11]
	v_fma_f32 v6, v6, s35, v154
	v_fma_f32 v7, v7, s35, v155
	v_fma_f32 v8, v8, s35, v156
	v_fma_f32 v9, v9, s35, v157
	v_fma_f32 v12, v12, s35, v158
	v_fma_f32 v13, v13, s35, v159
	v_fma_f32 v14, v14, s35, v160
	v_fma_f32 v15, v15, s35, v161
	v_readlane_b32 s0, v17, 28
	v_readlane_b32 s12, v17, 29
	v_readlane_b32 s13, v17, 30
	v_readlane_b32 s35, v17, 31
	v_cvt_pk_bf16_f32 v150, v6, v7
	v_cvt_pk_bf16_f32 v151, v8, v9
	v_cvt_pk_bf16_f32 v152, v12, v13
	v_cvt_pk_bf16_f32 v153, v14, v15
	v_lshlrev_b32_e32 v154, 16, v132
	v_and_b32_e32 v155, 0xffff0000, v132
	v_lshlrev_b32_e32 v156, 16, v133
	v_and_b32_e32 v157, 0xffff0000, v133
	v_lshlrev_b32_e32 v158, 16, v134
	v_and_b32_e32 v159, 0xffff0000, v134
	v_lshlrev_b32_e32 v160, 16, v135
	v_and_b32_e32 v161, 0xffff0000, v135
	global_store_dwordx4 v[148:149], v[150:153], off offset:2560
	v_lshl_add_u64 v[148:149], v[148:149], 0, s[10:11]
	v_fma_f32 v6, v6, s0, v154
	v_fma_f32 v7, v7, s0, v155
	v_fma_f32 v8, v8, s0, v156
	v_fma_f32 v9, v9, s0, v157
	v_fma_f32 v12, v12, s0, v158
	v_fma_f32 v13, v13, s0, v159
	v_fma_f32 v14, v14, s0, v160
	v_fma_f32 v15, v15, s0, v161
	v_cvt_pk_bf16_f32 v150, v6, v7
	v_cvt_pk_bf16_f32 v151, v8, v9
	v_cvt_pk_bf16_f32 v152, v12, v13
	v_cvt_pk_bf16_f32 v153, v14, v15
	v_lshlrev_b32_e32 v154, 16, v136
	v_and_b32_e32 v155, 0xffff0000, v136
	v_lshlrev_b32_e32 v156, 16, v137
	v_and_b32_e32 v157, 0xffff0000, v137
	v_lshlrev_b32_e32 v158, 16, v138
	v_and_b32_e32 v159, 0xffff0000, v138
	v_lshlrev_b32_e32 v160, 16, v139
	v_and_b32_e32 v161, 0xffff0000, v139
	global_store_dwordx4 v[148:149], v[150:153], off offset:2560
	v_lshl_add_u64 v[148:149], v[148:149], 0, s[10:11]
	v_fma_f32 v6, v6, s12, v154
	v_fma_f32 v7, v7, s12, v155
	v_fma_f32 v8, v8, s12, v156
	v_fma_f32 v9, v9, s12, v157
	v_fma_f32 v12, v12, s12, v158
	v_fma_f32 v13, v13, s12, v159
	v_fma_f32 v14, v14, s12, v160
	v_fma_f32 v15, v15, s12, v161
	v_cvt_pk_bf16_f32 v150, v6, v7
	v_cvt_pk_bf16_f32 v151, v8, v9
	v_cvt_pk_bf16_f32 v152, v12, v13
	v_cvt_pk_bf16_f32 v153, v14, v15
	v_lshlrev_b32_e32 v154, 16, v140
	v_and_b32_e32 v155, 0xffff0000, v140
	v_lshlrev_b32_e32 v156, 16, v141
	v_and_b32_e32 v157, 0xffff0000, v141
	v_lshlrev_b32_e32 v158, 16, v142
	v_and_b32_e32 v159, 0xffff0000, v142
	v_lshlrev_b32_e32 v160, 16, v143
	v_and_b32_e32 v161, 0xffff0000, v143
	global_store_dwordx4 v[148:149], v[150:153], off offset:2560
	v_lshl_add_u64 v[148:149], v[148:149], 0, s[10:11]
	v_fma_f32 v6, v6, s13, v154
	v_fma_f32 v7, v7, s13, v155
	v_fma_f32 v8, v8, s13, v156
	v_fma_f32 v9, v9, s13, v157
	v_fma_f32 v12, v12, s13, v158
	v_fma_f32 v13, v13, s13, v159
	v_fma_f32 v14, v14, s13, v160
	v_fma_f32 v15, v15, s13, v161
	v_cvt_pk_bf16_f32 v150, v6, v7
	v_cvt_pk_bf16_f32 v151, v8, v9
	v_cvt_pk_bf16_f32 v152, v12, v13
	v_cvt_pk_bf16_f32 v153, v14, v15
	v_lshlrev_b32_e32 v154, 16, v144
	v_and_b32_e32 v155, 0xffff0000, v144
	v_lshlrev_b32_e32 v156, 16, v145
	v_and_b32_e32 v157, 0xffff0000, v145
	v_lshlrev_b32_e32 v158, 16, v146
	v_and_b32_e32 v159, 0xffff0000, v146
	v_lshlrev_b32_e32 v160, 16, v147
	v_and_b32_e32 v161, 0xffff0000, v147
	global_store_dwordx4 v[148:149], v[150:153], off offset:2560
	v_lshl_add_u64 v[148:149], v[148:149], 0, s[10:11]
	v_fma_f32 v6, v6, s35, v154
	v_fma_f32 v7, v7, s35, v155
	v_fma_f32 v8, v8, s35, v156
	v_fma_f32 v9, v9, s35, v157
	v_fma_f32 v12, v12, s35, v158
	v_fma_f32 v13, v13, s35, v159
	v_fma_f32 v14, v14, s35, v160
	v_fma_f32 v15, v15, s35, v161
	s_waitcnt vmcnt(24)
	global_load_dwordx4 v[84:87], v[18:19], off offset:2560
	v_lshl_add_u64 v[18:19], v[18:19], 0, s[10:11]
	global_load_dwordx4 v[88:91], v[18:19], off offset:2560
	v_lshl_add_u64 v[18:19], v[18:19], 0, s[10:11]
	global_load_dwordx4 v[92:95], v[18:19], off offset:2560
	v_lshl_add_u64 v[18:19], v[18:19], 0, s[10:11]
	global_load_dwordx4 v[96:99], v[18:19], off offset:2560
	v_lshl_add_u64 v[18:19], v[18:19], 0, s[10:11]
	global_load_dwordx4 v[100:103], v[18:19], off offset:2560
	v_lshl_add_u64 v[18:19], v[18:19], 0, s[10:11]
	global_load_dwordx4 v[104:107], v[18:19], off offset:2560
	v_lshl_add_u64 v[18:19], v[18:19], 0, s[10:11]
	global_load_dwordx4 v[108:111], v[18:19], off offset:2560
	v_lshl_add_u64 v[18:19], v[18:19], 0, s[10:11]
	global_load_dwordx4 v[112:115], v[18:19], off offset:2560
	v_lshl_add_u64 v[18:19], v[18:19], 0, s[10:11]
	global_load_dwordx4 v[116:119], v[18:19], off offset:2560
	v_lshl_add_u64 v[18:19], v[18:19], 0, s[10:11]
	global_load_dwordx4 v[120:123], v[18:19], off offset:2560
	v_lshl_add_u64 v[18:19], v[18:19], 0, s[10:11]
	global_load_dwordx4 v[124:127], v[18:19], off offset:2560
	v_lshl_add_u64 v[18:19], v[18:19], 0, s[10:11]
	global_load_dwordx4 v[128:131], v[18:19], off offset:2560
	v_lshl_add_u64 v[18:19], v[18:19], 0, s[10:11]
	global_load_dwordx4 v[132:135], v[18:19], off offset:2560
	v_lshl_add_u64 v[18:19], v[18:19], 0, s[10:11]
	global_load_dwordx4 v[136:139], v[18:19], off offset:2560
	v_lshl_add_u64 v[18:19], v[18:19], 0, s[10:11]
	global_load_dwordx4 v[140:143], v[18:19], off offset:2560
	v_lshl_add_u64 v[18:19], v[18:19], 0, s[10:11]
	global_load_dwordx4 v[144:147], v[18:19], off offset:2560
	v_lshl_add_u64 v[18:19], v[18:19], 0, s[10:11]
	s_waitcnt vmcnt(32)
	v_readlane_b32 s0, v17, 32
	v_readlane_b32 s12, v17, 33
	v_readlane_b32 s13, v17, 34
	v_readlane_b32 s35, v17, 35
	v_cvt_pk_bf16_f32 v150, v6, v7
	v_cvt_pk_bf16_f32 v151, v8, v9
	v_cvt_pk_bf16_f32 v152, v12, v13
	v_cvt_pk_bf16_f32 v153, v14, v15
	v_lshlrev_b32_e32 v154, 16, v20
	v_and_b32_e32 v155, 0xffff0000, v20
	v_lshlrev_b32_e32 v156, 16, v21
	v_and_b32_e32 v157, 0xffff0000, v21
	v_lshlrev_b32_e32 v158, 16, v22
	v_and_b32_e32 v159, 0xffff0000, v22
	v_lshlrev_b32_e32 v160, 16, v23
	v_and_b32_e32 v161, 0xffff0000, v23
	global_store_dwordx4 v[148:149], v[150:153], off offset:2560
	v_lshl_add_u64 v[148:149], v[148:149], 0, s[10:11]
	v_fma_f32 v6, v6, s0, v154
	v_fma_f32 v7, v7, s0, v155
	v_fma_f32 v8, v8, s0, v156
	v_fma_f32 v9, v9, s0, v157
	v_fma_f32 v12, v12, s0, v158
	v_fma_f32 v13, v13, s0, v159
	v_fma_f32 v14, v14, s0, v160
	v_fma_f32 v15, v15, s0, v161
	v_cvt_pk_bf16_f32 v150, v6, v7
	v_cvt_pk_bf16_f32 v151, v8, v9
	v_cvt_pk_bf16_f32 v152, v12, v13
	v_cvt_pk_bf16_f32 v153, v14, v15
	v_lshlrev_b32_e32 v154, 16, v24
	v_and_b32_e32 v155, 0xffff0000, v24
	v_lshlrev_b32_e32 v156, 16, v25
	v_and_b32_e32 v157, 0xffff0000, v25
	v_lshlrev_b32_e32 v158, 16, v26
	v_and_b32_e32 v159, 0xffff0000, v26
	v_lshlrev_b32_e32 v160, 16, v27
	v_and_b32_e32 v161, 0xffff0000, v27
	global_store_dwordx4 v[148:149], v[150:153], off offset:2560
	v_lshl_add_u64 v[148:149], v[148:149], 0, s[10:11]
	v_fma_f32 v6, v6, s12, v154
	v_fma_f32 v7, v7, s12, v155
	v_fma_f32 v8, v8, s12, v156
	v_fma_f32 v9, v9, s12, v157
	v_fma_f32 v12, v12, s12, v158
	v_fma_f32 v13, v13, s12, v159
	v_fma_f32 v14, v14, s12, v160
	v_fma_f32 v15, v15, s12, v161
	v_cvt_pk_bf16_f32 v150, v6, v7
	v_cvt_pk_bf16_f32 v151, v8, v9
	v_cvt_pk_bf16_f32 v152, v12, v13
	v_cvt_pk_bf16_f32 v153, v14, v15
	v_lshlrev_b32_e32 v154, 16, v28
	v_and_b32_e32 v155, 0xffff0000, v28
	v_lshlrev_b32_e32 v156, 16, v29
	v_and_b32_e32 v157, 0xffff0000, v29
	v_lshlrev_b32_e32 v158, 16, v30
	v_and_b32_e32 v159, 0xffff0000, v30
	v_lshlrev_b32_e32 v160, 16, v31
	v_and_b32_e32 v161, 0xffff0000, v31
	global_store_dwordx4 v[148:149], v[150:153], off offset:2560
	v_lshl_add_u64 v[148:149], v[148:149], 0, s[10:11]
	v_fma_f32 v6, v6, s13, v154
	v_fma_f32 v7, v7, s13, v155
	v_fma_f32 v8, v8, s13, v156
	v_fma_f32 v9, v9, s13, v157
	v_fma_f32 v12, v12, s13, v158
	v_fma_f32 v13, v13, s13, v159
	v_fma_f32 v14, v14, s13, v160
	v_fma_f32 v15, v15, s13, v161
	v_cvt_pk_bf16_f32 v150, v6, v7
	v_cvt_pk_bf16_f32 v151, v8, v9
	v_cvt_pk_bf16_f32 v152, v12, v13
	v_cvt_pk_bf16_f32 v153, v14, v15
	v_lshlrev_b32_e32 v154, 16, v32
	v_and_b32_e32 v155, 0xffff0000, v32
	v_lshlrev_b32_e32 v156, 16, v33
	v_and_b32_e32 v157, 0xffff0000, v33
	v_lshlrev_b32_e32 v158, 16, v34
	v_and_b32_e32 v159, 0xffff0000, v34
	v_lshlrev_b32_e32 v160, 16, v35
	v_and_b32_e32 v161, 0xffff0000, v35
	global_store_dwordx4 v[148:149], v[150:153], off offset:2560
	v_lshl_add_u64 v[148:149], v[148:149], 0, s[10:11]
	v_fma_f32 v6, v6, s35, v154
	v_fma_f32 v7, v7, s35, v155
	v_fma_f32 v8, v8, s35, v156
	v_fma_f32 v9, v9, s35, v157
	v_fma_f32 v12, v12, s35, v158
	v_fma_f32 v13, v13, s35, v159
	v_fma_f32 v14, v14, s35, v160
	v_fma_f32 v15, v15, s35, v161
	v_readlane_b32 s0, v17, 36
	v_readlane_b32 s12, v17, 37
	v_readlane_b32 s13, v17, 38
	v_readlane_b32 s35, v17, 39
	v_cvt_pk_bf16_f32 v150, v6, v7
	v_cvt_pk_bf16_f32 v151, v8, v9
	v_cvt_pk_bf16_f32 v152, v12, v13
	v_cvt_pk_bf16_f32 v153, v14, v15
	v_lshlrev_b32_e32 v154, 16, v36
	v_and_b32_e32 v155, 0xffff0000, v36
	v_lshlrev_b32_e32 v156, 16, v37
	v_and_b32_e32 v157, 0xffff0000, v37
	v_lshlrev_b32_e32 v158, 16, v38
	v_and_b32_e32 v159, 0xffff0000, v38
	v_lshlrev_b32_e32 v160, 16, v39
	v_and_b32_e32 v161, 0xffff0000, v39
	global_store_dwordx4 v[148:149], v[150:153], off offset:2560
	v_lshl_add_u64 v[148:149], v[148:149], 0, s[10:11]
	v_fma_f32 v6, v6, s0, v154
	v_fma_f32 v7, v7, s0, v155
	v_fma_f32 v8, v8, s0, v156
	v_fma_f32 v9, v9, s0, v157
	v_fma_f32 v12, v12, s0, v158
	v_fma_f32 v13, v13, s0, v159
	v_fma_f32 v14, v14, s0, v160
	v_fma_f32 v15, v15, s0, v161
	v_cvt_pk_bf16_f32 v150, v6, v7
	v_cvt_pk_bf16_f32 v151, v8, v9
	v_cvt_pk_bf16_f32 v152, v12, v13
	v_cvt_pk_bf16_f32 v153, v14, v15
	v_lshlrev_b32_e32 v154, 16, v40
	v_and_b32_e32 v155, 0xffff0000, v40
	v_lshlrev_b32_e32 v156, 16, v41
	v_and_b32_e32 v157, 0xffff0000, v41
	v_lshlrev_b32_e32 v158, 16, v42
	v_and_b32_e32 v159, 0xffff0000, v42
	v_lshlrev_b32_e32 v160, 16, v43
	v_and_b32_e32 v161, 0xffff0000, v43
	global_store_dwordx4 v[148:149], v[150:153], off offset:2560
	v_lshl_add_u64 v[148:149], v[148:149], 0, s[10:11]
	v_fma_f32 v6, v6, s12, v154
	v_fma_f32 v7, v7, s12, v155
	v_fma_f32 v8, v8, s12, v156
	v_fma_f32 v9, v9, s12, v157
	v_fma_f32 v12, v12, s12, v158
	v_fma_f32 v13, v13, s12, v159
	v_fma_f32 v14, v14, s12, v160
	v_fma_f32 v15, v15, s12, v161
	v_cvt_pk_bf16_f32 v150, v6, v7
	v_cvt_pk_bf16_f32 v151, v8, v9
	v_cvt_pk_bf16_f32 v152, v12, v13
	v_cvt_pk_bf16_f32 v153, v14, v15
	v_lshlrev_b32_e32 v154, 16, v44
	v_and_b32_e32 v155, 0xffff0000, v44
	v_lshlrev_b32_e32 v156, 16, v45
	v_and_b32_e32 v157, 0xffff0000, v45
	v_lshlrev_b32_e32 v158, 16, v46
	v_and_b32_e32 v159, 0xffff0000, v46
	v_lshlrev_b32_e32 v160, 16, v47
	v_and_b32_e32 v161, 0xffff0000, v47
	global_store_dwordx4 v[148:149], v[150:153], off offset:2560
	v_lshl_add_u64 v[148:149], v[148:149], 0, s[10:11]
	v_fma_f32 v6, v6, s13, v154
	v_fma_f32 v7, v7, s13, v155
	v_fma_f32 v8, v8, s13, v156
	v_fma_f32 v9, v9, s13, v157
	v_fma_f32 v12, v12, s13, v158
	v_fma_f32 v13, v13, s13, v159
	v_fma_f32 v14, v14, s13, v160
	v_fma_f32 v15, v15, s13, v161
	v_cvt_pk_bf16_f32 v150, v6, v7
	v_cvt_pk_bf16_f32 v151, v8, v9
	v_cvt_pk_bf16_f32 v152, v12, v13
	v_cvt_pk_bf16_f32 v153, v14, v15
	v_lshlrev_b32_e32 v154, 16, v48
	v_and_b32_e32 v155, 0xffff0000, v48
	v_lshlrev_b32_e32 v156, 16, v49
	v_and_b32_e32 v157, 0xffff0000, v49
	v_lshlrev_b32_e32 v158, 16, v50
	v_and_b32_e32 v159, 0xffff0000, v50
	v_lshlrev_b32_e32 v160, 16, v51
	v_and_b32_e32 v161, 0xffff0000, v51
	global_store_dwordx4 v[148:149], v[150:153], off offset:2560
	v_lshl_add_u64 v[148:149], v[148:149], 0, s[10:11]
	v_fma_f32 v6, v6, s35, v154
	v_fma_f32 v7, v7, s35, v155
	v_fma_f32 v8, v8, s35, v156
	v_fma_f32 v9, v9, s35, v157
	v_fma_f32 v12, v12, s35, v158
	v_fma_f32 v13, v13, s35, v159
	v_fma_f32 v14, v14, s35, v160
	v_fma_f32 v15, v15, s35, v161
	v_readlane_b32 s0, v17, 40
	v_readlane_b32 s12, v17, 41
	v_readlane_b32 s13, v17, 42
	v_readlane_b32 s35, v17, 43
	v_cvt_pk_bf16_f32 v150, v6, v7
	v_cvt_pk_bf16_f32 v151, v8, v9
	v_cvt_pk_bf16_f32 v152, v12, v13
	v_cvt_pk_bf16_f32 v153, v14, v15
	v_lshlrev_b32_e32 v154, 16, v52
	v_and_b32_e32 v155, 0xffff0000, v52
	v_lshlrev_b32_e32 v156, 16, v53
	v_and_b32_e32 v157, 0xffff0000, v53
	v_lshlrev_b32_e32 v158, 16, v54
	v_and_b32_e32 v159, 0xffff0000, v54
	v_lshlrev_b32_e32 v160, 16, v55
	v_and_b32_e32 v161, 0xffff0000, v55
	global_store_dwordx4 v[148:149], v[150:153], off offset:2560
	v_lshl_add_u64 v[148:149], v[148:149], 0, s[10:11]
	v_fma_f32 v6, v6, s0, v154
	v_fma_f32 v7, v7, s0, v155
	v_fma_f32 v8, v8, s0, v156
	v_fma_f32 v9, v9, s0, v157
	v_fma_f32 v12, v12, s0, v158
	v_fma_f32 v13, v13, s0, v159
	v_fma_f32 v14, v14, s0, v160
	v_fma_f32 v15, v15, s0, v161
	v_cvt_pk_bf16_f32 v150, v6, v7
	v_cvt_pk_bf16_f32 v151, v8, v9
	v_cvt_pk_bf16_f32 v152, v12, v13
	v_cvt_pk_bf16_f32 v153, v14, v15
	v_lshlrev_b32_e32 v154, 16, v56
	v_and_b32_e32 v155, 0xffff0000, v56
	v_lshlrev_b32_e32 v156, 16, v57
	v_and_b32_e32 v157, 0xffff0000, v57
	v_lshlrev_b32_e32 v158, 16, v58
	v_and_b32_e32 v159, 0xffff0000, v58
	v_lshlrev_b32_e32 v160, 16, v59
	v_and_b32_e32 v161, 0xffff0000, v59
	global_store_dwordx4 v[148:149], v[150:153], off offset:2560
	v_lshl_add_u64 v[148:149], v[148:149], 0, s[10:11]
	v_fma_f32 v6, v6, s12, v154
	v_fma_f32 v7, v7, s12, v155
	v_fma_f32 v8, v8, s12, v156
	v_fma_f32 v9, v9, s12, v157
	v_fma_f32 v12, v12, s12, v158
	v_fma_f32 v13, v13, s12, v159
	v_fma_f32 v14, v14, s12, v160
	v_fma_f32 v15, v15, s12, v161
	v_cvt_pk_bf16_f32 v150, v6, v7
	v_cvt_pk_bf16_f32 v151, v8, v9
	v_cvt_pk_bf16_f32 v152, v12, v13
	v_cvt_pk_bf16_f32 v153, v14, v15
	v_lshlrev_b32_e32 v154, 16, v60
	v_and_b32_e32 v155, 0xffff0000, v60
	v_lshlrev_b32_e32 v156, 16, v61
	v_and_b32_e32 v157, 0xffff0000, v61
	v_lshlrev_b32_e32 v158, 16, v62
	v_and_b32_e32 v159, 0xffff0000, v62
	v_lshlrev_b32_e32 v160, 16, v63
	v_and_b32_e32 v161, 0xffff0000, v63
	global_store_dwordx4 v[148:149], v[150:153], off offset:2560
	v_lshl_add_u64 v[148:149], v[148:149], 0, s[10:11]
	v_fma_f32 v6, v6, s13, v154
	v_fma_f32 v7, v7, s13, v155
	v_fma_f32 v8, v8, s13, v156
	v_fma_f32 v9, v9, s13, v157
	v_fma_f32 v12, v12, s13, v158
	v_fma_f32 v13, v13, s13, v159
	v_fma_f32 v14, v14, s13, v160
	v_fma_f32 v15, v15, s13, v161
	v_cvt_pk_bf16_f32 v150, v6, v7
	v_cvt_pk_bf16_f32 v151, v8, v9
	v_cvt_pk_bf16_f32 v152, v12, v13
	v_cvt_pk_bf16_f32 v153, v14, v15
	v_lshlrev_b32_e32 v154, 16, v64
	v_and_b32_e32 v155, 0xffff0000, v64
	v_lshlrev_b32_e32 v156, 16, v65
	v_and_b32_e32 v157, 0xffff0000, v65
	v_lshlrev_b32_e32 v158, 16, v66
	v_and_b32_e32 v159, 0xffff0000, v66
	v_lshlrev_b32_e32 v160, 16, v67
	v_and_b32_e32 v161, 0xffff0000, v67
	global_store_dwordx4 v[148:149], v[150:153], off offset:2560
	v_lshl_add_u64 v[148:149], v[148:149], 0, s[10:11]
	v_fma_f32 v6, v6, s35, v154
	v_fma_f32 v7, v7, s35, v155
	v_fma_f32 v8, v8, s35, v156
	v_fma_f32 v9, v9, s35, v157
	v_fma_f32 v12, v12, s35, v158
	v_fma_f32 v13, v13, s35, v159
	v_fma_f32 v14, v14, s35, v160
	v_fma_f32 v15, v15, s35, v161
	v_readlane_b32 s0, v17, 44
	v_readlane_b32 s12, v17, 45
	v_readlane_b32 s13, v17, 46
	v_readlane_b32 s35, v17, 47
	v_cvt_pk_bf16_f32 v150, v6, v7
	v_cvt_pk_bf16_f32 v151, v8, v9
	v_cvt_pk_bf16_f32 v152, v12, v13
	v_cvt_pk_bf16_f32 v153, v14, v15
	v_lshlrev_b32_e32 v154, 16, v68
	v_and_b32_e32 v155, 0xffff0000, v68
	v_lshlrev_b32_e32 v156, 16, v69
	v_and_b32_e32 v157, 0xffff0000, v69
	v_lshlrev_b32_e32 v158, 16, v70
	v_and_b32_e32 v159, 0xffff0000, v70
	v_lshlrev_b32_e32 v160, 16, v71
	v_and_b32_e32 v161, 0xffff0000, v71
	global_store_dwordx4 v[148:149], v[150:153], off offset:2560
	v_lshl_add_u64 v[148:149], v[148:149], 0, s[10:11]
	v_fma_f32 v6, v6, s0, v154
	v_fma_f32 v7, v7, s0, v155
	v_fma_f32 v8, v8, s0, v156
	v_fma_f32 v9, v9, s0, v157
	v_fma_f32 v12, v12, s0, v158
	v_fma_f32 v13, v13, s0, v159
	v_fma_f32 v14, v14, s0, v160
	v_fma_f32 v15, v15, s0, v161
	v_cvt_pk_bf16_f32 v150, v6, v7
	v_cvt_pk_bf16_f32 v151, v8, v9
	v_cvt_pk_bf16_f32 v152, v12, v13
	v_cvt_pk_bf16_f32 v153, v14, v15
	v_lshlrev_b32_e32 v154, 16, v72
	v_and_b32_e32 v155, 0xffff0000, v72
	v_lshlrev_b32_e32 v156, 16, v73
	v_and_b32_e32 v157, 0xffff0000, v73
	v_lshlrev_b32_e32 v158, 16, v74
	v_and_b32_e32 v159, 0xffff0000, v74
	v_lshlrev_b32_e32 v160, 16, v75
	v_and_b32_e32 v161, 0xffff0000, v75
	global_store_dwordx4 v[148:149], v[150:153], off offset:2560
	v_lshl_add_u64 v[148:149], v[148:149], 0, s[10:11]
	v_fma_f32 v6, v6, s12, v154
	v_fma_f32 v7, v7, s12, v155
	v_fma_f32 v8, v8, s12, v156
	v_fma_f32 v9, v9, s12, v157
	v_fma_f32 v12, v12, s12, v158
	v_fma_f32 v13, v13, s12, v159
	v_fma_f32 v14, v14, s12, v160
	v_fma_f32 v15, v15, s12, v161
	v_cvt_pk_bf16_f32 v150, v6, v7
	v_cvt_pk_bf16_f32 v151, v8, v9
	v_cvt_pk_bf16_f32 v152, v12, v13
	v_cvt_pk_bf16_f32 v153, v14, v15
	v_lshlrev_b32_e32 v154, 16, v76
	v_and_b32_e32 v155, 0xffff0000, v76
	v_lshlrev_b32_e32 v156, 16, v77
	v_and_b32_e32 v157, 0xffff0000, v77
	v_lshlrev_b32_e32 v158, 16, v78
	v_and_b32_e32 v159, 0xffff0000, v78
	v_lshlrev_b32_e32 v160, 16, v79
	v_and_b32_e32 v161, 0xffff0000, v79
	global_store_dwordx4 v[148:149], v[150:153], off offset:2560
	v_lshl_add_u64 v[148:149], v[148:149], 0, s[10:11]
	v_fma_f32 v6, v6, s13, v154
	v_fma_f32 v7, v7, s13, v155
	v_fma_f32 v8, v8, s13, v156
	v_fma_f32 v9, v9, s13, v157
	v_fma_f32 v12, v12, s13, v158
	v_fma_f32 v13, v13, s13, v159
	v_fma_f32 v14, v14, s13, v160
	v_fma_f32 v15, v15, s13, v161
	v_cvt_pk_bf16_f32 v150, v6, v7
	v_cvt_pk_bf16_f32 v151, v8, v9
	v_cvt_pk_bf16_f32 v152, v12, v13
	v_cvt_pk_bf16_f32 v153, v14, v15
	v_lshlrev_b32_e32 v154, 16, v80
	v_and_b32_e32 v155, 0xffff0000, v80
	v_lshlrev_b32_e32 v156, 16, v81
	v_and_b32_e32 v157, 0xffff0000, v81
	v_lshlrev_b32_e32 v158, 16, v82
	v_and_b32_e32 v159, 0xffff0000, v82
	v_lshlrev_b32_e32 v160, 16, v83
	v_and_b32_e32 v161, 0xffff0000, v83
	global_store_dwordx4 v[148:149], v[150:153], off offset:2560
	v_lshl_add_u64 v[148:149], v[148:149], 0, s[10:11]
	v_fma_f32 v6, v6, s35, v154
	v_fma_f32 v7, v7, s35, v155
	v_fma_f32 v8, v8, s35, v156
	v_fma_f32 v9, v9, s35, v157
	v_fma_f32 v12, v12, s35, v158
	v_fma_f32 v13, v13, s35, v159
	v_fma_f32 v14, v14, s35, v160
	v_fma_f32 v15, v15, s35, v161
	s_waitcnt vmcnt(16)
	v_readlane_b32 s0, v17, 48
	v_readlane_b32 s12, v17, 49
	v_readlane_b32 s13, v17, 50
	v_readlane_b32 s35, v17, 51
	v_cvt_pk_bf16_f32 v150, v6, v7
	v_cvt_pk_bf16_f32 v151, v8, v9
	v_cvt_pk_bf16_f32 v152, v12, v13
	v_cvt_pk_bf16_f32 v153, v14, v15
	v_lshlrev_b32_e32 v154, 16, v84
	v_and_b32_e32 v155, 0xffff0000, v84
	v_lshlrev_b32_e32 v156, 16, v85
	v_and_b32_e32 v157, 0xffff0000, v85
	v_lshlrev_b32_e32 v158, 16, v86
	v_and_b32_e32 v159, 0xffff0000, v86
	v_lshlrev_b32_e32 v160, 16, v87
	v_and_b32_e32 v161, 0xffff0000, v87
	global_store_dwordx4 v[148:149], v[150:153], off offset:2560
	v_lshl_add_u64 v[148:149], v[148:149], 0, s[10:11]
	v_fma_f32 v6, v6, s0, v154
	v_fma_f32 v7, v7, s0, v155
	v_fma_f32 v8, v8, s0, v156
	v_fma_f32 v9, v9, s0, v157
	v_fma_f32 v12, v12, s0, v158
	v_fma_f32 v13, v13, s0, v159
	v_fma_f32 v14, v14, s0, v160
	v_fma_f32 v15, v15, s0, v161
	v_cvt_pk_bf16_f32 v150, v6, v7
	v_cvt_pk_bf16_f32 v151, v8, v9
	v_cvt_pk_bf16_f32 v152, v12, v13
	v_cvt_pk_bf16_f32 v153, v14, v15
	v_lshlrev_b32_e32 v154, 16, v88
	v_and_b32_e32 v155, 0xffff0000, v88
	v_lshlrev_b32_e32 v156, 16, v89
	v_and_b32_e32 v157, 0xffff0000, v89
	v_lshlrev_b32_e32 v158, 16, v90
	v_and_b32_e32 v159, 0xffff0000, v90
	v_lshlrev_b32_e32 v160, 16, v91
	v_and_b32_e32 v161, 0xffff0000, v91
	global_store_dwordx4 v[148:149], v[150:153], off offset:2560
	v_lshl_add_u64 v[148:149], v[148:149], 0, s[10:11]
	v_fma_f32 v6, v6, s12, v154
	v_fma_f32 v7, v7, s12, v155
	v_fma_f32 v8, v8, s12, v156
	v_fma_f32 v9, v9, s12, v157
	v_fma_f32 v12, v12, s12, v158
	v_fma_f32 v13, v13, s12, v159
	v_fma_f32 v14, v14, s12, v160
	v_fma_f32 v15, v15, s12, v161
	v_cvt_pk_bf16_f32 v150, v6, v7
	v_cvt_pk_bf16_f32 v151, v8, v9
	v_cvt_pk_bf16_f32 v152, v12, v13
	v_cvt_pk_bf16_f32 v153, v14, v15
	v_lshlrev_b32_e32 v154, 16, v92
	v_and_b32_e32 v155, 0xffff0000, v92
	v_lshlrev_b32_e32 v156, 16, v93
	v_and_b32_e32 v157, 0xffff0000, v93
	v_lshlrev_b32_e32 v158, 16, v94
	v_and_b32_e32 v159, 0xffff0000, v94
	v_lshlrev_b32_e32 v160, 16, v95
	v_and_b32_e32 v161, 0xffff0000, v95
	global_store_dwordx4 v[148:149], v[150:153], off offset:2560
	v_lshl_add_u64 v[148:149], v[148:149], 0, s[10:11]
	v_fma_f32 v6, v6, s13, v154
	v_fma_f32 v7, v7, s13, v155
	v_fma_f32 v8, v8, s13, v156
	v_fma_f32 v9, v9, s13, v157
	v_fma_f32 v12, v12, s13, v158
	v_fma_f32 v13, v13, s13, v159
	v_fma_f32 v14, v14, s13, v160
	v_fma_f32 v15, v15, s13, v161
	v_cvt_pk_bf16_f32 v150, v6, v7
	v_cvt_pk_bf16_f32 v151, v8, v9
	v_cvt_pk_bf16_f32 v152, v12, v13
	v_cvt_pk_bf16_f32 v153, v14, v15
	v_lshlrev_b32_e32 v154, 16, v96
	v_and_b32_e32 v155, 0xffff0000, v96
	v_lshlrev_b32_e32 v156, 16, v97
	v_and_b32_e32 v157, 0xffff0000, v97
	v_lshlrev_b32_e32 v158, 16, v98
	v_and_b32_e32 v159, 0xffff0000, v98
	v_lshlrev_b32_e32 v160, 16, v99
	v_and_b32_e32 v161, 0xffff0000, v99
	global_store_dwordx4 v[148:149], v[150:153], off offset:2560
	v_lshl_add_u64 v[148:149], v[148:149], 0, s[10:11]
	v_fma_f32 v6, v6, s35, v154
	v_fma_f32 v7, v7, s35, v155
	v_fma_f32 v8, v8, s35, v156
	v_fma_f32 v9, v9, s35, v157
	v_fma_f32 v12, v12, s35, v158
	v_fma_f32 v13, v13, s35, v159
	v_fma_f32 v14, v14, s35, v160
	v_fma_f32 v15, v15, s35, v161
	v_readlane_b32 s0, v17, 52
	v_readlane_b32 s12, v17, 53
	v_readlane_b32 s13, v17, 54
	v_readlane_b32 s35, v17, 55
	v_cvt_pk_bf16_f32 v150, v6, v7
	v_cvt_pk_bf16_f32 v151, v8, v9
	v_cvt_pk_bf16_f32 v152, v12, v13
	v_cvt_pk_bf16_f32 v153, v14, v15
	v_lshlrev_b32_e32 v154, 16, v100
	v_and_b32_e32 v155, 0xffff0000, v100
	v_lshlrev_b32_e32 v156, 16, v101
	v_and_b32_e32 v157, 0xffff0000, v101
	v_lshlrev_b32_e32 v158, 16, v102
	v_and_b32_e32 v159, 0xffff0000, v102
	v_lshlrev_b32_e32 v160, 16, v103
	v_and_b32_e32 v161, 0xffff0000, v103
	global_store_dwordx4 v[148:149], v[150:153], off offset:2560
	v_lshl_add_u64 v[148:149], v[148:149], 0, s[10:11]
	v_fma_f32 v6, v6, s0, v154
	v_fma_f32 v7, v7, s0, v155
	v_fma_f32 v8, v8, s0, v156
	v_fma_f32 v9, v9, s0, v157
	v_fma_f32 v12, v12, s0, v158
	v_fma_f32 v13, v13, s0, v159
	v_fma_f32 v14, v14, s0, v160
	v_fma_f32 v15, v15, s0, v161
	v_cvt_pk_bf16_f32 v150, v6, v7
	v_cvt_pk_bf16_f32 v151, v8, v9
	v_cvt_pk_bf16_f32 v152, v12, v13
	v_cvt_pk_bf16_f32 v153, v14, v15
	v_lshlrev_b32_e32 v154, 16, v104
	v_and_b32_e32 v155, 0xffff0000, v104
	v_lshlrev_b32_e32 v156, 16, v105
	v_and_b32_e32 v157, 0xffff0000, v105
	v_lshlrev_b32_e32 v158, 16, v106
	v_and_b32_e32 v159, 0xffff0000, v106
	v_lshlrev_b32_e32 v160, 16, v107
	v_and_b32_e32 v161, 0xffff0000, v107
	global_store_dwordx4 v[148:149], v[150:153], off offset:2560
	v_lshl_add_u64 v[148:149], v[148:149], 0, s[10:11]
	v_fma_f32 v6, v6, s12, v154
	v_fma_f32 v7, v7, s12, v155
	v_fma_f32 v8, v8, s12, v156
	v_fma_f32 v9, v9, s12, v157
	v_fma_f32 v12, v12, s12, v158
	v_fma_f32 v13, v13, s12, v159
	v_fma_f32 v14, v14, s12, v160
	v_fma_f32 v15, v15, s12, v161
	v_cvt_pk_bf16_f32 v150, v6, v7
	v_cvt_pk_bf16_f32 v151, v8, v9
	v_cvt_pk_bf16_f32 v152, v12, v13
	v_cvt_pk_bf16_f32 v153, v14, v15
	v_lshlrev_b32_e32 v154, 16, v108
	v_and_b32_e32 v155, 0xffff0000, v108
	v_lshlrev_b32_e32 v156, 16, v109
	v_and_b32_e32 v157, 0xffff0000, v109
	v_lshlrev_b32_e32 v158, 16, v110
	v_and_b32_e32 v159, 0xffff0000, v110
	v_lshlrev_b32_e32 v160, 16, v111
	v_and_b32_e32 v161, 0xffff0000, v111
	global_store_dwordx4 v[148:149], v[150:153], off offset:2560
	v_lshl_add_u64 v[148:149], v[148:149], 0, s[10:11]
	v_fma_f32 v6, v6, s13, v154
	v_fma_f32 v7, v7, s13, v155
	v_fma_f32 v8, v8, s13, v156
	v_fma_f32 v9, v9, s13, v157
	v_fma_f32 v12, v12, s13, v158
	v_fma_f32 v13, v13, s13, v159
	v_fma_f32 v14, v14, s13, v160
	v_fma_f32 v15, v15, s13, v161
	v_cvt_pk_bf16_f32 v150, v6, v7
	v_cvt_pk_bf16_f32 v151, v8, v9
	v_cvt_pk_bf16_f32 v152, v12, v13
	v_cvt_pk_bf16_f32 v153, v14, v15
	v_lshlrev_b32_e32 v154, 16, v112
	v_and_b32_e32 v155, 0xffff0000, v112
	v_lshlrev_b32_e32 v156, 16, v113
	v_and_b32_e32 v157, 0xffff0000, v113
	v_lshlrev_b32_e32 v158, 16, v114
	v_and_b32_e32 v159, 0xffff0000, v114
	v_lshlrev_b32_e32 v160, 16, v115
	v_and_b32_e32 v161, 0xffff0000, v115
	global_store_dwordx4 v[148:149], v[150:153], off offset:2560
	v_lshl_add_u64 v[148:149], v[148:149], 0, s[10:11]
	v_fma_f32 v6, v6, s35, v154
	v_fma_f32 v7, v7, s35, v155
	v_fma_f32 v8, v8, s35, v156
	v_fma_f32 v9, v9, s35, v157
	v_fma_f32 v12, v12, s35, v158
	v_fma_f32 v13, v13, s35, v159
	v_fma_f32 v14, v14, s35, v160
	v_fma_f32 v15, v15, s35, v161
	v_readlane_b32 s0, v17, 56
	v_readlane_b32 s12, v17, 57
	v_readlane_b32 s13, v17, 58
	v_readlane_b32 s35, v17, 59
	v_cvt_pk_bf16_f32 v150, v6, v7
	v_cvt_pk_bf16_f32 v151, v8, v9
	v_cvt_pk_bf16_f32 v152, v12, v13
	v_cvt_pk_bf16_f32 v153, v14, v15
	v_lshlrev_b32_e32 v154, 16, v116
	v_and_b32_e32 v155, 0xffff0000, v116
	v_lshlrev_b32_e32 v156, 16, v117
	v_and_b32_e32 v157, 0xffff0000, v117
	v_lshlrev_b32_e32 v158, 16, v118
	v_and_b32_e32 v159, 0xffff0000, v118
	v_lshlrev_b32_e32 v160, 16, v119
	v_and_b32_e32 v161, 0xffff0000, v119
	global_store_dwordx4 v[148:149], v[150:153], off offset:2560
	v_lshl_add_u64 v[148:149], v[148:149], 0, s[10:11]
	v_fma_f32 v6, v6, s0, v154
	v_fma_f32 v7, v7, s0, v155
	v_fma_f32 v8, v8, s0, v156
	v_fma_f32 v9, v9, s0, v157
	v_fma_f32 v12, v12, s0, v158
	v_fma_f32 v13, v13, s0, v159
	v_fma_f32 v14, v14, s0, v160
	v_fma_f32 v15, v15, s0, v161
	v_cvt_pk_bf16_f32 v150, v6, v7
	v_cvt_pk_bf16_f32 v151, v8, v9
	v_cvt_pk_bf16_f32 v152, v12, v13
	v_cvt_pk_bf16_f32 v153, v14, v15
	v_lshlrev_b32_e32 v154, 16, v120
	v_and_b32_e32 v155, 0xffff0000, v120
	v_lshlrev_b32_e32 v156, 16, v121
	v_and_b32_e32 v157, 0xffff0000, v121
	v_lshlrev_b32_e32 v158, 16, v122
	v_and_b32_e32 v159, 0xffff0000, v122
	v_lshlrev_b32_e32 v160, 16, v123
	v_and_b32_e32 v161, 0xffff0000, v123
	global_store_dwordx4 v[148:149], v[150:153], off offset:2560
	v_lshl_add_u64 v[148:149], v[148:149], 0, s[10:11]
	v_fma_f32 v6, v6, s12, v154
	v_fma_f32 v7, v7, s12, v155
	v_fma_f32 v8, v8, s12, v156
	v_fma_f32 v9, v9, s12, v157
	v_fma_f32 v12, v12, s12, v158
	v_fma_f32 v13, v13, s12, v159
	v_fma_f32 v14, v14, s12, v160
	v_fma_f32 v15, v15, s12, v161
	v_cvt_pk_bf16_f32 v150, v6, v7
	v_cvt_pk_bf16_f32 v151, v8, v9
	v_cvt_pk_bf16_f32 v152, v12, v13
	v_cvt_pk_bf16_f32 v153, v14, v15
	v_lshlrev_b32_e32 v154, 16, v124
	v_and_b32_e32 v155, 0xffff0000, v124
	v_lshlrev_b32_e32 v156, 16, v125
	v_and_b32_e32 v157, 0xffff0000, v125
	v_lshlrev_b32_e32 v158, 16, v126
	v_and_b32_e32 v159, 0xffff0000, v126
	v_lshlrev_b32_e32 v160, 16, v127
	v_and_b32_e32 v161, 0xffff0000, v127
	global_store_dwordx4 v[148:149], v[150:153], off offset:2560
	v_lshl_add_u64 v[148:149], v[148:149], 0, s[10:11]
	v_fma_f32 v6, v6, s13, v154
	v_fma_f32 v7, v7, s13, v155
	v_fma_f32 v8, v8, s13, v156
	v_fma_f32 v9, v9, s13, v157
	v_fma_f32 v12, v12, s13, v158
	v_fma_f32 v13, v13, s13, v159
	v_fma_f32 v14, v14, s13, v160
	v_fma_f32 v15, v15, s13, v161
	v_cvt_pk_bf16_f32 v150, v6, v7
	v_cvt_pk_bf16_f32 v151, v8, v9
	v_cvt_pk_bf16_f32 v152, v12, v13
	v_cvt_pk_bf16_f32 v153, v14, v15
	v_lshlrev_b32_e32 v154, 16, v128
	v_and_b32_e32 v155, 0xffff0000, v128
	v_lshlrev_b32_e32 v156, 16, v129
	v_and_b32_e32 v157, 0xffff0000, v129
	v_lshlrev_b32_e32 v158, 16, v130
	v_and_b32_e32 v159, 0xffff0000, v130
	v_lshlrev_b32_e32 v160, 16, v131
	v_and_b32_e32 v161, 0xffff0000, v131
	global_store_dwordx4 v[148:149], v[150:153], off offset:2560
	v_lshl_add_u64 v[148:149], v[148:149], 0, s[10:11]
	v_fma_f32 v6, v6, s35, v154
	v_fma_f32 v7, v7, s35, v155
	v_fma_f32 v8, v8, s35, v156
	v_fma_f32 v9, v9, s35, v157
	v_fma_f32 v12, v12, s35, v158
	v_fma_f32 v13, v13, s35, v159
	v_fma_f32 v14, v14, s35, v160
	v_fma_f32 v15, v15, s35, v161
	v_readlane_b32 s0, v17, 60
	v_readlane_b32 s12, v17, 61
	v_readlane_b32 s13, v17, 62
	v_readlane_b32 s35, v17, 63
	v_cvt_pk_bf16_f32 v150, v6, v7
	v_cvt_pk_bf16_f32 v151, v8, v9
	v_cvt_pk_bf16_f32 v152, v12, v13
	v_cvt_pk_bf16_f32 v153, v14, v15
	v_lshlrev_b32_e32 v154, 16, v132
	v_and_b32_e32 v155, 0xffff0000, v132
	v_lshlrev_b32_e32 v156, 16, v133
	v_and_b32_e32 v157, 0xffff0000, v133
	v_lshlrev_b32_e32 v158, 16, v134
	v_and_b32_e32 v159, 0xffff0000, v134
	v_lshlrev_b32_e32 v160, 16, v135
	v_and_b32_e32 v161, 0xffff0000, v135
	global_store_dwordx4 v[148:149], v[150:153], off offset:2560
	v_lshl_add_u64 v[148:149], v[148:149], 0, s[10:11]
	v_fma_f32 v6, v6, s0, v154
	v_fma_f32 v7, v7, s0, v155
	v_fma_f32 v8, v8, s0, v156
	v_fma_f32 v9, v9, s0, v157
	v_fma_f32 v12, v12, s0, v158
	v_fma_f32 v13, v13, s0, v159
	v_fma_f32 v14, v14, s0, v160
	v_fma_f32 v15, v15, s0, v161
	v_cvt_pk_bf16_f32 v150, v6, v7
	v_cvt_pk_bf16_f32 v151, v8, v9
	v_cvt_pk_bf16_f32 v152, v12, v13
	v_cvt_pk_bf16_f32 v153, v14, v15
	v_lshlrev_b32_e32 v154, 16, v136
	v_and_b32_e32 v155, 0xffff0000, v136
	v_lshlrev_b32_e32 v156, 16, v137
	v_and_b32_e32 v157, 0xffff0000, v137
	v_lshlrev_b32_e32 v158, 16, v138
	v_and_b32_e32 v159, 0xffff0000, v138
	v_lshlrev_b32_e32 v160, 16, v139
	v_and_b32_e32 v161, 0xffff0000, v139
	global_store_dwordx4 v[148:149], v[150:153], off offset:2560
	v_lshl_add_u64 v[148:149], v[148:149], 0, s[10:11]
	v_fma_f32 v6, v6, s12, v154
	v_fma_f32 v7, v7, s12, v155
	v_fma_f32 v8, v8, s12, v156
	v_fma_f32 v9, v9, s12, v157
	v_fma_f32 v12, v12, s12, v158
	v_fma_f32 v13, v13, s12, v159
	v_fma_f32 v14, v14, s12, v160
	v_fma_f32 v15, v15, s12, v161
	v_cvt_pk_bf16_f32 v150, v6, v7
	v_cvt_pk_bf16_f32 v151, v8, v9
	v_cvt_pk_bf16_f32 v152, v12, v13
	v_cvt_pk_bf16_f32 v153, v14, v15
	v_lshlrev_b32_e32 v154, 16, v140
	v_and_b32_e32 v155, 0xffff0000, v140
	v_lshlrev_b32_e32 v156, 16, v141
	v_and_b32_e32 v157, 0xffff0000, v141
	v_lshlrev_b32_e32 v158, 16, v142
	v_and_b32_e32 v159, 0xffff0000, v142
	v_lshlrev_b32_e32 v160, 16, v143
	v_and_b32_e32 v161, 0xffff0000, v143
	global_store_dwordx4 v[148:149], v[150:153], off offset:2560
	v_lshl_add_u64 v[148:149], v[148:149], 0, s[10:11]
	v_fma_f32 v6, v6, s13, v154
	v_fma_f32 v7, v7, s13, v155
	v_fma_f32 v8, v8, s13, v156
	v_fma_f32 v9, v9, s13, v157
	v_fma_f32 v12, v12, s13, v158
	v_fma_f32 v13, v13, s13, v159
	v_fma_f32 v14, v14, s13, v160
	v_fma_f32 v15, v15, s13, v161
	v_cvt_pk_bf16_f32 v150, v6, v7
	v_cvt_pk_bf16_f32 v151, v8, v9
	v_cvt_pk_bf16_f32 v152, v12, v13
	v_cvt_pk_bf16_f32 v153, v14, v15
	v_lshlrev_b32_e32 v154, 16, v144
	v_and_b32_e32 v155, 0xffff0000, v144
	v_lshlrev_b32_e32 v156, 16, v145
	v_and_b32_e32 v157, 0xffff0000, v145
	v_lshlrev_b32_e32 v158, 16, v146
	v_and_b32_e32 v159, 0xffff0000, v146
	v_lshlrev_b32_e32 v160, 16, v147
	v_and_b32_e32 v161, 0xffff0000, v147
	global_store_dwordx4 v[148:149], v[150:153], off offset:2560
	v_lshl_add_u64 v[148:149], v[148:149], 0, s[10:11]
	v_fma_f32 v6, v6, s35, v154
	v_fma_f32 v7, v7, s35, v155
	v_fma_f32 v8, v8, s35, v156
	v_fma_f32 v9, v9, s35, v157
	v_fma_f32 v12, v12, s35, v158
	v_fma_f32 v13, v13, s35, v159
	v_fma_f32 v14, v14, s35, v160
	v_fma_f32 v15, v15, s35, v161
	s_cmp_eq_u32 s34, 0
	s_movk_i32 s0, 0x80
	s_cselect_b64 s[10:11], -1, 0
	v_cmp_gt_i32_e32 vcc, s0, v2
	s_and_b64 s[12:13], s[10:11], vcc
	s_and_saveexec_b64 s[10:11], s[12:13]
	s_cbranch_execz .LBB0_418
	v_readlane_b32 s36, v252, 8
	s_lshl_b64 s[6:7], s[6:7], 15
	s_lshl_b64 s[8:9], s[8:9], 9
	v_readlane_b32 s50, v252, 22
	v_ashrrev_i32_e32 v3, 31, v2
	v_readlane_b32 s51, v252, 23
	s_add_u32 s8, s50, s8
	s_addc_u32 s9, s51, s9
	v_lshlrev_b64 v[2:3], 2, v[2:3]
	v_lshl_add_u64 v[4:5], s[8:9], 0, v[2:3]
	global_load_dword v0, v[4:5], off
	v_lshl_add_u64 v[2:3], s[6:7], 0, v[2:3]
	s_mov_b32 s6, 64
	v_readlane_b32 s37, v252, 9
	v_readlane_b32 s38, v252, 10
	v_readlane_b32 s39, v252, 11
	v_readlane_b32 s40, v252, 12
	v_readlane_b32 s41, v252, 13
	v_readlane_b32 s42, v252, 14
	v_readlane_b32 s43, v252, 15
	v_readlane_b32 s44, v252, 16
	v_readlane_b32 s45, v252, 17
	v_readlane_b32 s46, v252, 18
	v_readlane_b32 s47, v252, 19
	v_readlane_b32 s48, v252, 20
	v_readlane_b32 s49, v252, 21
.Lscan_dn:
	v_lshl_add_u64 v[4:5], s[92:93], 0, v[2:3]
	s_mov_b32 s8, 0x2000
	s_mov_b32 s9, 0
	v_add_co_u32_e32 v6, vcc, 0x1d6b1a00, v4
	s_nop 1
	v_addc_co_u32_e32 v7, vcc, 0, v5, vcc
	v_mov_b32_e32 v8, v6
	v_mov_b32_e32 v9, v7
	global_load_dword v20, v[6:7], off offset:-4096
	global_load_dword v21, v[6:7], off offset:-3584
	global_load_dword v22, v[6:7], off offset:-3072
	global_load_dword v23, v[6:7], off offset:-2560
	global_load_dword v24, v[6:7], off offset:-2048
	global_load_dword v25, v[6:7], off offset:-1536
	global_load_dword v26, v[6:7], off offset:-1024
	global_load_dword v27, v[6:7], off offset:-512
	global_load_dword v28, v[6:7], off offset:0
	global_load_dword v29, v[6:7], off offset:512
	global_load_dword v30, v[6:7], off offset:1024
	global_load_dword v31, v[6:7], off offset:1536
	global_load_dword v32, v[6:7], off offset:2048
	global_load_dword v33, v[6:7], off offset:2560
	global_load_dword v34, v[6:7], off offset:3072
	global_load_dword v35, v[6:7], off offset:3584
	v_lshl_add_u64 v[6:7], v[6:7], 0, s[8:9]
	global_load_dword v36, v[6:7], off offset:-4096
	global_load_dword v37, v[6:7], off offset:-3584
	global_load_dword v38, v[6:7], off offset:-3072
	global_load_dword v39, v[6:7], off offset:-2560
	global_load_dword v40, v[6:7], off offset:-2048
	global_load_dword v41, v[6:7], off offset:-1536
	global_load_dword v42, v[6:7], off offset:-1024
	global_load_dword v43, v[6:7], off offset:-512
	global_load_dword v44, v[6:7], off offset:0
	global_load_dword v45, v[6:7], off offset:512
	global_load_dword v46, v[6:7], off offset:1024
	global_load_dword v47, v[6:7], off offset:1536
	global_load_dword v48, v[6:7], off offset:2048
	global_load_dword v49, v[6:7], off offset:2560
	global_load_dword v50, v[6:7], off offset:3072
	global_load_dword v51, v[6:7], off offset:3584
	v_lshl_add_u64 v[6:7], v[6:7], 0, s[8:9]
	s_waitcnt vmcnt(0)
	v_readlane_b32 s0, v17, 0
	v_readlane_b32 s12, v17, 1
	v_readlane_b32 s13, v17, 2
	v_readlane_b32 s35, v17, 3
	s_nop 1
	global_store_dword v[8:9], v0, off offset:-4096
	v_fma_f32 v0, v0, s0, v20
	global_store_dword v[8:9], v0, off offset:-3584
	v_fma_f32 v0, v0, s12, v21
	global_store_dword v[8:9], v0, off offset:-3072
	v_fma_f32 v0, v0, s13, v22
	global_store_dword v[8:9], v0, off offset:-2560
	v_fma_f32 v0, v0, s35, v23
	v_readlane_b32 s0, v17, 4
	v_readlane_b32 s12, v17, 5
	v_readlane_b32 s13, v17, 6
	v_readlane_b32 s35, v17, 7
	s_nop 1
	global_store_dword v[8:9], v0, off offset:-2048
	v_fma_f32 v0, v0, s0, v24
	global_store_dword v[8:9], v0, off offset:-1536
	v_fma_f32 v0, v0, s12, v25
	global_store_dword v[8:9], v0, off offset:-1024
	v_fma_f32 v0, v0, s13, v26
	global_store_dword v[8:9], v0, off offset:-512
	v_fma_f32 v0, v0, s35, v27
	v_readlane_b32 s0, v17, 8
	v_readlane_b32 s12, v17, 9
	v_readlane_b32 s13, v17, 10
	v_readlane_b32 s35, v17, 11
	s_nop 1
	global_store_dword v[8:9], v0, off offset:0
	v_fma_f32 v0, v0, s0, v28
	global_store_dword v[8:9], v0, off offset:512
	v_fma_f32 v0, v0, s12, v29
	global_store_dword v[8:9], v0, off offset:1024
	v_fma_f32 v0, v0, s13, v30
	global_store_dword v[8:9], v0, off offset:1536
	v_fma_f32 v0, v0, s35, v31
	v_readlane_b32 s0, v17, 12
	v_readlane_b32 s12, v17, 13
	v_readlane_b32 s13, v17, 14
	v_readlane_b32 s35, v17, 15
	s_nop 1
	global_store_dword v[8:9], v0, off offset:2048
	v_fma_f32 v0, v0, s0, v32
	global_store_dword v[8:9], v0, off offset:2560
	v_fma_f32 v0, v0, s12, v33
	global_store_dword v[8:9], v0, off offset:3072
	v_fma_f32 v0, v0, s13, v34
	global_store_dword v[8:9], v0, off offset:3584
	v_fma_f32 v0, v0, s35, v35
	v_lshl_add_u64 v[8:9], v[8:9], 0, s[8:9]
	v_readlane_b32 s0, v17, 16
	v_readlane_b32 s12, v17, 17
	v_readlane_b32 s13, v17, 18
	v_readlane_b32 s35, v17, 19
	s_nop 1
	global_store_dword v[8:9], v0, off offset:-4096
	v_fma_f32 v0, v0, s0, v36
	global_store_dword v[8:9], v0, off offset:-3584
	v_fma_f32 v0, v0, s12, v37
	global_store_dword v[8:9], v0, off offset:-3072
	v_fma_f32 v0, v0, s13, v38
	global_store_dword v[8:9], v0, off offset:-2560
	v_fma_f32 v0, v0, s35, v39
	v_readlane_b32 s0, v17, 20
	v_readlane_b32 s12, v17, 21
	v_readlane_b32 s13, v17, 22
	v_readlane_b32 s35, v17, 23
	s_nop 1
	global_store_dword v[8:9], v0, off offset:-2048
	v_fma_f32 v0, v0, s0, v40
	global_store_dword v[8:9], v0, off offset:-1536
	v_fma_f32 v0, v0, s12, v41
	global_store_dword v[8:9], v0, off offset:-1024
	v_fma_f32 v0, v0, s13, v42
	global_store_dword v[8:9], v0, off offset:-512
	v_fma_f32 v0, v0, s35, v43
	v_readlane_b32 s0, v17, 24
	v_readlane_b32 s12, v17, 25
	v_readlane_b32 s13, v17, 26
	v_readlane_b32 s35, v17, 27
	s_nop 1
	global_store_dword v[8:9], v0, off offset:0
	v_fma_f32 v0, v0, s0, v44
	global_store_dword v[8:9], v0, off offset:512
	v_fma_f32 v0, v0, s12, v45
	global_store_dword v[8:9], v0, off offset:1024
	v_fma_f32 v0, v0, s13, v46
	global_store_dword v[8:9], v0, off offset:1536
	v_fma_f32 v0, v0, s35, v47
	v_readlane_b32 s0, v17, 28
	v_readlane_b32 s12, v17, 29
	v_readlane_b32 s13, v17, 30
	v_readlane_b32 s35, v17, 31
	s_nop 1
	global_store_dword v[8:9], v0, off offset:2048
	v_fma_f32 v0, v0, s0, v48
	global_store_dword v[8:9], v0, off offset:2560
	v_fma_f32 v0, v0, s12, v49
	global_store_dword v[8:9], v0, off offset:3072
	v_fma_f32 v0, v0, s13, v50
	global_store_dword v[8:9], v0, off offset:3584
	v_fma_f32 v0, v0, s35, v51
	v_lshl_add_u64 v[8:9], v[8:9], 0, s[8:9]
	s_waitcnt vmcnt(8)
	global_load_dword v20, v[6:7], off offset:-4096
	global_load_dword v21, v[6:7], off offset:-3584
	global_load_dword v22, v[6:7], off offset:-3072
	global_load_dword v23, v[6:7], off offset:-2560
	global_load_dword v24, v[6:7], off offset:-2048
	global_load_dword v25, v[6:7], off offset:-1536
	global_load_dword v26, v[6:7], off offset:-1024
	global_load_dword v27, v[6:7], off offset:-512
	global_load_dword v28, v[6:7], off offset:0
	global_load_dword v29, v[6:7], off offset:512
	global_load_dword v30, v[6:7], off offset:1024
	global_load_dword v31, v[6:7], off offset:1536
	global_load_dword v32, v[6:7], off offset:2048
	global_load_dword v33, v[6:7], off offset:2560
	global_load_dword v34, v[6:7], off offset:3072
	global_load_dword v35, v[6:7], off offset:3584
	v_lshl_add_u64 v[6:7], v[6:7], 0, s[8:9]
	global_load_dword v36, v[6:7], off offset:-4096
	global_load_dword v37, v[6:7], off offset:-3584
	global_load_dword v38, v[6:7], off offset:-3072
	global_load_dword v39, v[6:7], off offset:-2560
	global_load_dword v40, v[6:7], off offset:-2048
	global_load_dword v41, v[6:7], off offset:-1536
	global_load_dword v42, v[6:7], off offset:-1024
	global_load_dword v43, v[6:7], off offset:-512
	global_load_dword v44, v[6:7], off offset:0
	global_load_dword v45, v[6:7], off offset:512
	global_load_dword v46, v[6:7], off offset:1024
	global_load_dword v47, v[6:7], off offset:1536
	global_load_dword v48, v[6:7], off offset:2048
	global_load_dword v49, v[6:7], off offset:2560
	global_load_dword v50, v[6:7], off offset:3072
	global_load_dword v51, v[6:7], off offset:3584
	v_lshl_add_u64 v[6:7], v[6:7], 0, s[8:9]
	s_waitcnt vmcnt(0)
	v_readlane_b32 s0, v17, 32
	v_readlane_b32 s12, v17, 33
	v_readlane_b32 s13, v17, 34
	v_readlane_b32 s35, v17, 35
	s_nop 1
	global_store_dword v[8:9], v0, off offset:-4096
	v_fma_f32 v0, v0, s0, v20
	global_store_dword v[8:9], v0, off offset:-3584
	v_fma_f32 v0, v0, s12, v21
	global_store_dword v[8:9], v0, off offset:-3072
	v_fma_f32 v0, v0, s13, v22
	global_store_dword v[8:9], v0, off offset:-2560
	v_fma_f32 v0, v0, s35, v23
	v_readlane_b32 s0, v17, 36
	v_readlane_b32 s12, v17, 37
	v_readlane_b32 s13, v17, 38
	v_readlane_b32 s35, v17, 39
	s_nop 1
	global_store_dword v[8:9], v0, off offset:-2048
	v_fma_f32 v0, v0, s0, v24
	global_store_dword v[8:9], v0, off offset:-1536
	v_fma_f32 v0, v0, s12, v25
	global_store_dword v[8:9], v0, off offset:-1024
	v_fma_f32 v0, v0, s13, v26
	global_store_dword v[8:9], v0, off offset:-512
	v_fma_f32 v0, v0, s35, v27
	v_readlane_b32 s0, v17, 40
	v_readlane_b32 s12, v17, 41
	v_readlane_b32 s13, v17, 42
	v_readlane_b32 s35, v17, 43
	s_nop 1
	global_store_dword v[8:9], v0, off offset:0
	v_fma_f32 v0, v0, s0, v28
	global_store_dword v[8:9], v0, off offset:512
	v_fma_f32 v0, v0, s12, v29
	global_store_dword v[8:9], v0, off offset:1024
	v_fma_f32 v0, v0, s13, v30
	global_store_dword v[8:9], v0, off offset:1536
	v_fma_f32 v0, v0, s35, v31
	v_readlane_b32 s0, v17, 44
	v_readlane_b32 s12, v17, 45
	v_readlane_b32 s13, v17, 46
	v_readlane_b32 s35, v17, 47
	s_nop 1
	global_store_dword v[8:9], v0, off offset:2048
	v_fma_f32 v0, v0, s0, v32
	global_store_dword v[8:9], v0, off offset:2560
	v_fma_f32 v0, v0, s12, v33
	global_store_dword v[8:9], v0, off offset:3072
	v_fma_f32 v0, v0, s13, v34
	global_store_dword v[8:9], v0, off offset:3584
	v_fma_f32 v0, v0, s35, v35
	v_lshl_add_u64 v[8:9], v[8:9], 0, s[8:9]
	v_readlane_b32 s0, v17, 48
	v_readlane_b32 s12, v17, 49
	v_readlane_b32 s13, v17, 50
	v_readlane_b32 s35, v17, 51
	s_nop 1
	global_store_dword v[8:9], v0, off offset:-4096
	v_fma_f32 v0, v0, s0, v36
	global_store_dword v[8:9], v0, off offset:-3584
	v_fma_f32 v0, v0, s12, v37
	global_store_dword v[8:9], v0, off offset:-3072
	v_fma_f32 v0, v0, s13, v38
	global_store_dword v[8:9], v0, off offset:-2560
	v_fma_f32 v0, v0, s35, v39
	v_readlane_b32 s0, v17, 52
	v_readlane_b32 s12, v17, 53
	v_readlane_b32 s13, v17, 54
	v_readlane_b32 s35, v17, 55
	s_nop 1
	global_store_dword v[8:9], v0, off offset:-2048
	v_fma_f32 v0, v0, s0, v40
	global_store_dword v[8:9], v0, off offset:-1536
	v_fma_f32 v0, v0, s12, v41
	global_store_dword v[8:9], v0, off offset:-1024
	v_fma_f32 v0, v0, s13, v42
	global_store_dword v[8:9], v0, off offset:-512
	v_fma_f32 v0, v0, s35, v43
	v_readlane_b32 s0, v17, 56
	v_readlane_b32 s12, v17, 57
	v_readlane_b32 s13, v17, 58
	v_readlane_b32 s35, v17, 59
	s_nop 1
	global_store_dword v[8:9], v0, off offset:0
	v_fma_f32 v0, v0, s0, v44
	global_store_dword v[8:9], v0, off offset:512
	v_fma_f32 v0, v0, s12, v45
	global_store_dword v[8:9], v0, off offset:1024
	v_fma_f32 v0, v0, s13, v46
	global_store_dword v[8:9], v0, off offset:1536
	v_fma_f32 v0, v0, s35, v47
	v_readlane_b32 s0, v17, 60
	v_readlane_b32 s12, v17, 61
	v_readlane_b32 s13, v17, 62
	v_readlane_b32 s35, v17, 63
	s_nop 1
	global_store_dword v[8:9], v0, off offset:2048
	v_fma_f32 v0, v0, s0, v48
	global_store_dword v[8:9], v0, off offset:2560
	v_fma_f32 v0, v0, s12, v49
	global_store_dword v[8:9], v0, off offset:3072
	v_fma_f32 v0, v0, s13, v50
	global_store_dword v[8:9], v0, off offset:3584
	v_fma_f32 v0, v0, s35, v51
	v_lshl_add_u64 v[8:9], v[8:9], 0, s[8:9]
	s_branch .LBB0_418

.LBB0_431:
	s_lshr_b32 s6, s79, 3
	s_and_b32 s8, s79, 56
	v_readlane_b32 s0, v252, 42
	s_and_b32 s7, s79, 7
	s_or_b32 s43, s8, s0
	s_and_b32 s40, s6, 56
	v_mov_b32_e32 v6, v171
	s_or_b32 s42, s40, s7
	s_lshl_b32 s6, s43, 19
	v_lshlrev_b32_e32 v2, 3, v6
	s_add_u32 s6, s98, s6
	v_ashrrev_i32_e32 v3, 31, v2
	s_addc_u32 s7, s99, 0
	v_lshlrev_b64 v[4:5], 1, v[2:3]
	v_lshl_add_u64 v[154:155], s[6:7], 0, v[4:5]
	s_lshl_b32 s6, s42, 18
	s_add_u32 s6, s92, s6
	s_addc_u32 s7, s93, 0
	v_lshrrev_b32_e32 v3, 2, v6
	v_and_b32_e32 v0, 24, v2
	v_lshl_add_u64 v[156:157], s[6:7], 0, v[4:5]
	v_mad_u64_u32 v[158:159], s[6:7], v3, 40, v[0:1]
	s_movk_i32 s0, 0x50
	v_and_b32_e32 v2, 0x30, v6
	v_xor_b32_e32 v154, v154, v2
	v_xor_b32_e32 v156, v156, v2
	v_and_b32_e32 v130, 31, v6
	v_lshlrev_b32_e32 v130, 6, v130
	v_lshrrev_b32_e32 v131, 2, v6
	v_and_b32_e32 v131, 3, v131
	v_bfe_u32 v133, v6, 5, 1
	v_xor_b32_e32 v131, v131, v133
	v_lshl_or_b32 v130, v131, 4, v130
	v_lshrrev_b32_e32 v131, 7, v6
	v_lshl_or_b32 v132, v131, 13, v130
	v_bfe_u32 v131, v6, 6, 1
	v_lshl_or_b32 v133, v131, 12, v130
	v_or_b32_e32 v133, 0x4000, v133
	v_xor_b32_e32 v134, 32, v132
	v_xor_b32_e32 v135, 32, v133
	v_lshrrev_b32_e32 v131, 6, v6
	s_nop 1
	v_readfirstlane_b32 s72, v131
	s_nop 3
	s_lshl_b32 s72, s72, 10
	s_waitcnt lgkmcnt(0)
	s_barrier
	s_mov_b32 s14, 0
	s_lshl_b64 s[12:13], s[14:15], 14
	v_lshl_add_u64 v[244:245], v[154:155], 0, s[12:13]
	s_add_u32 s12, s12, 0x1000
	s_addc_u32 s13, s13, 0
	v_lshl_add_u64 v[246:247], v[154:155], 0, s[12:13]
	s_add_u32 s12, s12, 0x1000
	s_addc_u32 s13, s13, 0
	v_lshl_add_u64 v[248:249], v[154:155], 0, s[12:13]
	s_add_u32 s12, s12, 0x1000
	s_addc_u32 s13, s13, 0
	v_lshl_add_u64 v[140:141], v[154:155], 0, s[12:13]
	s_lshl_b64 s[12:13], s[14:15], 13
	v_lshl_add_u64 v[142:143], v[156:157], 0, s[12:13]
	s_add_u32 s12, s12, 0x1000
	s_addc_u32 s13, s13, 0
	v_lshl_add_u64 v[144:145], v[156:157], 0, s[12:13]
	s_add_u32 m0, s72, 0x0
	s_nop 0
	global_load_lds_dwordx4 v[244:245], off
	s_add_u32 m0, m0, 0x1000
	s_nop 0
	global_load_lds_dwordx4 v[246:247], off
	s_add_u32 m0, m0, 0x1000
	s_nop 0
	global_load_lds_dwordx4 v[248:249], off
	s_add_u32 m0, m0, 0x1000
	s_nop 0
	global_load_lds_dwordx4 v[140:141], off
	s_add_u32 m0, m0, 0x1000
	s_nop 0
	global_load_lds_dwordx4 v[142:143], off
	s_add_u32 m0, m0, 0x1000
	s_nop 0
	global_load_lds_dwordx4 v[144:145], off
	s_mov_b32 s14, 1
	s_lshl_b64 s[12:13], s[14:15], 14
	v_lshl_add_u64 v[244:245], v[154:155], 0, s[12:13]
	s_add_u32 s12, s12, 0x1000
	s_addc_u32 s13, s13, 0
	v_lshl_add_u64 v[246:247], v[154:155], 0, s[12:13]
	s_add_u32 s12, s12, 0x1000
	s_addc_u32 s13, s13, 0
	v_lshl_add_u64 v[248:249], v[154:155], 0, s[12:13]
	s_add_u32 s12, s12, 0x1000
	s_addc_u32 s13, s13, 0
	v_lshl_add_u64 v[140:141], v[154:155], 0, s[12:13]
	s_lshl_b64 s[12:13], s[14:15], 13
	v_lshl_add_u64 v[142:143], v[156:157], 0, s[12:13]
	s_add_u32 s12, s12, 0x1000
	s_addc_u32 s13, s13, 0
	v_lshl_add_u64 v[144:145], v[156:157], 0, s[12:13]
	s_add_u32 m0, s72, 0x6000
	s_nop 0
	global_load_lds_dwordx4 v[244:245], off
	s_add_u32 m0, m0, 0x1000
	s_nop 0
	global_load_lds_dwordx4 v[246:247], off
	s_add_u32 m0, m0, 0x1000
	s_nop 0
	global_load_lds_dwordx4 v[248:249], off
	s_add_u32 m0, m0, 0x1000
	s_nop 0
	global_load_lds_dwordx4 v[140:141], off
	s_add_u32 m0, m0, 0x1000
	s_nop 0
	global_load_lds_dwordx4 v[142:143], off
	s_add_u32 m0, m0, 0x1000
	s_nop 0
	global_load_lds_dwordx4 v[144:145], off
	s_mov_b32 s14, 2
	s_lshl_b64 s[12:13], s[14:15], 14
	v_lshl_add_u64 v[244:245], v[154:155], 0, s[12:13]
	s_add_u32 s12, s12, 0x1000
	s_addc_u32 s13, s13, 0
	v_lshl_add_u64 v[246:247], v[154:155], 0, s[12:13]
	s_add_u32 s12, s12, 0x1000
	s_addc_u32 s13, s13, 0
	v_lshl_add_u64 v[248:249], v[154:155], 0, s[12:13]
	s_add_u32 s12, s12, 0x1000
	s_addc_u32 s13, s13, 0
	v_lshl_add_u64 v[140:141], v[154:155], 0, s[12:13]
	s_lshl_b64 s[12:13], s[14:15], 13
	v_lshl_add_u64 v[142:143], v[156:157], 0, s[12:13]
	s_add_u32 s12, s12, 0x1000
	s_addc_u32 s13, s13, 0
	v_lshl_add_u64 v[144:145], v[156:157], 0, s[12:13]
	s_add_u32 m0, s72, 0xc000
	s_nop 0
	global_load_lds_dwordx4 v[244:245], off
	s_add_u32 m0, m0, 0x1000
	s_nop 0
	global_load_lds_dwordx4 v[246:247], off
	s_add_u32 m0, m0, 0x1000
	s_nop 0
	global_load_lds_dwordx4 v[248:249], off
	s_add_u32 m0, m0, 0x1000
	s_nop 0
	global_load_lds_dwordx4 v[140:141], off
	s_add_u32 m0, m0, 0x1000
	s_nop 0
	global_load_lds_dwordx4 v[142:143], off
	s_add_u32 m0, m0, 0x1000
	s_nop 0
	global_load_lds_dwordx4 v[144:145], off
	v_and_b32_e32 v2, 0xfffff9f, v6
	v_mul_lo_u32 v160, v2, s0
	v_or_b32_e32 v2, 0x60, v6
	v_lshrrev_b32_e32 v0, 1, v6
	v_and_b32_e32 v3, 0x5f, v6
	v_mul_lo_u32 v161, v2, s0
	v_mov_b32_e32 v2, 0
	s_mov_b32 s6, 0
	v_and_b32_e32 v0, 16, v0
	v_mul_u32_u24_e32 v159, 0x50, v3
	v_mov_b32_e32 v3, v2
	v_mov_b32_e32 v4, v2
	v_mov_b32_e32 v5, v2
	v_mov_b32_e32 v6, v2
	v_mov_b32_e32 v7, v2
	v_mov_b32_e32 v8, v2
	v_mov_b32_e32 v9, v2
	v_mov_b32_e32 v10, v2
	v_mov_b32_e32 v11, v2
	v_mov_b32_e32 v12, v2
	v_mov_b32_e32 v13, v2
	v_mov_b32_e32 v14, v2
	v_mov_b32_e32 v15, v2
	v_mov_b32_e32 v16, v2
	v_mov_b32_e32 v17, v2
	v_mov_b32_e32 v18, v2
	v_mov_b32_e32 v19, v2
	v_mov_b32_e32 v20, v2
	v_mov_b32_e32 v21, v2
	v_mov_b32_e32 v22, v2
	v_mov_b32_e32 v23, v2
	v_mov_b32_e32 v24, v2
	v_mov_b32_e32 v25, v2
	v_mov_b32_e32 v26, v2
	v_mov_b32_e32 v27, v2
	v_mov_b32_e32 v28, v2
	v_mov_b32_e32 v29, v2
	v_mov_b32_e32 v30, v2
	v_mov_b32_e32 v31, v2
	v_mov_b32_e32 v32, v2
	v_mov_b32_e32 v33, v2
	v_mov_b32_e32 v34, v2
	v_mov_b32_e32 v35, v2
	v_mov_b32_e32 v36, v2
	v_mov_b32_e32 v37, v2
	v_mov_b32_e32 v38, v2
	v_mov_b32_e32 v39, v2
	v_mov_b32_e32 v40, v2
	v_mov_b32_e32 v41, v2
	v_mov_b32_e32 v42, v2
	v_mov_b32_e32 v43, v2
	v_mov_b32_e32 v44, v2
	v_mov_b32_e32 v45, v2
	v_mov_b32_e32 v46, v2
	v_mov_b32_e32 v47, v2
	v_mov_b32_e32 v48, v2
	v_mov_b32_e32 v49, v2
	v_mov_b32_e32 v50, v2
	v_mov_b32_e32 v51, v2
	v_mov_b32_e32 v52, v2
	v_mov_b32_e32 v53, v2
	v_mov_b32_e32 v54, v2
	v_mov_b32_e32 v55, v2
	v_mov_b32_e32 v56, v2
	v_mov_b32_e32 v57, v2
	v_mov_b32_e32 v58, v2
	v_mov_b32_e32 v59, v2
	v_mov_b32_e32 v60, v2
	v_mov_b32_e32 v61, v2
	v_mov_b32_e32 v62, v2
	v_mov_b32_e32 v63, v2
	v_mov_b32_e32 v64, v2
	v_mov_b32_e32 v65, v2
	v_mov_b32_e32 v66, v2
	v_mov_b32_e32 v67, v2
	v_mov_b32_e32 v68, v2
	v_mov_b32_e32 v69, v2
	v_mov_b32_e32 v70, v2
	v_mov_b32_e32 v71, v2
	v_mov_b32_e32 v72, v2
	v_mov_b32_e32 v73, v2
	v_mov_b32_e32 v74, v2
	v_mov_b32_e32 v75, v2
	v_mov_b32_e32 v76, v2
	v_mov_b32_e32 v77, v2
	v_mov_b32_e32 v78, v2
	v_mov_b32_e32 v79, v2
	v_mov_b32_e32 v80, v2
	v_mov_b32_e32 v81, v2
	s_waitcnt vmcnt(17)
	v_mov_b32_e32 v82, v2
	v_mov_b32_e32 v83, v2
	v_mov_b32_e32 v84, v2
	v_mov_b32_e32 v85, v2
	s_waitcnt vmcnt(16)
	v_mov_b32_e32 v86, v2
	v_mov_b32_e32 v87, v2
	v_mov_b32_e32 v88, v2
	v_mov_b32_e32 v89, v2
	s_waitcnt vmcnt(15)
	v_mov_b32_e32 v90, v2
	v_mov_b32_e32 v91, v2
	v_mov_b32_e32 v92, v2
	v_mov_b32_e32 v93, v2
	s_waitcnt vmcnt(14)
	v_mov_b32_e32 v94, v2
	v_mov_b32_e32 v95, v2
	v_mov_b32_e32 v96, v2
	v_mov_b32_e32 v97, v2
	v_mov_b32_e32 v98, v2
	v_mov_b32_e32 v99, v2
	v_mov_b32_e32 v100, v2
	v_mov_b32_e32 v101, v2
	v_mov_b32_e32 v102, v2
	v_mov_b32_e32 v103, v2
	v_mov_b32_e32 v104, v2
	v_mov_b32_e32 v105, v2
	v_mov_b32_e32 v106, v2
	v_mov_b32_e32 v107, v2
	v_mov_b32_e32 v108, v2
	v_mov_b32_e32 v109, v2
	v_mov_b32_e32 v110, v2
	v_mov_b32_e32 v111, v2
	v_mov_b32_e32 v112, v2
	v_mov_b32_e32 v113, v2
	v_mov_b32_e32 v114, v2
	v_mov_b32_e32 v115, v2
	v_mov_b32_e32 v116, v2
	v_mov_b32_e32 v117, v2
	v_mov_b32_e32 v118, v2
	v_mov_b32_e32 v119, v2
	v_mov_b32_e32 v120, v2
	v_mov_b32_e32 v121, v2
	v_mov_b32_e32 v122, v2
	v_mov_b32_e32 v123, v2
	v_mov_b32_e32 v124, v2
	v_mov_b32_e32 v125, v2
	v_mov_b32_e32 v126, v2
	v_mov_b32_e32 v127, v2
	v_mov_b32_e32 v128, v2
	v_mov_b32_e32 v129, v2
	s_waitcnt lgkmcnt(0)
	s_mov_b32 s6, 0
	s_mov_b32 s7, 0
	v_mov_b32_e32 v138, v132
	v_mov_b32_e32 v139, v133
	s_waitcnt vmcnt(12)
	s_barrier
	ds_read_b128 v[162:165], v138 offset:0
	ds_read_b128 v[228:231], v139 offset:0
	ds_read_b128 v[236:239], v139 offset:2048
	ds_read_b128 v[204:207], v138 offset:2048
	ds_read_b128 v[212:215], v138 offset:4096
	ds_read_b128 v[220:223], v138 offset:6144
.Lg432_loop:
	v_add_u32_e32 v136, s7, v134
	v_add_u32_e32 v137, s7, v135
	ds_read_b128 v[166:169], v136 offset:0
	ds_read_b128 v[232:235], v137 offset:0
	ds_read_b128 v[240:243], v137 offset:2048
	ds_read_b128 v[208:211], v136 offset:2048
	ds_read_b128 v[216:219], v136 offset:4096
	ds_read_b128 v[224:227], v136 offset:6144
	s_add_i32 s6, s6, 1
	s_add_u32 s73, s7, 0x6000
	s_cmp_lt_u32 s73, 0x12000
	s_cselect_b32 s73, s73, 0
	v_add_u32_e32 v138, s73, v132
	v_add_u32_e32 v139, s73, v133
	s_waitcnt lgkmcnt(6)
	v_mfma_f32_32x32x16_bf16 v[114:129], v[162:165], v[228:231], v[114:129]
	s_add_i32 s14, s6, 2
	s_lshl_b64 s[12:13], s[14:15], 14
	v_lshl_add_u64 v[244:245], v[154:155], 0, s[12:13]
	v_mfma_f32_32x32x16_bf16 v[98:113], v[162:165], v[236:239], v[98:113]
	s_add_u32 s12, s12, 0x1000
	s_addc_u32 s13, s13, 0
	v_lshl_add_u64 v[246:247], v[154:155], 0, s[12:13]
	v_mfma_f32_32x32x16_bf16 v[82:97], v[204:207], v[228:231], v[82:97]
	s_add_u32 s12, s12, 0x1000
	s_addc_u32 s13, s13, 0
	v_lshl_add_u64 v[248:249], v[154:155], 0, s[12:13]
	v_mfma_f32_32x32x16_bf16 v[66:81], v[204:207], v[236:239], v[66:81]
	s_add_u32 s12, s12, 0x1000
	s_addc_u32 s13, s13, 0
	v_lshl_add_u64 v[140:141], v[154:155], 0, s[12:13]
	v_mfma_f32_32x32x16_bf16 v[50:65], v[212:215], v[228:231], v[50:65]
	s_lshl_b64 s[12:13], s[14:15], 13
	v_lshl_add_u64 v[142:143], v[156:157], 0, s[12:13]
	v_mfma_f32_32x32x16_bf16 v[34:49], v[212:215], v[236:239], v[34:49]
	s_add_u32 s12, s12, 0x1000
	s_addc_u32 s13, s13, 0
	v_lshl_add_u64 v[144:145], v[156:157], 0, s[12:13]
	v_mfma_f32_32x32x16_bf16 v[18:33], v[220:223], v[228:231], v[18:33]
	v_mfma_f32_32x32x16_bf16 v[2:17], v[220:223], v[236:239], v[2:17]
	s_waitcnt vmcnt(6) lgkmcnt(0)
	s_barrier
	s_add_u32 m0, s7, s72
	v_mfma_f32_32x32x16_bf16 v[114:129], v[166:169], v[232:235], v[114:129]
	global_load_lds_dwordx4 v[244:245], off
	ds_read_b128 v[162:165], v138 offset:0
	ds_read_b128 v[228:231], v139 offset:0
	s_add_u32 m0, m0, 0x1000
	v_mfma_f32_32x32x16_bf16 v[98:113], v[166:169], v[240:243], v[98:113]
	global_load_lds_dwordx4 v[246:247], off
	ds_read_b128 v[236:239], v139 offset:2048
	ds_read_b128 v[204:207], v138 offset:2048
	s_add_u32 m0, m0, 0x1000
	v_mfma_f32_32x32x16_bf16 v[82:97], v[208:211], v[232:235], v[82:97]
	global_load_lds_dwordx4 v[248:249], off
	ds_read_b128 v[212:215], v138 offset:4096
	ds_read_b128 v[220:223], v138 offset:6144
	s_add_u32 m0, m0, 0x1000
	v_mfma_f32_32x32x16_bf16 v[66:81], v[208:211], v[240:243], v[66:81]
	global_load_lds_dwordx4 v[140:141], off
	s_add_u32 m0, m0, 0x1000
	v_mfma_f32_32x32x16_bf16 v[50:65], v[216:219], v[232:235], v[50:65]
	global_load_lds_dwordx4 v[142:143], off
	s_add_u32 m0, m0, 0x1000
	v_mfma_f32_32x32x16_bf16 v[34:49], v[216:219], v[240:243], v[34:49]
	global_load_lds_dwordx4 v[144:145], off
	v_mfma_f32_32x32x16_bf16 v[18:33], v[224:227], v[232:235], v[18:33]
	v_mfma_f32_32x32x16_bf16 v[2:17], v[224:227], v[240:243], v[2:17]
	s_mov_b32 s7, s73
	s_cmp_lg_u32 s6, 29
	s_cbranch_scc1 .Lg432_loop
	v_add_u32_e32 v136, s7, v134
	v_add_u32_e32 v137, s7, v135
	ds_read_b128 v[166:169], v136 offset:0
	ds_read_b128 v[232:235], v137 offset:0
	ds_read_b128 v[240:243], v137 offset:2048
	ds_read_b128 v[208:211], v136 offset:2048
	ds_read_b128 v[216:219], v136 offset:4096
	ds_read_b128 v[224:227], v136 offset:6144
	s_add_i32 s6, s6, 1
	s_add_u32 s73, s7, 0x6000
	s_cmp_lt_u32 s73, 0x12000
	s_cselect_b32 s73, s73, 0
	v_add_u32_e32 v138, s73, v132
	v_add_u32_e32 v139, s73, v133
	s_waitcnt lgkmcnt(6)
	v_mfma_f32_32x32x16_bf16 v[114:129], v[162:165], v[228:231], v[114:129]
	v_mfma_f32_32x32x16_bf16 v[98:113], v[162:165], v[236:239], v[98:113]
	v_mfma_f32_32x32x16_bf16 v[82:97], v[204:207], v[228:231], v[82:97]
	v_mfma_f32_32x32x16_bf16 v[66:81], v[204:207], v[236:239], v[66:81]
	v_mfma_f32_32x32x16_bf16 v[50:65], v[212:215], v[228:231], v[50:65]
	v_mfma_f32_32x32x16_bf16 v[34:49], v[212:215], v[236:239], v[34:49]
	v_mfma_f32_32x32x16_bf16 v[18:33], v[220:223], v[228:231], v[18:33]
	v_mfma_f32_32x32x16_bf16 v[2:17], v[220:223], v[236:239], v[2:17]
	s_waitcnt vmcnt(6) lgkmcnt(0)
	s_barrier
	v_mfma_f32_32x32x16_bf16 v[114:129], v[166:169], v[232:235], v[114:129]
	ds_read_b128 v[162:165], v138 offset:0
	ds_read_b128 v[228:231], v139 offset:0
	v_mfma_f32_32x32x16_bf16 v[98:113], v[166:169], v[240:243], v[98:113]
	ds_read_b128 v[236:239], v139 offset:2048
	ds_read_b128 v[204:207], v138 offset:2048
	v_mfma_f32_32x32x16_bf16 v[82:97], v[208:211], v[232:235], v[82:97]
	ds_read_b128 v[212:215], v138 offset:4096
	ds_read_b128 v[220:223], v138 offset:6144
	v_mfma_f32_32x32x16_bf16 v[66:81], v[208:211], v[240:243], v[66:81]
	v_mfma_f32_32x32x16_bf16 v[50:65], v[216:219], v[232:235], v[50:65]
	v_mfma_f32_32x32x16_bf16 v[34:49], v[216:219], v[240:243], v[34:49]
	v_mfma_f32_32x32x16_bf16 v[18:33], v[224:227], v[232:235], v[18:33]
	v_mfma_f32_32x32x16_bf16 v[2:17], v[224:227], v[240:243], v[2:17]
	s_mov_b32 s7, s73
	v_add_u32_e32 v136, s7, v134
	v_add_u32_e32 v137, s7, v135
	ds_read_b128 v[166:169], v136 offset:0
	ds_read_b128 v[232:235], v137 offset:0
	ds_read_b128 v[240:243], v137 offset:2048
	ds_read_b128 v[208:211], v136 offset:2048
	ds_read_b128 v[216:219], v136 offset:4096
	ds_read_b128 v[224:227], v136 offset:6144
	s_add_i32 s6, s6, 1
	s_add_u32 s73, s7, 0x6000
	s_cmp_lt_u32 s73, 0x12000
	s_cselect_b32 s73, s73, 0
	v_add_u32_e32 v138, s73, v132
	v_add_u32_e32 v139, s73, v133
	s_waitcnt lgkmcnt(6)
	v_mfma_f32_32x32x16_bf16 v[114:129], v[162:165], v[228:231], v[114:129]
	v_mfma_f32_32x32x16_bf16 v[98:113], v[162:165], v[236:239], v[98:113]
	v_mfma_f32_32x32x16_bf16 v[82:97], v[204:207], v[228:231], v[82:97]
	v_mfma_f32_32x32x16_bf16 v[66:81], v[204:207], v[236:239], v[66:81]
	v_mfma_f32_32x32x16_bf16 v[50:65], v[212:215], v[228:231], v[50:65]
	v_mfma_f32_32x32x16_bf16 v[34:49], v[212:215], v[236:239], v[34:49]
	v_mfma_f32_32x32x16_bf16 v[18:33], v[220:223], v[228:231], v[18:33]
	v_mfma_f32_32x32x16_bf16 v[2:17], v[220:223], v[236:239], v[2:17]
	s_waitcnt vmcnt(0) lgkmcnt(0)
	s_barrier
	v_mfma_f32_32x32x16_bf16 v[114:129], v[166:169], v[232:235], v[114:129]
	ds_read_b128 v[162:165], v138 offset:0
	ds_read_b128 v[228:231], v139 offset:0
	v_mfma_f32_32x32x16_bf16 v[98:113], v[166:169], v[240:243], v[98:113]
	ds_read_b128 v[236:239], v139 offset:2048
	ds_read_b128 v[204:207], v138 offset:2048
	v_mfma_f32_32x32x16_bf16 v[82:97], v[208:211], v[232:235], v[82:97]
	ds_read_b128 v[212:215], v138 offset:4096
	ds_read_b128 v[220:223], v138 offset:6144
	v_mfma_f32_32x32x16_bf16 v[66:81], v[208:211], v[240:243], v[66:81]
	v_mfma_f32_32x32x16_bf16 v[50:65], v[216:219], v[232:235], v[50:65]
	v_mfma_f32_32x32x16_bf16 v[34:49], v[216:219], v[240:243], v[34:49]
	v_mfma_f32_32x32x16_bf16 v[18:33], v[224:227], v[232:235], v[18:33]
	v_mfma_f32_32x32x16_bf16 v[2:17], v[224:227], v[240:243], v[2:17]
	s_mov_b32 s7, s73
	v_add_u32_e32 v136, s7, v134
	v_add_u32_e32 v137, s7, v135
	ds_read_b128 v[166:169], v136 offset:0
	ds_read_b128 v[232:235], v137 offset:0
	ds_read_b128 v[240:243], v137 offset:2048
	ds_read_b128 v[208:211], v136 offset:2048
	ds_read_b128 v[216:219], v136 offset:4096
	ds_read_b128 v[224:227], v136 offset:6144
	s_add_i32 s6, s6, 1
	s_waitcnt lgkmcnt(6)
	v_mfma_f32_32x32x16_bf16 v[114:129], v[162:165], v[228:231], v[114:129]
	v_mfma_f32_32x32x16_bf16 v[98:113], v[162:165], v[236:239], v[98:113]
	v_mfma_f32_32x32x16_bf16 v[82:97], v[204:207], v[228:231], v[82:97]
	v_mfma_f32_32x32x16_bf16 v[66:81], v[204:207], v[236:239], v[66:81]
	v_mfma_f32_32x32x16_bf16 v[50:65], v[212:215], v[228:231], v[50:65]
	v_mfma_f32_32x32x16_bf16 v[34:49], v[212:215], v[236:239], v[34:49]
	v_mfma_f32_32x32x16_bf16 v[18:33], v[220:223], v[228:231], v[18:33]
	v_mfma_f32_32x32x16_bf16 v[2:17], v[220:223], v[236:239], v[2:17]
	s_waitcnt lgkmcnt(0)
	v_mfma_f32_32x32x16_bf16 v[114:129], v[166:169], v[232:235], v[114:129]
	v_mfma_f32_32x32x16_bf16 v[98:113], v[166:169], v[240:243], v[98:113]
	v_mfma_f32_32x32x16_bf16 v[82:97], v[208:211], v[232:235], v[82:97]
	v_mfma_f32_32x32x16_bf16 v[66:81], v[208:211], v[240:243], v[66:81]
	v_mfma_f32_32x32x16_bf16 v[50:65], v[216:219], v[232:235], v[50:65]
	v_mfma_f32_32x32x16_bf16 v[34:49], v[216:219], v[240:243], v[34:49]
	v_mfma_f32_32x32x16_bf16 v[18:33], v[224:227], v[232:235], v[18:33]
	v_mfma_f32_32x32x16_bf16 v[2:17], v[224:227], v[240:243], v[2:17]
	s_mov_b32 s14, 31
	s_lshl_b64 s[12:13], s[14:15], 13
	s_movk_i32 s7, 0x7800
	s_movk_i32 s72, 0x6000
	s_mov_b32 s73, 0xc000
	v_mov_b32_e32 v0, v171
	s_barrier
	s_movk_i32 s0, 0x210
	s_waitcnt vmcnt(4)
	v_lshrrev_b32_e32 v130, 1, v0
	v_and_b32_e32 v130, 0xfffffc0, v130
	v_lshrrev_b32_e32 v131, 3, v0
	v_and_or_b32 v130, v131, 4, v130
	v_and_b32_e32 v0, 0x5f, v0
	v_mul_lo_u32 v130, v130, s0
	v_lshl_add_u32 v0, v0, 2, v130
	s_barrier
	ds_write2_b32 v0, v114, v98 offset1:32
	ds_write2_b32 v0, v115, v99 offset0:132 offset1:164
	v_add_u32_e32 v98, 0x400, v0
	ds_write2_b32 v98, v116, v100 offset0:8 offset1:40
	ds_write2_b32 v98, v117, v101 offset0:140 offset1:172
	v_add_u32_e32 v98, 0x1000, v0
	ds_write2_b32 v98, v118, v102 offset0:32 offset1:64
	ds_write2_b32 v98, v119, v103 offset0:164 offset1:196
	v_add_u32_e32 v98, 0x1400, v0
	ds_write2_b32 v98, v120, v104 offset0:40 offset1:72
	ds_write2_b32 v98, v121, v105 offset0:172 offset1:204
	v_add_u32_e32 v98, 0x2000, v0
	ds_write2_b32 v98, v122, v106 offset0:64 offset1:96
	ds_write2_b32 v98, v123, v107 offset0:196 offset1:228
	v_add_u32_e32 v98, 0x2400, v0
	ds_write2_b32 v98, v124, v108 offset0:72 offset1:104
	ds_write2_b32 v98, v125, v109 offset0:204 offset1:236
	v_add_u32_e32 v98, 0x3000, v0
	ds_write2_b32 v98, v126, v110 offset0:96 offset1:128
	v_add_u32_e32 v98, 0x3200, v0
	ds_write2_b32 v98, v127, v111 offset0:100 offset1:132
	v_add_u32_e32 v98, 0x3400, v0
	ds_write2_b32 v98, v128, v112 offset0:104 offset1:136
	v_add_u32_e32 v98, 0x3600, v0
	ds_write2_b32 v98, v129, v113 offset0:108 offset1:140
	v_add_u32_e32 v98, 0x4000, v0
	ds_write2_b32 v98, v82, v66 offset0:128 offset1:160
	v_add_u32_e32 v66, 0x4400, v0
	ds_write2_b32 v66, v83, v67 offset0:4 offset1:36
	ds_write2_b32 v66, v84, v68 offset0:136 offset1:168
	v_add_u32_e32 v66, 0x4800, v0
	ds_write2_b32 v66, v85, v69 offset0:12 offset1:44
	v_add_u32_e32 v66, 0x5000, v0
	ds_write2_b32 v66, v86, v70 offset0:160 offset1:192
	v_add_u32_e32 v66, 0x5400, v0
	ds_write2_b32 v66, v87, v71 offset0:36 offset1:68
	ds_write2_b32 v66, v88, v72 offset0:168 offset1:200
	v_add_u32_e32 v66, 0x5800, v0
	ds_write2_b32 v66, v89, v73 offset0:44 offset1:76
	v_add_u32_e32 v66, 0x6000, v0
	ds_write2_b32 v66, v90, v74 offset0:192 offset1:224
	v_add_u32_e32 v66, 0x6400, v0
	ds_write2_b32 v66, v91, v75 offset0:68 offset1:100
	ds_write2_b32 v66, v92, v76 offset0:200 offset1:232
	v_add_u32_e32 v66, 0x6800, v0
	ds_write2_b32 v66, v93, v77 offset0:76 offset1:108
	v_add_u32_e32 v66, 0x7200, v0
	ds_write2_b32 v66, v94, v78 offset0:96 offset1:128
	v_add_u32_e32 v66, 0x7400, v0
	s_lshr_b32 s14, s42, 2
	ds_write2_b32 v66, v95, v79 offset0:100 offset1:132
	v_add_u32_e32 v66, 0x7600, v0
	v_add_u32_e32 v0, 0x7800, v0
	v_mov_b32_e32 v105, v171
	s_cmp_lt_i32 s14, 14
	s_mov_b64 s[6:7], -1
	ds_write2_b32 v66, v96, v80 offset0:104 offset1:136
	ds_write2_b32 v0, v97, v81 offset0:108 offset1:140
	s_waitcnt lgkmcnt(0)
	s_barrier
	s_cbranch_scc1 .LBB0_439
	s_cmp_gt_i32 s14, 14
	s_cbranch_scc0 .LBB0_436
	s_mov_b64 s[6:7], 0

.LBB0_587:
	s_lshr_b32 s6, s8, 3
	s_and_b32 s9, s8, 56
	v_readlane_b32 s0, v252, 42
	s_and_b32 s6, s6, 0xffffff8
	s_and_b32 s7, s8, 7
	s_or_b32 s10, s9, s0
	v_mov_b32_e32 v6, v171
	s_or_b32 s6, s6, s7
	s_lshl_b32 s7, s10, 21
	v_readlane_b32 s0, v252, 46
	v_lshlrev_b32_e32 v2, 3, v6
	v_readlane_b32 s1, v252, 47
	s_add_u32 s12, s0, s7
	v_ashrrev_i32_e32 v3, 31, v2
	s_addc_u32 s13, s1, 0
	v_lshlrev_b64 v[4:5], 1, v[2:3]
	s_mov_b32 s7, s15
	v_lshl_add_u64 v[154:155], s[12:13], 0, v[4:5]
	s_lshl_b64 s[12:13], s[6:7], 20
	v_readlane_b32 s0, v252, 34
	v_readlane_b32 s1, v252, 35
	s_add_u32 s12, s0, s12
	s_addc_u32 s13, s1, s13
	v_lshrrev_b32_e32 v3, 2, v6
	v_and_b32_e32 v0, 24, v2
	v_lshl_add_u64 v[156:157], s[12:13], 0, v[4:5]
	v_mad_u64_u32 v[158:159], s[12:13], v3, 40, v[0:1]
	s_movk_i32 s0, 0x50
	v_and_b32_e32 v2, 0x30, v6
	v_xor_b32_e32 v154, v154, v2
	v_xor_b32_e32 v156, v156, v2
	v_and_b32_e32 v130, 31, v6
	v_lshlrev_b32_e32 v130, 6, v130
	v_lshrrev_b32_e32 v131, 2, v6
	v_and_b32_e32 v131, 3, v131
	v_bfe_u32 v133, v6, 5, 1
	v_xor_b32_e32 v131, v131, v133
	v_lshl_or_b32 v130, v131, 4, v130
	v_lshrrev_b32_e32 v131, 7, v6
	v_lshl_or_b32 v132, v131, 13, v130
	v_bfe_u32 v131, v6, 6, 1
	v_lshl_or_b32 v133, v131, 12, v130
	v_or_b32_e32 v133, 0x4000, v133
	v_xor_b32_e32 v134, 32, v132
	v_xor_b32_e32 v135, 32, v133
	v_lshrrev_b32_e32 v131, 6, v6
	s_nop 1
	v_readfirstlane_b32 s72, v131
	s_nop 3
	s_lshl_b32 s72, s72, 10
	s_waitcnt lgkmcnt(0)
	s_barrier
	s_mov_b32 s14, 0
	s_lshl_b64 s[12:13], s[14:15], 14
	v_lshl_add_u64 v[244:245], v[154:155], 0, s[12:13]
	s_add_u32 s12, s12, 0x1000
	s_addc_u32 s13, s13, 0
	v_lshl_add_u64 v[246:247], v[154:155], 0, s[12:13]
	s_add_u32 s12, s12, 0x1000
	s_addc_u32 s13, s13, 0
	v_lshl_add_u64 v[248:249], v[154:155], 0, s[12:13]
	s_add_u32 s12, s12, 0x1000
	s_addc_u32 s13, s13, 0
	v_lshl_add_u64 v[140:141], v[154:155], 0, s[12:13]
	s_lshl_b64 s[12:13], s[14:15], 13
	v_lshl_add_u64 v[142:143], v[156:157], 0, s[12:13]
	s_add_u32 s12, s12, 0x1000
	s_addc_u32 s13, s13, 0
	v_lshl_add_u64 v[144:145], v[156:157], 0, s[12:13]
	s_add_u32 m0, s72, 0x0
	s_nop 0
	global_load_lds_dwordx4 v[244:245], off
	s_add_u32 m0, m0, 0x1000
	s_nop 0
	global_load_lds_dwordx4 v[246:247], off
	s_add_u32 m0, m0, 0x1000
	s_nop 0
	global_load_lds_dwordx4 v[248:249], off
	s_add_u32 m0, m0, 0x1000
	s_nop 0
	global_load_lds_dwordx4 v[140:141], off
	s_add_u32 m0, m0, 0x1000
	s_nop 0
	global_load_lds_dwordx4 v[142:143], off
	s_add_u32 m0, m0, 0x1000
	s_nop 0
	global_load_lds_dwordx4 v[144:145], off
	s_mov_b32 s14, 1
	s_lshl_b64 s[12:13], s[14:15], 14
	v_lshl_add_u64 v[244:245], v[154:155], 0, s[12:13]
	s_add_u32 s12, s12, 0x1000
	s_addc_u32 s13, s13, 0
	v_lshl_add_u64 v[246:247], v[154:155], 0, s[12:13]
	s_add_u32 s12, s12, 0x1000
	s_addc_u32 s13, s13, 0
	v_lshl_add_u64 v[248:249], v[154:155], 0, s[12:13]
	s_add_u32 s12, s12, 0x1000
	s_addc_u32 s13, s13, 0
	v_lshl_add_u64 v[140:141], v[154:155], 0, s[12:13]
	s_lshl_b64 s[12:13], s[14:15], 13
	v_lshl_add_u64 v[142:143], v[156:157], 0, s[12:13]
	s_add_u32 s12, s12, 0x1000
	s_addc_u32 s13, s13, 0
	v_lshl_add_u64 v[144:145], v[156:157], 0, s[12:13]
	s_add_u32 m0, s72, 0x6000
	s_nop 0
	global_load_lds_dwordx4 v[244:245], off
	s_add_u32 m0, m0, 0x1000
	s_nop 0
	global_load_lds_dwordx4 v[246:247], off
	s_add_u32 m0, m0, 0x1000
	s_nop 0
	global_load_lds_dwordx4 v[248:249], off
	s_add_u32 m0, m0, 0x1000
	s_nop 0
	global_load_lds_dwordx4 v[140:141], off
	s_add_u32 m0, m0, 0x1000
	s_nop 0
	global_load_lds_dwordx4 v[142:143], off
	s_add_u32 m0, m0, 0x1000
	s_nop 0
	global_load_lds_dwordx4 v[144:145], off
	s_mov_b32 s14, 2
	s_lshl_b64 s[12:13], s[14:15], 14
	v_lshl_add_u64 v[244:245], v[154:155], 0, s[12:13]
	s_add_u32 s12, s12, 0x1000
	s_addc_u32 s13, s13, 0
	v_lshl_add_u64 v[246:247], v[154:155], 0, s[12:13]
	s_add_u32 s12, s12, 0x1000
	s_addc_u32 s13, s13, 0
	v_lshl_add_u64 v[248:249], v[154:155], 0, s[12:13]
	s_add_u32 s12, s12, 0x1000
	s_addc_u32 s13, s13, 0
	v_lshl_add_u64 v[140:141], v[154:155], 0, s[12:13]
	s_lshl_b64 s[12:13], s[14:15], 13
	v_lshl_add_u64 v[142:143], v[156:157], 0, s[12:13]
	s_add_u32 s12, s12, 0x1000
	s_addc_u32 s13, s13, 0
	v_lshl_add_u64 v[144:145], v[156:157], 0, s[12:13]
	s_add_u32 m0, s72, 0xc000
	s_nop 0
	global_load_lds_dwordx4 v[244:245], off
	s_add_u32 m0, m0, 0x1000
	s_nop 0
	global_load_lds_dwordx4 v[246:247], off
	s_add_u32 m0, m0, 0x1000
	s_nop 0
	global_load_lds_dwordx4 v[248:249], off
	s_add_u32 m0, m0, 0x1000
	s_nop 0
	global_load_lds_dwordx4 v[140:141], off
	s_add_u32 m0, m0, 0x1000
	s_nop 0
	global_load_lds_dwordx4 v[142:143], off
	s_add_u32 m0, m0, 0x1000
	s_nop 0
	global_load_lds_dwordx4 v[144:145], off
	v_and_b32_e32 v2, 0xfffff9f, v6
	v_mul_lo_u32 v160, v2, s0
	v_or_b32_e32 v2, 0x60, v6
	v_lshrrev_b32_e32 v0, 1, v6
	v_and_b32_e32 v3, 0x5f, v6
	v_mul_lo_u32 v161, v2, s0
	v_mov_b32_e32 v2, 0
	s_mov_b32 s7, 0
	v_and_b32_e32 v0, 16, v0
	v_mul_u32_u24_e32 v159, 0x50, v3
	v_mov_b32_e32 v3, v2
	v_mov_b32_e32 v4, v2
	v_mov_b32_e32 v5, v2
	v_mov_b32_e32 v6, v2
	v_mov_b32_e32 v7, v2
	v_mov_b32_e32 v8, v2
	v_mov_b32_e32 v9, v2
	v_mov_b32_e32 v10, v2
	v_mov_b32_e32 v11, v2
	v_mov_b32_e32 v12, v2
	v_mov_b32_e32 v13, v2
	v_mov_b32_e32 v14, v2
	v_mov_b32_e32 v15, v2
	v_mov_b32_e32 v16, v2
	v_mov_b32_e32 v17, v2
	v_mov_b32_e32 v18, v2
	v_mov_b32_e32 v19, v2
	v_mov_b32_e32 v20, v2
	v_mov_b32_e32 v21, v2
	v_mov_b32_e32 v22, v2
	v_mov_b32_e32 v23, v2
	v_mov_b32_e32 v24, v2
	v_mov_b32_e32 v25, v2
	v_mov_b32_e32 v26, v2
	v_mov_b32_e32 v27, v2
	v_mov_b32_e32 v28, v2
	v_mov_b32_e32 v29, v2
	v_mov_b32_e32 v30, v2
	v_mov_b32_e32 v31, v2
	v_mov_b32_e32 v32, v2
	v_mov_b32_e32 v33, v2
	v_mov_b32_e32 v34, v2
	v_mov_b32_e32 v35, v2
	v_mov_b32_e32 v36, v2
	v_mov_b32_e32 v37, v2
	v_mov_b32_e32 v38, v2
	v_mov_b32_e32 v39, v2
	v_mov_b32_e32 v40, v2
	v_mov_b32_e32 v41, v2
	v_mov_b32_e32 v42, v2
	v_mov_b32_e32 v43, v2
	v_mov_b32_e32 v44, v2
	v_mov_b32_e32 v45, v2
	v_mov_b32_e32 v46, v2
	v_mov_b32_e32 v47, v2
	v_mov_b32_e32 v48, v2
	v_mov_b32_e32 v49, v2
	v_mov_b32_e32 v50, v2
	v_mov_b32_e32 v51, v2
	v_mov_b32_e32 v52, v2
	v_mov_b32_e32 v53, v2
	v_mov_b32_e32 v54, v2
	v_mov_b32_e32 v55, v2
	v_mov_b32_e32 v56, v2
	v_mov_b32_e32 v57, v2
	v_mov_b32_e32 v58, v2
	v_mov_b32_e32 v59, v2
	v_mov_b32_e32 v60, v2
	v_mov_b32_e32 v61, v2
	v_mov_b32_e32 v62, v2
	v_mov_b32_e32 v63, v2
	v_mov_b32_e32 v64, v2
	v_mov_b32_e32 v65, v2
	v_mov_b32_e32 v66, v2
	v_mov_b32_e32 v67, v2
	v_mov_b32_e32 v68, v2
	v_mov_b32_e32 v69, v2
	v_mov_b32_e32 v70, v2
	v_mov_b32_e32 v71, v2
	v_mov_b32_e32 v72, v2
	v_mov_b32_e32 v73, v2
	v_mov_b32_e32 v74, v2
	v_mov_b32_e32 v75, v2
	v_mov_b32_e32 v76, v2
	v_mov_b32_e32 v77, v2
	v_mov_b32_e32 v78, v2
	v_mov_b32_e32 v79, v2
	v_mov_b32_e32 v80, v2
	v_mov_b32_e32 v81, v2
	s_waitcnt vmcnt(17)
	v_mov_b32_e32 v82, v2
	v_mov_b32_e32 v83, v2
	v_mov_b32_e32 v84, v2
	v_mov_b32_e32 v85, v2
	s_waitcnt vmcnt(16)
	v_mov_b32_e32 v86, v2
	v_mov_b32_e32 v87, v2
	v_mov_b32_e32 v88, v2
	v_mov_b32_e32 v89, v2
	s_waitcnt vmcnt(15)
	v_mov_b32_e32 v90, v2
	v_mov_b32_e32 v91, v2
	v_mov_b32_e32 v92, v2
	v_mov_b32_e32 v93, v2
	s_waitcnt vmcnt(14)
	v_mov_b32_e32 v94, v2
	v_mov_b32_e32 v95, v2
	v_mov_b32_e32 v96, v2
	v_mov_b32_e32 v97, v2
	v_mov_b32_e32 v98, v2
	v_mov_b32_e32 v99, v2
	v_mov_b32_e32 v100, v2
	v_mov_b32_e32 v101, v2
	v_mov_b32_e32 v102, v2
	v_mov_b32_e32 v103, v2
	v_mov_b32_e32 v104, v2
	v_mov_b32_e32 v105, v2
	v_mov_b32_e32 v106, v2
	v_mov_b32_e32 v107, v2
	v_mov_b32_e32 v108, v2
	v_mov_b32_e32 v109, v2
	v_mov_b32_e32 v110, v2
	v_mov_b32_e32 v111, v2
	v_mov_b32_e32 v112, v2
	v_mov_b32_e32 v113, v2
	v_mov_b32_e32 v114, v2
	v_mov_b32_e32 v115, v2
	v_mov_b32_e32 v116, v2
	v_mov_b32_e32 v117, v2
	v_mov_b32_e32 v118, v2
	v_mov_b32_e32 v119, v2
	v_mov_b32_e32 v120, v2
	v_mov_b32_e32 v121, v2
	v_mov_b32_e32 v122, v2
	v_mov_b32_e32 v123, v2
	v_mov_b32_e32 v124, v2
	v_mov_b32_e32 v125, v2
	v_mov_b32_e32 v126, v2
	v_mov_b32_e32 v127, v2
	v_mov_b32_e32 v128, v2
	v_mov_b32_e32 v129, v2
	s_waitcnt lgkmcnt(0)
	s_mov_b32 s7, 0
	s_mov_b32 s11, 0
	v_mov_b32_e32 v138, v132
	v_mov_b32_e32 v139, v133
	s_waitcnt vmcnt(12)
	s_barrier
	ds_read_b128 v[162:165], v138 offset:0
	ds_read_b128 v[228:231], v139 offset:0
	ds_read_b128 v[236:239], v139 offset:2048
	ds_read_b128 v[204:207], v138 offset:2048
	ds_read_b128 v[212:215], v138 offset:4096
	ds_read_b128 v[220:223], v138 offset:6144
.Lg588_loop:
	v_add_u32_e32 v136, s11, v134
	v_add_u32_e32 v137, s11, v135
	ds_read_b128 v[166:169], v136 offset:0
	ds_read_b128 v[232:235], v137 offset:0
	ds_read_b128 v[240:243], v137 offset:2048
	ds_read_b128 v[208:211], v136 offset:2048
	ds_read_b128 v[216:219], v136 offset:4096
	ds_read_b128 v[224:227], v136 offset:6144
	s_add_i32 s7, s7, 1
	s_add_u32 s73, s11, 0x6000
	s_cmp_lt_u32 s73, 0x12000
	s_cselect_b32 s73, s73, 0
	v_add_u32_e32 v138, s73, v132
	v_add_u32_e32 v139, s73, v133
	s_waitcnt lgkmcnt(6)
	v_mfma_f32_32x32x16_bf16 v[114:129], v[162:165], v[228:231], v[114:129]
	s_add_i32 s14, s7, 2
	s_lshl_b64 s[12:13], s[14:15], 14
	v_lshl_add_u64 v[244:245], v[154:155], 0, s[12:13]
	v_mfma_f32_32x32x16_bf16 v[98:113], v[162:165], v[236:239], v[98:113]
	s_add_u32 s12, s12, 0x1000
	s_addc_u32 s13, s13, 0
	v_lshl_add_u64 v[246:247], v[154:155], 0, s[12:13]
	v_mfma_f32_32x32x16_bf16 v[82:97], v[204:207], v[228:231], v[82:97]
	s_add_u32 s12, s12, 0x1000
	s_addc_u32 s13, s13, 0
	v_lshl_add_u64 v[248:249], v[154:155], 0, s[12:13]
	v_mfma_f32_32x32x16_bf16 v[66:81], v[204:207], v[236:239], v[66:81]
	s_add_u32 s12, s12, 0x1000
	s_addc_u32 s13, s13, 0
	v_lshl_add_u64 v[140:141], v[154:155], 0, s[12:13]
	v_mfma_f32_32x32x16_bf16 v[50:65], v[212:215], v[228:231], v[50:65]
	s_lshl_b64 s[12:13], s[14:15], 13
	v_lshl_add_u64 v[142:143], v[156:157], 0, s[12:13]
	v_mfma_f32_32x32x16_bf16 v[34:49], v[212:215], v[236:239], v[34:49]
	s_add_u32 s12, s12, 0x1000
	s_addc_u32 s13, s13, 0
	v_lshl_add_u64 v[144:145], v[156:157], 0, s[12:13]
	v_mfma_f32_32x32x16_bf16 v[18:33], v[220:223], v[228:231], v[18:33]
	v_mfma_f32_32x32x16_bf16 v[2:17], v[220:223], v[236:239], v[2:17]
	s_waitcnt vmcnt(6) lgkmcnt(0)
	s_barrier
	s_add_u32 m0, s11, s72
	v_mfma_f32_32x32x16_bf16 v[114:129], v[166:169], v[232:235], v[114:129]
	global_load_lds_dwordx4 v[244:245], off
	ds_read_b128 v[162:165], v138 offset:0
	ds_read_b128 v[228:231], v139 offset:0
	s_add_u32 m0, m0, 0x1000
	v_mfma_f32_32x32x16_bf16 v[98:113], v[166:169], v[240:243], v[98:113]
	global_load_lds_dwordx4 v[246:247], off
	ds_read_b128 v[236:239], v139 offset:2048
	ds_read_b128 v[204:207], v138 offset:2048
	s_add_u32 m0, m0, 0x1000
	v_mfma_f32_32x32x16_bf16 v[82:97], v[208:211], v[232:235], v[82:97]
	global_load_lds_dwordx4 v[248:249], off
	ds_read_b128 v[212:215], v138 offset:4096
	ds_read_b128 v[220:223], v138 offset:6144
	s_add_u32 m0, m0, 0x1000
	v_mfma_f32_32x32x16_bf16 v[66:81], v[208:211], v[240:243], v[66:81]
	global_load_lds_dwordx4 v[140:141], off
	s_add_u32 m0, m0, 0x1000
	v_mfma_f32_32x32x16_bf16 v[50:65], v[216:219], v[232:235], v[50:65]
	global_load_lds_dwordx4 v[142:143], off
	s_add_u32 m0, m0, 0x1000
	v_mfma_f32_32x32x16_bf16 v[34:49], v[216:219], v[240:243], v[34:49]
	global_load_lds_dwordx4 v[144:145], off
	v_mfma_f32_32x32x16_bf16 v[18:33], v[224:227], v[232:235], v[18:33]
	v_mfma_f32_32x32x16_bf16 v[2:17], v[224:227], v[240:243], v[2:17]
	s_mov_b32 s11, s73
	s_cmp_lg_u32 s7, 125
	s_cbranch_scc1 .Lg588_loop
	v_add_u32_e32 v136, s11, v134
	v_add_u32_e32 v137, s11, v135
	ds_read_b128 v[166:169], v136 offset:0
	ds_read_b128 v[232:235], v137 offset:0
	ds_read_b128 v[240:243], v137 offset:2048
	ds_read_b128 v[208:211], v136 offset:2048
	ds_read_b128 v[216:219], v136 offset:4096
	ds_read_b128 v[224:227], v136 offset:6144
	s_add_i32 s7, s7, 1
	s_add_u32 s73, s11, 0x6000
	s_cmp_lt_u32 s73, 0x12000
	s_cselect_b32 s73, s73, 0
	v_add_u32_e32 v138, s73, v132
	v_add_u32_e32 v139, s73, v133
	s_waitcnt lgkmcnt(6)
	v_mfma_f32_32x32x16_bf16 v[114:129], v[162:165], v[228:231], v[114:129]
	v_mfma_f32_32x32x16_bf16 v[98:113], v[162:165], v[236:239], v[98:113]
	v_mfma_f32_32x32x16_bf16 v[82:97], v[204:207], v[228:231], v[82:97]
	v_mfma_f32_32x32x16_bf16 v[66:81], v[204:207], v[236:239], v[66:81]
	v_mfma_f32_32x32x16_bf16 v[50:65], v[212:215], v[228:231], v[50:65]
	v_mfma_f32_32x32x16_bf16 v[34:49], v[212:215], v[236:239], v[34:49]
	v_mfma_f32_32x32x16_bf16 v[18:33], v[220:223], v[228:231], v[18:33]
	v_mfma_f32_32x32x16_bf16 v[2:17], v[220:223], v[236:239], v[2:17]
	s_waitcnt vmcnt(6) lgkmcnt(0)
	s_barrier
	v_mfma_f32_32x32x16_bf16 v[114:129], v[166:169], v[232:235], v[114:129]
	ds_read_b128 v[162:165], v138 offset:0
	ds_read_b128 v[228:231], v139 offset:0
	v_mfma_f32_32x32x16_bf16 v[98:113], v[166:169], v[240:243], v[98:113]
	ds_read_b128 v[236:239], v139 offset:2048
	ds_read_b128 v[204:207], v138 offset:2048
	v_mfma_f32_32x32x16_bf16 v[82:97], v[208:211], v[232:235], v[82:97]
	ds_read_b128 v[212:215], v138 offset:4096
	ds_read_b128 v[220:223], v138 offset:6144
	v_mfma_f32_32x32x16_bf16 v[66:81], v[208:211], v[240:243], v[66:81]
	v_mfma_f32_32x32x16_bf16 v[50:65], v[216:219], v[232:235], v[50:65]
	v_mfma_f32_32x32x16_bf16 v[34:49], v[216:219], v[240:243], v[34:49]
	v_mfma_f32_32x32x16_bf16 v[18:33], v[224:227], v[232:235], v[18:33]
	v_mfma_f32_32x32x16_bf16 v[2:17], v[224:227], v[240:243], v[2:17]
	s_mov_b32 s11, s73
	v_add_u32_e32 v136, s11, v134
	v_add_u32_e32 v137, s11, v135
	ds_read_b128 v[166:169], v136 offset:0
	ds_read_b128 v[232:235], v137 offset:0
	ds_read_b128 v[240:243], v137 offset:2048
	ds_read_b128 v[208:211], v136 offset:2048
	ds_read_b128 v[216:219], v136 offset:4096
	ds_read_b128 v[224:227], v136 offset:6144
	s_add_i32 s7, s7, 1
	s_add_u32 s73, s11, 0x6000
	s_cmp_lt_u32 s73, 0x12000
	s_cselect_b32 s73, s73, 0
	v_add_u32_e32 v138, s73, v132
	v_add_u32_e32 v139, s73, v133
	s_waitcnt lgkmcnt(6)
	v_mfma_f32_32x32x16_bf16 v[114:129], v[162:165], v[228:231], v[114:129]
	v_mfma_f32_32x32x16_bf16 v[98:113], v[162:165], v[236:239], v[98:113]
	v_mfma_f32_32x32x16_bf16 v[82:97], v[204:207], v[228:231], v[82:97]
	v_mfma_f32_32x32x16_bf16 v[66:81], v[204:207], v[236:239], v[66:81]
	v_mfma_f32_32x32x16_bf16 v[50:65], v[212:215], v[228:231], v[50:65]
	v_mfma_f32_32x32x16_bf16 v[34:49], v[212:215], v[236:239], v[34:49]
	v_mfma_f32_32x32x16_bf16 v[18:33], v[220:223], v[228:231], v[18:33]
	v_mfma_f32_32x32x16_bf16 v[2:17], v[220:223], v[236:239], v[2:17]
	s_waitcnt vmcnt(0) lgkmcnt(0)
	s_barrier
	v_mfma_f32_32x32x16_bf16 v[114:129], v[166:169], v[232:235], v[114:129]
	ds_read_b128 v[162:165], v138 offset:0
	ds_read_b128 v[228:231], v139 offset:0
	v_mfma_f32_32x32x16_bf16 v[98:113], v[166:169], v[240:243], v[98:113]
	ds_read_b128 v[236:239], v139 offset:2048
	ds_read_b128 v[204:207], v138 offset:2048
	v_mfma_f32_32x32x16_bf16 v[82:97], v[208:211], v[232:235], v[82:97]
	ds_read_b128 v[212:215], v138 offset:4096
	ds_read_b128 v[220:223], v138 offset:6144
	v_mfma_f32_32x32x16_bf16 v[66:81], v[208:211], v[240:243], v[66:81]
	v_mfma_f32_32x32x16_bf16 v[50:65], v[216:219], v[232:235], v[50:65]
	v_mfma_f32_32x32x16_bf16 v[34:49], v[216:219], v[240:243], v[34:49]
	v_mfma_f32_32x32x16_bf16 v[18:33], v[224:227], v[232:235], v[18:33]
	v_mfma_f32_32x32x16_bf16 v[2:17], v[224:227], v[240:243], v[2:17]
	s_mov_b32 s11, s73
	v_add_u32_e32 v136, s11, v134
	v_add_u32_e32 v137, s11, v135
	ds_read_b128 v[166:169], v136 offset:0
	ds_read_b128 v[232:235], v137 offset:0
	ds_read_b128 v[240:243], v137 offset:2048
	ds_read_b128 v[208:211], v136 offset:2048
	ds_read_b128 v[216:219], v136 offset:4096
	ds_read_b128 v[224:227], v136 offset:6144
	s_add_i32 s7, s7, 1
	s_waitcnt lgkmcnt(6)
	v_mfma_f32_32x32x16_bf16 v[114:129], v[162:165], v[228:231], v[114:129]
	v_mfma_f32_32x32x16_bf16 v[98:113], v[162:165], v[236:239], v[98:113]
	v_mfma_f32_32x32x16_bf16 v[82:97], v[204:207], v[228:231], v[82:97]
	v_mfma_f32_32x32x16_bf16 v[66:81], v[204:207], v[236:239], v[66:81]
	v_mfma_f32_32x32x16_bf16 v[50:65], v[212:215], v[228:231], v[50:65]
	v_mfma_f32_32x32x16_bf16 v[34:49], v[212:215], v[236:239], v[34:49]
	v_mfma_f32_32x32x16_bf16 v[18:33], v[220:223], v[228:231], v[18:33]
	v_mfma_f32_32x32x16_bf16 v[2:17], v[220:223], v[236:239], v[2:17]
	s_waitcnt lgkmcnt(0)
	v_mfma_f32_32x32x16_bf16 v[114:129], v[166:169], v[232:235], v[114:129]
	v_mfma_f32_32x32x16_bf16 v[98:113], v[166:169], v[240:243], v[98:113]
	v_mfma_f32_32x32x16_bf16 v[82:97], v[208:211], v[232:235], v[82:97]
	v_mfma_f32_32x32x16_bf16 v[66:81], v[208:211], v[240:243], v[66:81]
	v_mfma_f32_32x32x16_bf16 v[50:65], v[216:219], v[232:235], v[50:65]
	v_mfma_f32_32x32x16_bf16 v[34:49], v[216:219], v[240:243], v[34:49]
	v_mfma_f32_32x32x16_bf16 v[18:33], v[224:227], v[232:235], v[18:33]
	v_mfma_f32_32x32x16_bf16 v[2:17], v[224:227], v[240:243], v[2:17]
	s_mov_b32 s14, 127
	s_lshl_b64 s[12:13], s[14:15], 13
	s_movk_i32 s11, 0x7800
	s_movk_i32 s72, 0x6000
	s_mov_b32 s73, 0xc000
	v_mov_b32_e32 v0, v171
	s_barrier
	s_movk_i32 s0, 0x210
	s_waitcnt vmcnt(4)
	v_lshrrev_b32_e32 v130, 1, v0
	v_and_b32_e32 v130, 0xfffffc0, v130
	v_lshrrev_b32_e32 v131, 3, v0
	v_and_or_b32 v130, v131, 4, v130
	v_and_b32_e32 v0, 0x5f, v0
	v_mul_lo_u32 v130, v130, s0
	v_lshl_add_u32 v0, v0, 2, v130
	s_barrier
	ds_write2_b32 v0, v114, v98 offset1:32
	ds_write2_b32 v0, v115, v99 offset0:132 offset1:164
	v_add_u32_e32 v98, 0x400, v0
	ds_write2_b32 v98, v116, v100 offset0:8 offset1:40
	ds_write2_b32 v98, v117, v101 offset0:140 offset1:172
	v_add_u32_e32 v98, 0x1000, v0
	ds_write2_b32 v98, v118, v102 offset0:32 offset1:64
	ds_write2_b32 v98, v119, v103 offset0:164 offset1:196
	v_add_u32_e32 v98, 0x1400, v0
	ds_write2_b32 v98, v120, v104 offset0:40 offset1:72
	ds_write2_b32 v98, v121, v105 offset0:172 offset1:204
	v_add_u32_e32 v98, 0x2000, v0
	ds_write2_b32 v98, v122, v106 offset0:64 offset1:96
	ds_write2_b32 v98, v123, v107 offset0:196 offset1:228
	v_add_u32_e32 v98, 0x2400, v0
	ds_write2_b32 v98, v124, v108 offset0:72 offset1:104
	ds_write2_b32 v98, v125, v109 offset0:204 offset1:236
	v_add_u32_e32 v98, 0x3000, v0
	ds_write2_b32 v98, v126, v110 offset0:96 offset1:128
	v_add_u32_e32 v98, 0x3200, v0
	ds_write2_b32 v98, v127, v111 offset0:100 offset1:132
	v_add_u32_e32 v98, 0x3400, v0
	ds_write2_b32 v98, v128, v112 offset0:104 offset1:136
	v_add_u32_e32 v98, 0x3600, v0
	ds_write2_b32 v98, v129, v113 offset0:108 offset1:140
	v_add_u32_e32 v98, 0x4000, v0
	ds_write2_b32 v98, v82, v66 offset0:128 offset1:160
	v_add_u32_e32 v66, 0x4400, v0
	ds_write2_b32 v66, v83, v67 offset0:4 offset1:36
	ds_write2_b32 v66, v84, v68 offset0:136 offset1:168
	v_add_u32_e32 v66, 0x4800, v0
	ds_write2_b32 v66, v85, v69 offset0:12 offset1:44
	v_add_u32_e32 v66, 0x5000, v0
	s_lshl_b32 s10, s10, 8
	ds_write2_b32 v66, v86, v70 offset0:160 offset1:192
	v_add_u32_e32 v66, 0x5400, v0
	s_lshl_b32 s11, s6, 7
	ds_write2_b32 v66, v87, v71 offset0:36 offset1:68
	ds_write2_b32 v66, v88, v72 offset0:168 offset1:200
	v_add_u32_e32 v66, 0x5800, v0
	s_add_i32 s6, s10, 0xffffe000
	ds_write2_b32 v66, v89, v73 offset0:44 offset1:76
	v_add_u32_e32 v66, 0x6000, v0
	s_lshr_b32 s6, s6, 12
	ds_write2_b32 v66, v90, v74 offset0:192 offset1:224
	v_add_u32_e32 v66, 0x6400, v0
	s_mulk_i32 s6, 0x1800
	ds_write2_b32 v66, v91, v75 offset0:68 offset1:100
	ds_write2_b32 v66, v92, v76 offset0:200 offset1:232
	v_add_u32_e32 v66, 0x6800, v0
	s_addk_i32 s6, 0x1800
	ds_write2_b32 v66, v93, v77 offset0:76 offset1:108
	v_add_u32_e32 v66, 0x7200, v0
	s_cmp_gt_u32 s9, 31
	ds_write2_b32 v66, v94, v78 offset0:96 offset1:128
	v_add_u32_e32 v66, 0x7400, v0
	s_cselect_b32 s14, s6, 0
	ds_write2_b32 v66, v95, v79 offset0:100 offset1:132
	v_add_u32_e32 v66, 0x7600, v0
	v_add_u32_e32 v0, 0x7800, v0
	v_mov_b32_e32 v84, v171
	s_lshl_b64 s[6:7], s[14:15], 2
	ds_write2_b32 v66, v96, v80 offset0:104 offset1:136
	ds_write2_b32 v0, v97, v81 offset0:108 offset1:140
	s_waitcnt lgkmcnt(0)
	s_barrier
	s_add_u32 s6, s61, s6
	v_lshlrev_b32_e32 v0, 3, v84
	v_and_b32_e32 v0, 0x78, v0
	s_addc_u32 s7, s53, s7
	v_or_b32_e32 v0, s11, v0
	s_add_u32 s6, s6, 0x1d645000
	s_addc_u32 s7, s7, 0
	v_lshlrev_b64 v[82:83], 2, v[0:1]
	v_lshl_add_u64 v[70:71], s[6:7], 0, v[82:83]
	v_lshl_add_u64 v[78:79], s[4:5], 0, v[82:83]
	global_load_dwordx4 v[66:69], v[70:71], off offset:16
	s_nop 0
	global_load_dwordx4 v[70:73], v[70:71], off
	s_nop 0
	global_load_dwordx4 v[74:77], v[78:79], off offset:16
	s_nop 0
	global_load_dwordx4 v[78:81], v[78:79], off
	v_ashrrev_i32_e32 v0, 4, v84
	v_mul_lo_u32 v85, v0, s0
	v_and_b32_e32 v84, 15, v84
	s_mov_b32 s9, 0
	v_lshl_add_u64 v[82:83], s[56:57], 0, v[82:83]
	v_lshl_add_u32 v84, v84, 5, v85
	v_lshlrev_b32_e32 v85, 1, v0

.LBB0_704:
	v_lshl_add_u64 v[12:13], s[40:41], 0, v[4:5]
	global_load_dword v0, v[12:13], off
	v_lshl_add_u64 v[12:13], s[44:45], 0, v[4:5]
	global_load_dword v17, v[12:13], off
	v_ashrrev_i32_e32 v11, 9, v10
	v_and_b32_e32 v14, 0x3fe00, v7
	v_lshrrev_b32_e32 v16, 9, v10
	s_movk_i32 s5, 0x180
	v_add_u32_e32 v7, s14, v7
	v_lshl_add_u64 v[4:5], v[4:5], 0, s[8:9]
	v_ashrrev_i32_e32 v12, 18, v10
	v_ashrrev_i32_e32 v13, 31, v12
	v_and_b32_e32 v20, 0x7f, v11
	v_lshlrev_b64 v[12:13], 20, v[12:13]
	v_and_or_b32 v20, v16, s5, v20
	v_lshl_or_b32 v12, v14, 2, v12
	v_lshl_add_u64 v[14:15], s[42:43], 0, v[12:13]
	v_lshlrev_b32_e32 v20, 2, v20
	v_mov_b32_e32 v21, 0
	v_lshl_add_u64 v[14:15], v[14:15], 0, v[20:21]
	global_load_dword v18, v[14:15], off
	s_movk_i32 s5, 0x1c0
	v_lshl_add_u64 v[12:13], s[46:47], 0, v[12:13]
	v_and_b32_e32 v20, 63, v11
	v_and_or_b32 v20, v16, s5, v20
	v_lshlrev_b32_e32 v20, 2, v20
	v_lshl_add_u64 v[12:13], v[12:13], 0, v[20:21]
	global_load_dword v19, v[12:13], off
	v_add_u32_e32 v10, s4, v10
	v_add_co_u32_e32 v12, vcc, 0x800000, v8
	s_nop 1
	v_addc_co_u32_e32 v13, vcc, 0, v9, vcc
	s_mov_b32 s5, 0x400000
	v_add_co_u32_e32 v14, vcc, s5, v8
	s_nop 1
	v_addc_co_u32_e32 v15, vcc, 0, v9, vcc
	v_add_co_u32_e32 v22, vcc, 0xc00000, v8
	s_nop 1
	v_addc_co_u32_e32 v23, vcc, 0, v9, vcc
	s_waitcnt vmcnt(3)
	v_cvt_pk_bf16_f32 v0, v0, s0
	global_store_short v[8:9], v0, off
	s_waitcnt vmcnt(3)
	v_cvt_pk_bf16_f32 v17, v17, s0
	global_store_short v[12:13], v17, off
	s_waitcnt vmcnt(3)
	v_cvt_pk_bf16_f32 v18, v18, s0
	global_store_short v[14:15], v18, off
	s_waitcnt vmcnt(3)
	v_cvt_pk_bf16_f32 v19, v19, s0
	global_store_short v[22:23], v19, off
	s_mov_b32 s5, 0x1fffff
	v_cmp_lt_i32_e32 vcc, s5, v10
	v_lshl_add_u64 v[8:9], v[8:9], 0, s[10:11]
	s_or_b64 s[12:13], vcc, s[12:13]
	s_andn2_b64 exec, exec, s[12:13]
	s_cbranch_execnz .LBB0_704
